# O5 + sc1 write-through stores in the EpiRes epilogues of the single-unit phases (pool-gemm, out-proj, FFN-down)
# baseline (speedup 1.0000x reference)
; __device__ __forceinline__ float h16_lo(unsigned u) { return (float)__builtin_bit_cast(h16x2, u).x; }
; __device__ __forceinline__ float h16_hi(unsigned u) { return (float)__builtin_bit_cast(h16x2, u).y; }
; __device__ __forceinline__ unsigned cvt_pk_bf16(float lo, float hi) { unsigned r; asm volatile("v_cvt_pk_bf16_f32 %0, %1, %2" : "=v"(r) : "v"(lo), "v"(hi)); return r; }
;     __device__ __forceinline__ void operator()(const f32x4 (&acc)[2][2][4][2], const Unit& u, int wr, int wc, int fr, int fq, const PG8_LAS float*) const {
;     ...
;         for (int bj = 0; bj < 2; ++bj) {
;             f32x4 gv[2], gm[2];
; #pragma unroll
;             for (int n = 0; n < 2; ++n) { const unsigned c = co + (unsigned)(bj * HALF + n * 4) * 4u;
;                 gv[n] = *(const gf32x4*)(gate + c); if (ls) gv[n] = gv[n] * *(const gf32x4*)(lsp + c);
;                 gm[n] = An ? *(const gf32x4*)(gnp + c) * (*(const gf32x4*)(scp + c) + 1.0f) : (f32x4){0.f, 0.f, 0.f, 0.f}; }
;             u32x4 bs[2][4];
; #pragma unroll
;             for (int ai = 0; ai < 2; ++ai)
; #pragma unroll
;                 for (int m = 0; m < 4; ++m) { const unsigned o = lo + (unsigned)((ai * HALF + m * 16) * DM + bj * HALF) * 2u; bs[ai][m] = *(const gu32x4*)(bt + o); }
;             asm volatile("" ::: "memory");
; #pragma unroll
;             for (int ai = 0; ai < 2; ++ai)
; #pragma unroll
;                 for (int m = 0; m < 4; ++m) { const unsigned o = lo + (unsigned)((ai * HALF + m * 16) * DM + bj * HALF) * 2u; const u32x4 b = bs[ai][m];
;                     const f32x4 x0 = (f32x4){h16_lo(b.x), h16_hi(b.x), h16_lo(b.y), h16_hi(b.y)} + acc[ai][bj][m][0] * gv[0], x1 = (f32x4){h16_lo(b.z), h16_hi(b.z), h16_lo(b.w), h16_hi(b.w)} + acc[ai][bj][m][1] * gv[1];
;                     { u32x4 w; w.x = pk_h16(x0.x, x0.y); w.y = pk_h16(x0.z, x0.w); w.z = pk_h16(x1.x, x1.y); w.w = pk_h16(x1.z, x1.w); *(gu32x4*)(ot + o) = w; }
;                     ssq[ai][m] += (x0.x * x0.x + x0.y * x0.y) + (x0.z * x0.z + x0.w * x0.w) + (x1.x * x1.x + x1.y * x1.y) + (x1.z * x1.z + x1.w * x1.w);
;                     if (An) { const f32x4 y0 = x0 * gm[0], y1 = x1 * gm[1]; u32x4 w; w.x = cvt_pk_bf16(y0.x, y0.y); w.y = cvt_pk_bf16(y0.z, y0.w); w.z = cvt_pk_bf16(y1.x, y1.y); w.w = cvt_pk_bf16(y1.z, y1.w); *(gu32x4*)(at + o) = w; } }
.LBB0_1125:
	s_waitcnt vmcnt(0)
	v_pk_add_f32 v[148:149], v[148:149], 1.0 op_sel_hi:[1,0]
	v_add_u32_e32 v199, s18, v159
	v_pk_add_f32 v[150:151], v[150:151], 1.0 op_sel_hi:[1,0]
	v_pk_mul_f32 v[172:173], v[144:145], v[148:149]
	v_lshlrev_b32_e32 v144, 12, v199
	v_pk_mul_f32 v[170:171], v[146:147], v[150:151]
	v_lshl_add_u32 v200, v158, 1, v144
	global_load_dwordx4 v[144:147], v[154:155], off offset:16
	global_load_dwordx4 v[148:151], v[152:153], off offset:16
	s_ashr_i32 s41, s40, 31
	s_lshl_b64 s[20:21], s[40:41], 20
	s_add_u32 s1, s73, s20
	s_addc_u32 s5, s74, s21
	s_add_u32 s20, s75, s20
	s_addc_u32 s21, s76, s21
	s_lshl_b64 s[14:15], s[14:15], 1
	s_add_u32 s60, s1, s14
	s_addc_u32 s61, s5, s15
	global_load_dwordx4 v[180:183], v200, s[60:61]
	v_add_u32_e32 v194, 0x10000, v200
	global_load_dwordx4 v[188:191], v194, s[60:61]
	v_add_u32_e32 v222, 0x20000, v200
	global_load_dwordx4 v[166:169], v222, s[60:61]
	v_add_u32_e32 v221, 0x30000, v200
	global_load_dwordx4 v[162:165], v221, s[60:61]
	v_add_u32_e32 v220, 0x80000, v200
	global_load_dwordx4 v[156:159], v220, s[60:61]
	v_add_u32_e32 v219, 0x90000, v200
	global_load_dwordx4 v[152:155], v219, s[60:61]
	v_add_u32_e32 v218, 0xa0000, v200
	v_add_u32_e32 v201, 0xb0000, v200
	s_add_u32 s58, s20, s14
	s_addc_u32 s59, s21, s15
	s_and_b64 vcc, exec, s[38:39]
	s_waitcnt vmcnt(6)
	v_pk_add_f32 v[150:151], v[150:151], 1.0 op_sel_hi:[1,0]
	v_pk_add_f32 v[148:149], v[148:149], 1.0 op_sel_hi:[1,0]
	v_pk_mul_f32 v[174:175], v[146:147], v[150:151]
	v_pk_mul_f32 v[176:177], v[144:145], v[148:149]
	global_load_dwordx4 v[148:151], v218, s[60:61]
	global_load_dwordx4 v[144:147], v201, s[60:61]
	s_waitcnt vmcnt(7)
	v_cvt_f32_f16_e32 v184, v180
	v_cvt_f32_f16_sdwa v185, v180 dst_sel:DWORD dst_unused:UNUSED_PAD src0_sel:WORD_1
	v_cvt_f32_f16_e32 v178, v181
	v_cvt_f32_f16_sdwa v179, v181 dst_sel:DWORD dst_unused:UNUSED_PAD src0_sel:WORD_1
	v_pk_fma_f32 v[180:181], v[136:137], v[132:133], v[184:185]
	v_cvt_f32_f16_e32 v136, v182
	v_pk_fma_f32 v[178:179], v[138:139], v[134:135], v[178:179]
	v_cvt_f32_f16_sdwa v137, v182 dst_sel:DWORD dst_unused:UNUSED_PAD src0_sel:WORD_1
	v_cvt_f32_f16_e32 v138, v183
	v_cvt_f32_f16_sdwa v139, v183 dst_sel:DWORD dst_unused:UNUSED_PAD src0_sel:WORD_1
	v_pk_fma_f32 v[184:185], v[128:129], v[140:141], v[136:137]
	v_cvt_pk_f16_f32 v128, v180, v181
	v_pk_fma_f32 v[182:183], v[130:131], v[142:143], v[138:139]
	v_cvt_pk_f16_f32 v129, v178, v179
	v_cvt_pk_f16_f32 v130, v184, v185
	v_cvt_pk_f16_f32 v131, v182, v183
	global_store_dwordx4 v200, v[128:131], s[60:61] sc1
	v_pk_mul_f32 v[136:137], v[174:175], v[182:183]
	v_pk_mul_f32 v[138:139], v[176:177], v[184:185]
	v_pk_mul_f32 v[130:131], v[170:171], v[178:179]
	v_pk_mul_f32 v[128:129], v[172:173], v[180:181]
	s_nop 0
	v_cvt_pk_bf16_f32 v128, v128, v129
	v_cvt_pk_bf16_f32 v129, v130, v131
	v_cvt_pk_bf16_f32 v130, v138, v139
	v_cvt_pk_bf16_f32 v131, v136, v137
	global_store_dwordx4 v200, v[128:131], s[58:59] sc1
	s_waitcnt vmcnt(8)
	s_nop 0
	v_cvt_f32_f16_e32 v128, v188
	v_cvt_f32_f16_sdwa v129, v188 dst_sel:DWORD dst_unused:UNUSED_PAD src0_sel:WORD_1
	v_cvt_f32_f16_e32 v130, v189
	v_cvt_f32_f16_sdwa v131, v189 dst_sel:DWORD dst_unused:UNUSED_PAD src0_sel:WORD_1
	v_pk_fma_f32 v[188:189], v[124:125], v[132:133], v[128:129]
	v_cvt_f32_f16_e32 v124, v190
	v_pk_fma_f32 v[186:187], v[126:127], v[134:135], v[130:131]
	v_cvt_f32_f16_sdwa v125, v190 dst_sel:DWORD dst_unused:UNUSED_PAD src0_sel:WORD_1
	v_cvt_f32_f16_e32 v126, v191
	v_cvt_f32_f16_sdwa v127, v191 dst_sel:DWORD dst_unused:UNUSED_PAD src0_sel:WORD_1
	v_pk_fma_f32 v[192:193], v[120:121], v[140:141], v[124:125]
	v_cvt_pk_f16_f32 v120, v188, v189
	v_pk_fma_f32 v[190:191], v[122:123], v[142:143], v[126:127]
	v_cvt_pk_f16_f32 v121, v186, v187
	v_cvt_pk_f16_f32 v122, v192, v193
	v_cvt_pk_f16_f32 v123, v190, v191
	global_store_dwordx4 v194, v[120:123], s[60:61] sc1
	v_pk_mul_f32 v[124:125], v[174:175], v[190:191]
	v_pk_mul_f32 v[126:127], v[176:177], v[192:193]
	v_pk_mul_f32 v[122:123], v[170:171], v[186:187]
	v_pk_mul_f32 v[120:121], v[172:173], v[188:189]
	s_nop 0
	v_cvt_pk_bf16_f32 v120, v120, v121
	v_cvt_pk_bf16_f32 v121, v122, v123
	v_cvt_pk_bf16_f32 v122, v126, v127
	v_cvt_pk_bf16_f32 v123, v124, v125
	global_store_dwordx4 v194, v[120:123], s[58:59] sc1
	s_waitcnt vmcnt(9)
	s_nop 0
	v_cvt_f32_f16_e32 v120, v166
	v_cvt_f32_f16_sdwa v121, v166 dst_sel:DWORD dst_unused:UNUSED_PAD src0_sel:WORD_1
	v_cvt_f32_f16_e32 v122, v167
	v_cvt_f32_f16_sdwa v123, v167 dst_sel:DWORD dst_unused:UNUSED_PAD src0_sel:WORD_1
	v_pk_fma_f32 v[194:195], v[116:117], v[132:133], v[120:121]
	v_cvt_f32_f16_e32 v116, v168
	v_pk_fma_f32 v[166:167], v[118:119], v[134:135], v[122:123]
	v_cvt_f32_f16_sdwa v117, v168 dst_sel:DWORD dst_unused:UNUSED_PAD src0_sel:WORD_1
	v_cvt_f32_f16_e32 v118, v169
	v_cvt_f32_f16_sdwa v119, v169 dst_sel:DWORD dst_unused:UNUSED_PAD src0_sel:WORD_1
	v_pk_fma_f32 v[196:197], v[112:113], v[140:141], v[116:117]
	v_cvt_pk_f16_f32 v112, v194, v195
	v_pk_fma_f32 v[168:169], v[114:115], v[142:143], v[118:119]
	v_cvt_pk_f16_f32 v113, v166, v167
	v_cvt_pk_f16_f32 v114, v196, v197
	v_cvt_pk_f16_f32 v115, v168, v169
	global_store_dwordx4 v222, v[112:115], s[60:61] sc1
	v_pk_mul_f32 v[116:117], v[174:175], v[168:169]
	v_pk_mul_f32 v[118:119], v[176:177], v[196:197]
	v_pk_mul_f32 v[114:115], v[170:171], v[166:167]
	v_pk_mul_f32 v[112:113], v[172:173], v[194:195]
	s_nop 0
	v_cvt_pk_bf16_f32 v112, v112, v113
	v_cvt_pk_bf16_f32 v113, v114, v115
	v_cvt_pk_bf16_f32 v114, v118, v119
	v_cvt_pk_bf16_f32 v115, v116, v117
	global_store_dwordx4 v222, v[112:115], s[58:59] sc1
	s_waitcnt vmcnt(10)
; __device__ __forceinline__ float h16_lo(unsigned u) { return (float)__builtin_bit_cast(h16x2, u).x; }
; __device__ __forceinline__ float h16_hi(unsigned u) { return (float)__builtin_bit_cast(h16x2, u).y; }
; __device__ __forceinline__ unsigned cvt_pk_bf16(float lo, float hi) { unsigned r; asm volatile("v_cvt_pk_bf16_f32 %0, %1, %2" : "=v"(r) : "v"(lo), "v"(hi)); return r; }
;     __device__ __forceinline__ void operator()(const f32x4 (&acc)[2][2][4][2], const Unit& u, int wr, int wc, int fr, int fq, const PG8_LAS float*) const {
;     ...
;             for (int n = 0; n < 2; ++n) { const unsigned c = co + (unsigned)(bj * HALF + n * 4) * 4u;
;                 gv[n] = *(const gf32x4*)(gate + c); if (ls) gv[n] = gv[n] * *(const gf32x4*)(lsp + c);
;                 gm[n] = An ? *(const gf32x4*)(gnp + c) * (*(const gf32x4*)(scp + c) + 1.0f) : (f32x4){0.f, 0.f, 0.f, 0.f}; }
;             u32x4 bs[2][4];
; #pragma unroll
;             for (int ai = 0; ai < 2; ++ai)
; #pragma unroll
;                 for (int m = 0; m < 4; ++m) { const unsigned o = lo + (unsigned)((ai * HALF + m * 16) * DM + bj * HALF) * 2u; bs[ai][m] = *(const gu32x4*)(bt + o); }
;             asm volatile("" ::: "memory");
; #pragma unroll
;             for (int ai = 0; ai < 2; ++ai)
; #pragma unroll
;                 for (int m = 0; m < 4; ++m) { const unsigned o = lo + (unsigned)((ai * HALF + m * 16) * DM + bj * HALF) * 2u; const u32x4 b = bs[ai][m];
;                     const f32x4 x0 = (f32x4){h16_lo(b.x), h16_hi(b.x), h16_lo(b.y), h16_hi(b.y)} + acc[ai][bj][m][0] * gv[0], x1 = (f32x4){h16_lo(b.z), h16_hi(b.z), h16_lo(b.w), h16_hi(b.w)} + acc[ai][bj][m][1] * gv[1];
;                     { u32x4 w; w.x = pk_h16(x0.x, x0.y); w.y = pk_h16(x0.z, x0.w); w.z = pk_h16(x1.x, x1.y); w.w = pk_h16(x1.z, x1.w); *(gu32x4*)(ot + o) = w; }
;                     ssq[ai][m] += (x0.x * x0.x + x0.y * x0.y) + (x0.z * x0.z + x0.w * x0.w) + (x1.x * x1.x + x1.y * x1.y) + (x1.z * x1.z + x1.w * x1.w);
;                     if (An) { const f32x4 y0 = x0 * gm[0], y1 = x1 * gm[1]; u32x4 w; w.x = cvt_pk_bf16(y0.x, y0.y); w.y = cvt_pk_bf16(y0.z, y0.w); w.z = cvt_pk_bf16(y1.x, y1.y); w.w = cvt_pk_bf16(y1.z, y1.w); *(gu32x4*)(at + o) = w; } }
	s_nop 0
	v_cvt_f32_f16_e32 v112, v162
	v_cvt_f32_f16_sdwa v113, v162 dst_sel:DWORD dst_unused:UNUSED_PAD src0_sel:WORD_1
	v_cvt_f32_f16_e32 v114, v163
	v_cvt_f32_f16_sdwa v115, v163 dst_sel:DWORD dst_unused:UNUSED_PAD src0_sel:WORD_1
	v_pk_fma_f32 v[108:109], v[108:109], v[132:133], v[112:113]
	v_cvt_f32_f16_e32 v112, v164
	v_pk_fma_f32 v[110:111], v[110:111], v[134:135], v[114:115]
	v_cvt_f32_f16_sdwa v113, v164 dst_sel:DWORD dst_unused:UNUSED_PAD src0_sel:WORD_1
	v_cvt_f32_f16_e32 v114, v165
	v_cvt_f32_f16_sdwa v115, v165 dst_sel:DWORD dst_unused:UNUSED_PAD src0_sel:WORD_1
	v_pk_fma_f32 v[104:105], v[104:105], v[140:141], v[112:113]
	v_cvt_pk_f16_f32 v112, v108, v109
	v_pk_fma_f32 v[106:107], v[106:107], v[142:143], v[114:115]
	v_cvt_pk_f16_f32 v113, v110, v111
	v_cvt_pk_f16_f32 v114, v104, v105
	v_cvt_pk_f16_f32 v115, v106, v107
	global_store_dwordx4 v221, v[112:115], s[60:61] sc1
	v_pk_mul_f32 v[116:117], v[174:175], v[106:107]
	v_pk_mul_f32 v[118:119], v[176:177], v[104:105]
	v_pk_mul_f32 v[114:115], v[170:171], v[110:111]
	v_pk_mul_f32 v[112:113], v[172:173], v[108:109]
	s_nop 0
	v_cvt_pk_bf16_f32 v112, v112, v113
	v_cvt_pk_bf16_f32 v113, v114, v115
	v_cvt_pk_bf16_f32 v114, v118, v119
	v_cvt_pk_bf16_f32 v115, v116, v117
	global_store_dwordx4 v221, v[112:115], s[58:59] sc1
	s_waitcnt vmcnt(11)
	s_nop 0
	v_cvt_f32_f16_e32 v114, v156
	v_cvt_f32_f16_sdwa v115, v156 dst_sel:DWORD dst_unused:UNUSED_PAD src0_sel:WORD_1
	v_cvt_f32_f16_e32 v112, v157
	v_cvt_f32_f16_sdwa v113, v157 dst_sel:DWORD dst_unused:UNUSED_PAD src0_sel:WORD_1
	v_pk_fma_f32 v[114:115], v[100:101], v[132:133], v[114:115]
	v_cvt_f32_f16_e32 v100, v158
	v_pk_fma_f32 v[112:113], v[102:103], v[134:135], v[112:113]
	v_cvt_f32_f16_sdwa v101, v158 dst_sel:DWORD dst_unused:UNUSED_PAD src0_sel:WORD_1
	v_cvt_f32_f16_e32 v102, v159
	v_cvt_f32_f16_sdwa v103, v159 dst_sel:DWORD dst_unused:UNUSED_PAD src0_sel:WORD_1
	v_pk_fma_f32 v[118:119], v[96:97], v[140:141], v[100:101]
	v_cvt_pk_f16_f32 v96, v114, v115
	v_pk_fma_f32 v[116:117], v[98:99], v[142:143], v[102:103]
	v_cvt_pk_f16_f32 v97, v112, v113
	v_cvt_pk_f16_f32 v98, v118, v119
	v_cvt_pk_f16_f32 v99, v116, v117
	global_store_dwordx4 v220, v[96:99], s[60:61] sc1
	v_pk_mul_f32 v[100:101], v[174:175], v[116:117]
	v_pk_mul_f32 v[102:103], v[176:177], v[118:119]
	v_pk_mul_f32 v[98:99], v[170:171], v[112:113]
	v_pk_mul_f32 v[96:97], v[172:173], v[114:115]
	s_nop 0
	v_cvt_pk_bf16_f32 v96, v96, v97
	v_cvt_pk_bf16_f32 v97, v98, v99
	v_cvt_pk_bf16_f32 v98, v102, v103
	v_cvt_pk_bf16_f32 v99, v100, v101
	global_store_dwordx4 v220, v[96:99], s[58:59] sc1
	s_waitcnt vmcnt(12)
	s_nop 0
	v_cvt_f32_f16_e32 v96, v152
	v_cvt_f32_f16_sdwa v97, v152 dst_sel:DWORD dst_unused:UNUSED_PAD src0_sel:WORD_1
	v_cvt_f32_f16_e32 v98, v153
	v_cvt_f32_f16_sdwa v99, v153 dst_sel:DWORD dst_unused:UNUSED_PAD src0_sel:WORD_1
	v_pk_fma_f32 v[124:125], v[92:93], v[132:133], v[96:97]
	v_cvt_f32_f16_e32 v92, v154
	v_pk_fma_f32 v[122:123], v[94:95], v[134:135], v[98:99]
	v_cvt_f32_f16_sdwa v93, v154 dst_sel:DWORD dst_unused:UNUSED_PAD src0_sel:WORD_1
	v_cvt_f32_f16_e32 v94, v155
	v_cvt_f32_f16_sdwa v95, v155 dst_sel:DWORD dst_unused:UNUSED_PAD src0_sel:WORD_1
	v_pk_fma_f32 v[136:137], v[88:89], v[140:141], v[92:93]
	v_cvt_pk_f16_f32 v88, v124, v125
	v_pk_fma_f32 v[130:131], v[90:91], v[142:143], v[94:95]
	v_cvt_pk_f16_f32 v89, v122, v123
	v_cvt_pk_f16_f32 v90, v136, v137
	v_cvt_pk_f16_f32 v91, v130, v131
	global_store_dwordx4 v219, v[88:91], s[60:61] sc1
	v_pk_mul_f32 v[92:93], v[174:175], v[130:131]
	v_pk_mul_f32 v[94:95], v[176:177], v[136:137]
	v_pk_mul_f32 v[90:91], v[170:171], v[122:123]
	v_pk_mul_f32 v[88:89], v[172:173], v[124:125]
	s_nop 0
	v_cvt_pk_bf16_f32 v88, v88, v89
	v_cvt_pk_bf16_f32 v89, v90, v91
	v_cvt_pk_bf16_f32 v90, v94, v95
	v_cvt_pk_bf16_f32 v91, v92, v93
	global_store_dwordx4 v219, v[88:91], s[58:59] sc1
	s_waitcnt vmcnt(13)
	s_nop 0
	v_cvt_f32_f16_e32 v88, v148
	v_cvt_f32_f16_sdwa v89, v148 dst_sel:DWORD dst_unused:UNUSED_PAD src0_sel:WORD_1
	v_cvt_f32_f16_e32 v90, v149
	v_cvt_f32_f16_sdwa v91, v149 dst_sel:DWORD dst_unused:UNUSED_PAD src0_sel:WORD_1
	v_pk_fma_f32 v[148:149], v[84:85], v[132:133], v[88:89]
	v_cvt_f32_f16_e32 v84, v150
	v_pk_fma_f32 v[138:139], v[86:87], v[134:135], v[90:91]
	v_cvt_f32_f16_sdwa v85, v150 dst_sel:DWORD dst_unused:UNUSED_PAD src0_sel:WORD_1
	v_cvt_f32_f16_e32 v86, v151
	v_cvt_f32_f16_sdwa v87, v151 dst_sel:DWORD dst_unused:UNUSED_PAD src0_sel:WORD_1
	v_pk_fma_f32 v[150:151], v[80:81], v[140:141], v[84:85]
	v_cvt_pk_f16_f32 v80, v148, v149
	v_pk_fma_f32 v[120:121], v[82:83], v[142:143], v[86:87]
	v_cvt_pk_f16_f32 v81, v138, v139
	v_cvt_pk_f16_f32 v82, v150, v151
	v_cvt_pk_f16_f32 v83, v120, v121
	global_store_dwordx4 v218, v[80:83], s[60:61] sc1
	v_pk_mul_f32 v[84:85], v[174:175], v[120:121]
	v_pk_mul_f32 v[86:87], v[176:177], v[150:151]
	v_pk_mul_f32 v[82:83], v[170:171], v[138:139]
	v_pk_mul_f32 v[80:81], v[172:173], v[148:149]
	s_nop 0
	v_cvt_pk_bf16_f32 v80, v80, v81
	v_cvt_pk_bf16_f32 v81, v82, v83
	v_cvt_pk_bf16_f32 v82, v86, v87
	v_cvt_pk_bf16_f32 v83, v84, v85
	global_store_dwordx4 v218, v[80:83], s[58:59] sc1
	s_waitcnt vmcnt(14)
	s_nop 0
	v_cvt_f32_f16_e32 v80, v144
	v_cvt_f32_f16_sdwa v81, v144 dst_sel:DWORD dst_unused:UNUSED_PAD src0_sel:WORD_1
	v_cvt_f32_f16_e32 v82, v145
	v_cvt_f32_f16_sdwa v83, v145 dst_sel:DWORD dst_unused:UNUSED_PAD src0_sel:WORD_1
	v_pk_fma_f32 v[128:129], v[76:77], v[132:133], v[80:81]
	v_cvt_f32_f16_e32 v76, v146
	v_pk_fma_f32 v[126:127], v[78:79], v[134:135], v[82:83]
	v_cvt_f32_f16_sdwa v77, v146 dst_sel:DWORD dst_unused:UNUSED_PAD src0_sel:WORD_1
	v_cvt_f32_f16_e32 v78, v147
	v_cvt_f32_f16_sdwa v79, v147 dst_sel:DWORD dst_unused:UNUSED_PAD src0_sel:WORD_1
	v_pk_fma_f32 v[134:135], v[72:73], v[140:141], v[76:77]
	v_cvt_pk_f16_f32 v72, v128, v129
	v_pk_fma_f32 v[132:133], v[74:75], v[142:143], v[78:79]
	v_cvt_pk_f16_f32 v73, v126, v127
	v_cvt_pk_f16_f32 v74, v134, v135
	v_cvt_pk_f16_f32 v75, v132, v133
	global_store_dwordx4 v201, v[72:75], s[60:61] sc1
	v_pk_mul_f32 v[76:77], v[174:175], v[132:133]
	v_pk_mul_f32 v[78:79], v[176:177], v[134:135]
	v_pk_mul_f32 v[74:75], v[170:171], v[126:127]
	v_pk_mul_f32 v[72:73], v[172:173], v[128:129]
	s_nop 0
	v_cvt_pk_bf16_f32 v72, v72, v73
	v_cvt_pk_bf16_f32 v73, v74, v75
	v_cvt_pk_bf16_f32 v74, v78, v79
	v_cvt_pk_bf16_f32 v75, v76, v77
	global_store_dwordx4 v201, v[72:75], s[58:59] sc1
	v_add_u32_e32 v76, 0x200, v160
	global_load_dwordx4 v[72:75], v76, s[64:65]
	v_mov_b32_e32 v77, v161
	s_cbranch_vccnz .LBB0_1127
	v_lshl_add_u64 v[78:79], s[56:57], 0, v[76:77]
	global_load_dwordx4 v[78:81], v[78:79], off
	s_waitcnt vmcnt(0)
	v_pk_mul_f32 v[74:75], v[74:75], v[80:81]
	v_pk_mul_f32 v[72:73], v[72:73], v[78:79]

; __device__ __forceinline__ float h16_lo(unsigned u) { return (float)__builtin_bit_cast(h16x2, u).x; }
; __device__ __forceinline__ float h16_hi(unsigned u) { return (float)__builtin_bit_cast(h16x2, u).y; }
; __device__ __forceinline__ unsigned cvt_pk_bf16(float lo, float hi) { unsigned r; asm volatile("v_cvt_pk_bf16_f32 %0, %1, %2" : "=v"(r) : "v"(lo), "v"(hi)); return r; }
;     __device__ __forceinline__ void operator()(const f32x4 (&acc)[2][2][4][2], const Unit& u, int wr, int wc, int fr, int fq, const PG8_LAS float*) const {
;     ...
;         for (int bj = 0; bj < 2; ++bj) {
;             f32x4 gv[2], gm[2];
; #pragma unroll
;             for (int n = 0; n < 2; ++n) { const unsigned c = co + (unsigned)(bj * HALF + n * 4) * 4u;
;                 gv[n] = *(const gf32x4*)(gate + c); if (ls) gv[n] = gv[n] * *(const gf32x4*)(lsp + c);
;                 gm[n] = An ? *(const gf32x4*)(gnp + c) * (*(const gf32x4*)(scp + c) + 1.0f) : (f32x4){0.f, 0.f, 0.f, 0.f}; }
;             u32x4 bs[2][4];
; #pragma unroll
;             for (int ai = 0; ai < 2; ++ai)
; #pragma unroll
;                 for (int m = 0; m < 4; ++m) { const unsigned o = lo + (unsigned)((ai * HALF + m * 16) * DM + bj * HALF) * 2u; bs[ai][m] = *(const gu32x4*)(bt + o); }
;             asm volatile("" ::: "memory");
; #pragma unroll
;             for (int ai = 0; ai < 2; ++ai)
; #pragma unroll
;                 for (int m = 0; m < 4; ++m) { const unsigned o = lo + (unsigned)((ai * HALF + m * 16) * DM + bj * HALF) * 2u; const u32x4 b = bs[ai][m];
;                     const f32x4 x0 = (f32x4){h16_lo(b.x), h16_hi(b.x), h16_lo(b.y), h16_hi(b.y)} + acc[ai][bj][m][0] * gv[0], x1 = (f32x4){h16_lo(b.z), h16_hi(b.z), h16_lo(b.w), h16_hi(b.w)} + acc[ai][bj][m][1] * gv[1];
;                     { u32x4 w; w.x = pk_h16(x0.x, x0.y); w.y = pk_h16(x0.z, x0.w); w.z = pk_h16(x1.x, x1.y); w.w = pk_h16(x1.z, x1.w); *(gu32x4*)(ot + o) = w; }
;                     ssq[ai][m] += (x0.x * x0.x + x0.y * x0.y) + (x0.z * x0.z + x0.w * x0.w) + (x1.x * x1.x + x1.y * x1.y) + (x1.z * x1.z + x1.w * x1.w);
;                     if (An) { const f32x4 y0 = x0 * gm[0], y1 = x1 * gm[1]; u32x4 w; w.x = cvt_pk_bf16(y0.x, y0.y); w.y = cvt_pk_bf16(y0.z, y0.w); w.z = cvt_pk_bf16(y1.x, y1.y); w.w = cvt_pk_bf16(y1.z, y1.w); *(gu32x4*)(at + o) = w; } }
.LBB0_1129:
	s_waitcnt vmcnt(1)
	v_pk_add_f32 v[84:85], v[84:85], 1.0 op_sel_hi:[1,0]
	v_pk_add_f32 v[86:87], v[86:87], 1.0 op_sel_hi:[1,0]
	v_pk_mul_f32 v[142:143], v[80:81], v[84:85]
	v_mul_f32_e32 v80, v181, v181
	v_mul_f32_e32 v81, v179, v179
	v_fmac_f32_e32 v80, v180, v180
	v_fmac_f32_e32 v81, v178, v178
	v_add_f32_e32 v80, v80, v81
	v_mul_f32_e32 v81, v185, v185
	v_fmac_f32_e32 v81, v184, v184
	v_add_f32_e32 v80, v81, v80
	v_mul_f32_e32 v81, v183, v183
	v_fmac_f32_e32 v81, v182, v182
	v_add_f32_e32 v158, v81, v80
	v_mul_f32_e32 v80, v189, v189
	v_mul_f32_e32 v81, v187, v187
	v_fmac_f32_e32 v80, v188, v188
	v_fmac_f32_e32 v81, v186, v186
	v_add_f32_e32 v80, v80, v81
	v_mul_f32_e32 v81, v193, v193
	v_fmac_f32_e32 v81, v192, v192
	v_add_f32_e32 v80, v81, v80
	v_mul_f32_e32 v81, v191, v191
	v_fmac_f32_e32 v81, v190, v190
	v_add_f32_e32 v156, v81, v80
	v_mul_f32_e32 v80, v195, v195
	v_mul_f32_e32 v81, v167, v167
	v_fmac_f32_e32 v80, v194, v194
	v_fmac_f32_e32 v81, v166, v166
	v_add_f32_e32 v80, v80, v81
	v_mul_f32_e32 v81, v197, v197
	v_fmac_f32_e32 v81, v196, v196
	v_add_f32_e32 v80, v81, v80
	v_mul_f32_e32 v81, v169, v169
	v_fmac_f32_e32 v81, v168, v168
	v_add_f32_e32 v154, v81, v80
	v_mul_f32_e32 v80, v109, v109
	v_mul_f32_e32 v81, v111, v111
	v_fmac_f32_e32 v80, v108, v108
	v_fmac_f32_e32 v81, v110, v110
	v_add_f32_e32 v80, v80, v81
	v_mul_f32_e32 v81, v105, v105
	v_fmac_f32_e32 v81, v104, v104
	v_add_f32_e32 v80, v81, v80
	v_mul_f32_e32 v81, v107, v107
	v_fmac_f32_e32 v81, v106, v106
	v_add_f32_e32 v152, v81, v80
	v_lshl_add_u64 v[80:81], s[10:11], 0, v[160:161]
	v_lshl_add_u64 v[84:85], s[62:63], 0, v[160:161]
	v_add_u32_e32 v166, 0x100, v200
	v_pk_mul_f32 v[140:141], v[82:83], v[86:87]
	global_load_dwordx4 v[80:83], v[80:81], off
	s_nop 0
	global_load_dwordx4 v[84:87], v[84:85], off
	v_add_u32_e32 v167, 0x10100, v200
	global_load_dwordx4 v[108:111], v166, s[60:61]
	global_load_dwordx4 v[104:107], v167, s[60:61]
	v_add_u32_e32 v168, 0x20100, v200
	global_load_dwordx4 v[100:103], v168, s[60:61]
	v_add_u32_e32 v160, 0x30100, v200
	global_load_dwordx4 v[96:99], v160, s[60:61]
	v_add_u32_e32 v159, 0x80100, v200
	global_load_dwordx4 v[92:95], v159, s[60:61]
	v_add_u32_e32 v157, 0x90100, v200
	global_load_dwordx4 v[88:91], v157, s[60:61]
	v_add_u32_e32 v155, 0xa0100, v200
	v_add_u32_e32 v153, 0xb0100, v200
	s_waitcnt vmcnt(6)
	v_pk_add_f32 v[86:87], v[86:87], 1.0 op_sel_hi:[1,0]
	v_pk_add_f32 v[84:85], v[84:85], 1.0 op_sel_hi:[1,0]
	s_waitcnt vmcnt(5)
	v_cvt_f32_f16_e32 v162, v108
	v_cvt_f32_f16_sdwa v163, v108 dst_sel:DWORD dst_unused:UNUSED_PAD src0_sel:WORD_1
	v_cvt_f32_f16_e32 v108, v109
	v_cvt_f32_f16_sdwa v109, v109 dst_sel:DWORD dst_unused:UNUSED_PAD src0_sel:WORD_1
	v_pk_mul_f32 v[144:145], v[82:83], v[86:87]
	v_pk_fma_f32 v[68:69], v[68:69], v[72:73], v[162:163]
	v_pk_mul_f32 v[146:147], v[80:81], v[84:85]
	v_pk_fma_f32 v[70:71], v[70:71], v[74:75], v[108:109]
	v_cvt_f32_f16_e32 v108, v110
	v_cvt_f32_f16_sdwa v109, v110 dst_sel:DWORD dst_unused:UNUSED_PAD src0_sel:WORD_1
	v_cvt_f32_f16_e32 v110, v111
	v_cvt_f32_f16_sdwa v111, v111 dst_sel:DWORD dst_unused:UNUSED_PAD src0_sel:WORD_1
	global_load_dwordx4 v[80:83], v155, s[60:61]
	global_load_dwordx4 v[84:87], v153, s[60:61]
	v_pk_fma_f32 v[108:109], v[64:65], v[76:77], v[108:109]
	v_pk_fma_f32 v[110:111], v[66:67], v[78:79], v[110:111]
	v_cvt_pk_f16_f32 v64, v68, v69
	v_cvt_pk_f16_f32 v65, v70, v71
	v_cvt_pk_f16_f32 v66, v108, v109
	v_cvt_pk_f16_f32 v67, v110, v111
	global_store_dwordx4 v166, v[64:67], s[60:61] sc1
	s_nop 1
	v_pk_mul_f32 v[64:65], v[70:71], v[70:71]
	v_pk_mul_f32 v[66:67], v[68:69], v[68:69]
	v_pk_mul_f32 v[70:71], v[140:141], v[70:71]
	v_pk_mov_b32 v[162:163], v[66:67], v[64:65] op_sel:[1,0]
	v_mov_b32_e32 v67, v65
	v_pk_add_f32 v[64:65], v[162:163], v[66:67]
	v_pk_mul_f32 v[66:67], v[110:111], v[110:111]
	v_pk_mul_f32 v[162:163], v[108:109], v[108:109]
	v_mov_b32_e32 v164, v66
	v_mov_b32_e32 v165, v162
	v_mov_b32_e32 v162, v67
	v_pk_add_f32 v[66:67], v[164:165], v[162:163]
	v_add_f32_e32 v64, v64, v65
	v_add_f32_e32 v64, v67, v64
	v_add_f32_e32 v64, v66, v64
	v_pk_mul_f32 v[66:67], v[142:143], v[68:69]
	v_pk_mul_f32 v[68:69], v[146:147], v[108:109]
	v_pk_mul_f32 v[110:111], v[144:145], v[110:111]
	v_cvt_pk_bf16_f32 v66, v66, v67
	v_cvt_pk_bf16_f32 v67, v70, v71
	v_cvt_pk_bf16_f32 v68, v68, v69
	v_add_f32_e32 v64, v158, v64
	v_cvt_pk_bf16_f32 v69, v110, v111
	global_store_dwordx4 v166, v[66:69], s[58:59] sc1
	s_waitcnt vmcnt(8)
	s_nop 0
	v_cvt_f32_f16_e32 v66, v104
	v_cvt_f32_f16_sdwa v67, v104 dst_sel:DWORD dst_unused:UNUSED_PAD src0_sel:WORD_1
	v_cvt_f32_f16_e32 v68, v105
	v_cvt_f32_f16_sdwa v69, v105 dst_sel:DWORD dst_unused:UNUSED_PAD src0_sel:WORD_1
	v_pk_fma_f32 v[60:61], v[60:61], v[72:73], v[66:67]
	v_cvt_f32_f16_e32 v66, v106
	v_pk_fma_f32 v[62:63], v[62:63], v[74:75], v[68:69]
	v_cvt_f32_f16_sdwa v67, v106 dst_sel:DWORD dst_unused:UNUSED_PAD src0_sel:WORD_1
	v_cvt_f32_f16_e32 v68, v107
	v_cvt_f32_f16_sdwa v69, v107 dst_sel:DWORD dst_unused:UNUSED_PAD src0_sel:WORD_1
	v_pk_fma_f32 v[66:67], v[56:57], v[76:77], v[66:67]
	v_cvt_pk_f16_f32 v56, v60, v61
	v_pk_fma_f32 v[68:69], v[58:59], v[78:79], v[68:69]
	v_cvt_pk_f16_f32 v57, v62, v63
	v_cvt_pk_f16_f32 v58, v66, v67
	v_cvt_pk_f16_f32 v59, v68, v69
	global_store_dwordx4 v167, v[56:59], s[60:61] sc1
	s_nop 1
	v_mul_f32_e32 v56, v61, v61
	v_mul_f32_e32 v57, v63, v63
	v_fmac_f32_e32 v56, v60, v60
	v_fmac_f32_e32 v57, v62, v62
	v_add_f32_e32 v56, v56, v57
	v_mul_f32_e32 v57, v67, v67
	v_fmac_f32_e32 v57, v66, v66
	v_add_f32_e32 v56, v57, v56
	v_mul_f32_e32 v57, v69, v69
	v_pk_mul_f32 v[58:59], v[142:143], v[60:61]
	v_pk_mul_f32 v[60:61], v[146:147], v[66:67]
	v_fmac_f32_e32 v57, v68, v68
	v_pk_mul_f32 v[62:63], v[140:141], v[62:63]
	v_pk_mul_f32 v[68:69], v[144:145], v[68:69]
	v_cvt_pk_bf16_f32 v58, v58, v59
	v_cvt_pk_bf16_f32 v59, v62, v63
	v_cvt_pk_bf16_f32 v60, v60, v61
	v_add_f32_e32 v56, v57, v56
	v_cvt_pk_bf16_f32 v61, v68, v69
	global_store_dwordx4 v167, v[58:61], s[58:59] sc1
	v_add_f32_e32 v56, v156, v56
	s_waitcnt vmcnt(9)
; __device__ __forceinline__ float h16_lo(unsigned u) { return (float)__builtin_bit_cast(h16x2, u).x; }
; __device__ __forceinline__ float h16_hi(unsigned u) { return (float)__builtin_bit_cast(h16x2, u).y; }
; __device__ __forceinline__ unsigned cvt_pk_bf16(float lo, float hi) { unsigned r; asm volatile("v_cvt_pk_bf16_f32 %0, %1, %2" : "=v"(r) : "v"(lo), "v"(hi)); return r; }
;     __device__ __forceinline__ void operator()(const f32x4 (&acc)[2][2][4][2], const Unit& u, int wr, int wc, int fr, int fq, const PG8_LAS float*) const {
;     ...
; #pragma unroll
;             for (int ai = 0; ai < 2; ++ai)
; #pragma unroll
;                 for (int m = 0; m < 4; ++m) { const unsigned o = lo + (unsigned)((ai * HALF + m * 16) * DM + bj * HALF) * 2u; const u32x4 b = bs[ai][m];
;                     const f32x4 x0 = (f32x4){h16_lo(b.x), h16_hi(b.x), h16_lo(b.y), h16_hi(b.y)} + acc[ai][bj][m][0] * gv[0], x1 = (f32x4){h16_lo(b.z), h16_hi(b.z), h16_lo(b.w), h16_hi(b.w)} + acc[ai][bj][m][1] * gv[1];
;                     { u32x4 w; w.x = pk_h16(x0.x, x0.y); w.y = pk_h16(x0.z, x0.w); w.z = pk_h16(x1.x, x1.y); w.w = pk_h16(x1.z, x1.w); *(gu32x4*)(ot + o) = w; }
;                     ssq[ai][m] += (x0.x * x0.x + x0.y * x0.y) + (x0.z * x0.z + x0.w * x0.w) + (x1.x * x1.x + x1.y * x1.y) + (x1.z * x1.z + x1.w * x1.w);
;                     if (An) { const f32x4 y0 = x0 * gm[0], y1 = x1 * gm[1]; u32x4 w; w.x = cvt_pk_bf16(y0.x, y0.y); w.y = cvt_pk_bf16(y0.z, y0.w); w.z = cvt_pk_bf16(y1.x, y1.y); w.w = cvt_pk_bf16(y1.z, y1.w); *(gu32x4*)(at + o) = w; } }
	v_cvt_f32_f16_e32 v58, v100
	v_cvt_f32_f16_sdwa v59, v100 dst_sel:DWORD dst_unused:UNUSED_PAD src0_sel:WORD_1
	v_cvt_f32_f16_e32 v60, v101
	v_cvt_f32_f16_sdwa v61, v101 dst_sel:DWORD dst_unused:UNUSED_PAD src0_sel:WORD_1
	v_pk_fma_f32 v[52:53], v[52:53], v[72:73], v[58:59]
	v_cvt_f32_f16_e32 v58, v102
	v_pk_fma_f32 v[54:55], v[54:55], v[74:75], v[60:61]
	v_cvt_f32_f16_sdwa v59, v102 dst_sel:DWORD dst_unused:UNUSED_PAD src0_sel:WORD_1
	v_cvt_f32_f16_e32 v60, v103
	v_cvt_f32_f16_sdwa v61, v103 dst_sel:DWORD dst_unused:UNUSED_PAD src0_sel:WORD_1
	v_pk_fma_f32 v[58:59], v[48:49], v[76:77], v[58:59]
	v_cvt_pk_f16_f32 v48, v52, v53
	v_pk_fma_f32 v[60:61], v[50:51], v[78:79], v[60:61]
	v_cvt_pk_f16_f32 v49, v54, v55
	v_cvt_pk_f16_f32 v50, v58, v59
	v_cvt_pk_f16_f32 v51, v60, v61
	global_store_dwordx4 v168, v[48:51], s[60:61] sc1
	s_nop 1
	v_mul_f32_e32 v48, v53, v53
	v_mul_f32_e32 v49, v55, v55
	v_fmac_f32_e32 v48, v52, v52
	v_fmac_f32_e32 v49, v54, v54
	v_add_f32_e32 v48, v48, v49
	v_mul_f32_e32 v49, v59, v59
	v_fmac_f32_e32 v49, v58, v58
	v_add_f32_e32 v48, v49, v48
	v_mul_f32_e32 v49, v61, v61
	v_fmac_f32_e32 v49, v60, v60
	v_add_f32_e32 v48, v49, v48
	v_add_f32_e32 v57, v154, v48
	v_pk_mul_f32 v[50:51], v[140:141], v[54:55]
	v_pk_mul_f32 v[48:49], v[142:143], v[52:53]
	v_pk_mul_f32 v[52:53], v[144:145], v[60:61]
	v_pk_mul_f32 v[54:55], v[146:147], v[58:59]
	v_cvt_pk_bf16_f32 v48, v48, v49
	v_cvt_pk_bf16_f32 v49, v50, v51
	s_nop 0
	v_cvt_pk_bf16_f32 v50, v54, v55
	v_cvt_pk_bf16_f32 v51, v52, v53
	global_store_dwordx4 v168, v[48:51], s[58:59] sc1
	s_waitcnt vmcnt(10)
	s_nop 0
	v_cvt_f32_f16_e32 v48, v96
	v_cvt_f32_f16_sdwa v49, v96 dst_sel:DWORD dst_unused:UNUSED_PAD src0_sel:WORD_1
	v_cvt_f32_f16_e32 v50, v97
	v_cvt_f32_f16_sdwa v51, v97 dst_sel:DWORD dst_unused:UNUSED_PAD src0_sel:WORD_1
	v_pk_fma_f32 v[44:45], v[44:45], v[72:73], v[48:49]
	v_cvt_f32_f16_e32 v48, v98
	v_pk_fma_f32 v[46:47], v[46:47], v[74:75], v[50:51]
	v_cvt_f32_f16_sdwa v49, v98 dst_sel:DWORD dst_unused:UNUSED_PAD src0_sel:WORD_1
	v_cvt_f32_f16_e32 v50, v99
	v_cvt_f32_f16_sdwa v51, v99 dst_sel:DWORD dst_unused:UNUSED_PAD src0_sel:WORD_1
	v_pk_fma_f32 v[48:49], v[40:41], v[76:77], v[48:49]
	v_cvt_pk_f16_f32 v40, v44, v45
	v_pk_fma_f32 v[50:51], v[42:43], v[78:79], v[50:51]
	v_cvt_pk_f16_f32 v41, v46, v47
	v_cvt_pk_f16_f32 v42, v48, v49
	v_cvt_pk_f16_f32 v43, v50, v51
	global_store_dwordx4 v160, v[40:43], s[60:61] sc1
	s_nop 1
	v_mul_f32_e32 v40, v45, v45
	v_mul_f32_e32 v41, v47, v47
	v_fmac_f32_e32 v40, v44, v44
	v_fmac_f32_e32 v41, v46, v46
	v_add_f32_e32 v40, v40, v41
	v_mul_f32_e32 v41, v49, v49
	v_fmac_f32_e32 v41, v48, v48
	v_add_f32_e32 v40, v41, v40
	v_mul_f32_e32 v41, v51, v51
	v_fmac_f32_e32 v41, v50, v50
	v_add_f32_e32 v40, v41, v40
	v_add_f32_e32 v52, v152, v40
	v_pk_mul_f32 v[42:43], v[140:141], v[46:47]
	v_pk_mul_f32 v[40:41], v[142:143], v[44:45]
	v_pk_mul_f32 v[44:45], v[144:145], v[50:51]
	v_pk_mul_f32 v[46:47], v[146:147], v[48:49]
	v_cvt_pk_bf16_f32 v40, v40, v41
	v_cvt_pk_bf16_f32 v41, v42, v43
	s_nop 0
	v_cvt_pk_bf16_f32 v42, v46, v47
	v_cvt_pk_bf16_f32 v43, v44, v45
	global_store_dwordx4 v160, v[40:43], s[58:59] sc1
	s_waitcnt vmcnt(11)
	s_nop 0
	v_cvt_f32_f16_e32 v40, v92
	v_cvt_f32_f16_sdwa v41, v92 dst_sel:DWORD dst_unused:UNUSED_PAD src0_sel:WORD_1
	v_cvt_f32_f16_e32 v42, v93
	v_cvt_f32_f16_sdwa v43, v93 dst_sel:DWORD dst_unused:UNUSED_PAD src0_sel:WORD_1
	v_pk_fma_f32 v[36:37], v[36:37], v[72:73], v[40:41]
	v_cvt_f32_f16_e32 v40, v94
	v_pk_fma_f32 v[38:39], v[38:39], v[74:75], v[42:43]
	v_cvt_f32_f16_sdwa v41, v94 dst_sel:DWORD dst_unused:UNUSED_PAD src0_sel:WORD_1
	v_cvt_f32_f16_e32 v42, v95
	v_cvt_f32_f16_sdwa v43, v95 dst_sel:DWORD dst_unused:UNUSED_PAD src0_sel:WORD_1
	v_pk_fma_f32 v[32:33], v[32:33], v[76:77], v[40:41]
	v_cvt_pk_f16_f32 v40, v36, v37
	v_pk_fma_f32 v[34:35], v[34:35], v[78:79], v[42:43]
	v_cvt_pk_f16_f32 v41, v38, v39
	v_cvt_pk_f16_f32 v42, v32, v33
	v_cvt_pk_f16_f32 v43, v34, v35
	global_store_dwordx4 v159, v[40:43], s[60:61] sc1
	v_pk_mul_f32 v[44:45], v[144:145], v[34:35]
	v_pk_mul_f32 v[46:47], v[146:147], v[32:33]
	v_pk_mul_f32 v[42:43], v[140:141], v[38:39]
	v_pk_mul_f32 v[40:41], v[142:143], v[36:37]
	s_nop 0
	v_cvt_pk_bf16_f32 v40, v40, v41
	v_cvt_pk_bf16_f32 v41, v42, v43
	v_cvt_pk_bf16_f32 v42, v46, v47
	v_cvt_pk_bf16_f32 v43, v44, v45
	global_store_dwordx4 v159, v[40:43], s[58:59] sc1
	s_waitcnt vmcnt(12)
; #define GAS __attribute__((address_space(1)))
; __device__ __forceinline__ float h16_lo(unsigned u) { return (float)__builtin_bit_cast(h16x2, u).x; }
; __device__ __forceinline__ float h16_hi(unsigned u) { return (float)__builtin_bit_cast(h16x2, u).y; }
; __device__ __forceinline__ unsigned cvt_pk_bf16(float lo, float hi) { unsigned r; asm volatile("v_cvt_pk_bf16_f32 %0, %1, %2" : "=v"(r) : "v"(lo), "v"(hi)); return r; }
; __device__ __forceinline__ void atomic_add_f32(gf32* p, float v) { (void)__builtin_amdgcn_global_atomic_fadd_f32(p, v); }
;     __device__ __forceinline__ void operator()(const f32x4 (&acc)[2][2][4][2], const Unit& u, int wr, int wc, int fr, int fq, const PG8_LAS float*) const {
;     ...
; #pragma unroll
;             for (int ai = 0; ai < 2; ++ai)
; #pragma unroll
;                 for (int m = 0; m < 4; ++m) { const unsigned o = lo + (unsigned)((ai * HALF + m * 16) * DM + bj * HALF) * 2u; const u32x4 b = bs[ai][m];
;                     const f32x4 x0 = (f32x4){h16_lo(b.x), h16_hi(b.x), h16_lo(b.y), h16_hi(b.y)} + acc[ai][bj][m][0] * gv[0], x1 = (f32x4){h16_lo(b.z), h16_hi(b.z), h16_lo(b.w), h16_hi(b.w)} + acc[ai][bj][m][1] * gv[1];
;                     { u32x4 w; w.x = pk_h16(x0.x, x0.y); w.y = pk_h16(x0.z, x0.w); w.z = pk_h16(x1.x, x1.y); w.w = pk_h16(x1.z, x1.w); *(gu32x4*)(ot + o) = w; }
;                     ssq[ai][m] += (x0.x * x0.x + x0.y * x0.y) + (x0.z * x0.z + x0.w * x0.w) + (x1.x * x1.x + x1.y * x1.y) + (x1.z * x1.z + x1.w * x1.w);
;                     if (An) { const f32x4 y0 = x0 * gm[0], y1 = x1 * gm[1]; u32x4 w; w.x = cvt_pk_bf16(y0.x, y0.y); w.y = cvt_pk_bf16(y0.z, y0.w); w.z = cvt_pk_bf16(y1.x, y1.y); w.w = cvt_pk_bf16(y1.z, y1.w); *(gu32x4*)(at + o) = w; } }
;             asm volatile("" ::: "memory");
;         }
;         if (stats) {
; #pragma unroll
;             for (int ai = 0; ai < 2; ++ai) {
; #pragma unroll
;                 for (int m = 0; m < 4; ++m) { ssq[ai][m] += __shfl_xor(ssq[ai][m], 16); ssq[ai][m] += __shfl_xor(ssq[ai][m], 32); }
;                 const float v = fq == 0 ? ssq[ai][0] : fq == 1 ? ssq[ai][1] : fq == 2 ? ssq[ai][2] : ssq[ai][3];
;                 atomic_add_f32((gf32*)((GAS char*)(stats + u.pm * BM + ai * HALF) + so), v); }
	s_nop 0
	v_cvt_f32_f16_e32 v40, v88
	v_cvt_f32_f16_sdwa v41, v88 dst_sel:DWORD dst_unused:UNUSED_PAD src0_sel:WORD_1
	v_cvt_f32_f16_e32 v42, v89
	v_cvt_f32_f16_sdwa v43, v89 dst_sel:DWORD dst_unused:UNUSED_PAD src0_sel:WORD_1
	v_pk_fma_f32 v[28:29], v[28:29], v[72:73], v[40:41]
	v_cvt_f32_f16_e32 v40, v90
	v_pk_fma_f32 v[30:31], v[30:31], v[74:75], v[42:43]
	v_cvt_f32_f16_sdwa v41, v90 dst_sel:DWORD dst_unused:UNUSED_PAD src0_sel:WORD_1
	v_cvt_f32_f16_e32 v42, v91
	v_cvt_f32_f16_sdwa v43, v91 dst_sel:DWORD dst_unused:UNUSED_PAD src0_sel:WORD_1
	v_pk_fma_f32 v[24:25], v[24:25], v[76:77], v[40:41]
	v_cvt_pk_f16_f32 v40, v28, v29
	v_pk_fma_f32 v[26:27], v[26:27], v[78:79], v[42:43]
	v_cvt_pk_f16_f32 v41, v30, v31
	v_cvt_pk_f16_f32 v42, v24, v25
	v_cvt_pk_f16_f32 v43, v26, v27
	global_store_dwordx4 v157, v[40:43], s[60:61] sc1
	v_pk_mul_f32 v[44:45], v[144:145], v[26:27]
	v_pk_mul_f32 v[46:47], v[146:147], v[24:25]
	v_pk_mul_f32 v[42:43], v[140:141], v[30:31]
	v_pk_mul_f32 v[40:41], v[142:143], v[28:29]
	s_nop 0
	v_cvt_pk_bf16_f32 v40, v40, v41
	v_cvt_pk_bf16_f32 v41, v42, v43
	v_cvt_pk_bf16_f32 v42, v46, v47
	v_cvt_pk_bf16_f32 v43, v44, v45
	global_store_dwordx4 v157, v[40:43], s[58:59] sc1
	s_waitcnt vmcnt(13)
	s_nop 0
	v_cvt_f32_f16_e32 v40, v80
	v_cvt_f32_f16_sdwa v41, v80 dst_sel:DWORD dst_unused:UNUSED_PAD src0_sel:WORD_1
	v_cvt_f32_f16_e32 v42, v81
	v_cvt_f32_f16_sdwa v43, v81 dst_sel:DWORD dst_unused:UNUSED_PAD src0_sel:WORD_1
	v_pk_fma_f32 v[20:21], v[20:21], v[72:73], v[40:41]
	v_cvt_f32_f16_e32 v40, v82
	v_pk_fma_f32 v[22:23], v[22:23], v[74:75], v[42:43]
	v_cvt_f32_f16_sdwa v41, v82 dst_sel:DWORD dst_unused:UNUSED_PAD src0_sel:WORD_1
	v_cvt_f32_f16_e32 v42, v83
	v_cvt_f32_f16_sdwa v43, v83 dst_sel:DWORD dst_unused:UNUSED_PAD src0_sel:WORD_1
	v_pk_fma_f32 v[16:17], v[16:17], v[76:77], v[40:41]
	v_cvt_pk_f16_f32 v40, v20, v21
	v_pk_fma_f32 v[18:19], v[18:19], v[78:79], v[42:43]
	v_cvt_pk_f16_f32 v41, v22, v23
	v_cvt_pk_f16_f32 v42, v16, v17
	v_cvt_pk_f16_f32 v43, v18, v19
	global_store_dwordx4 v155, v[40:43], s[60:61] sc1
	v_pk_mul_f32 v[44:45], v[144:145], v[18:19]
	v_pk_mul_f32 v[46:47], v[146:147], v[16:17]
	v_pk_mul_f32 v[42:43], v[140:141], v[22:23]
	v_pk_mul_f32 v[40:41], v[142:143], v[20:21]
	s_nop 0
	v_cvt_pk_bf16_f32 v40, v40, v41
	v_cvt_pk_bf16_f32 v41, v42, v43
	v_cvt_pk_bf16_f32 v42, v46, v47
	v_cvt_pk_bf16_f32 v43, v44, v45
	global_store_dwordx4 v155, v[40:43], s[58:59] sc1
	s_waitcnt vmcnt(14)
	s_nop 0
	v_cvt_f32_f16_e32 v40, v84
	v_cvt_f32_f16_sdwa v41, v84 dst_sel:DWORD dst_unused:UNUSED_PAD src0_sel:WORD_1
	v_cvt_f32_f16_e32 v42, v85
	v_cvt_f32_f16_sdwa v43, v85 dst_sel:DWORD dst_unused:UNUSED_PAD src0_sel:WORD_1
	v_pk_fma_f32 v[12:13], v[12:13], v[72:73], v[40:41]
	v_cvt_f32_f16_e32 v40, v86
	v_pk_fma_f32 v[14:15], v[14:15], v[74:75], v[42:43]
	v_cvt_f32_f16_sdwa v41, v86 dst_sel:DWORD dst_unused:UNUSED_PAD src0_sel:WORD_1
	v_cvt_f32_f16_e32 v42, v87
	v_cvt_f32_f16_sdwa v43, v87 dst_sel:DWORD dst_unused:UNUSED_PAD src0_sel:WORD_1
	v_pk_fma_f32 v[8:9], v[8:9], v[76:77], v[40:41]
	v_cvt_pk_f16_f32 v40, v12, v13
	v_pk_fma_f32 v[10:11], v[10:11], v[78:79], v[42:43]
	v_cvt_pk_f16_f32 v41, v14, v15
	v_cvt_pk_f16_f32 v42, v8, v9
	v_cvt_pk_f16_f32 v43, v10, v11
	global_store_dwordx4 v153, v[40:43], s[60:61] sc1
	v_pk_mul_f32 v[44:45], v[144:145], v[10:11]
	v_pk_mul_f32 v[46:47], v[146:147], v[8:9]
	v_pk_mul_f32 v[40:41], v[142:143], v[12:13]
	v_pk_mul_f32 v[42:43], v[140:141], v[14:15]
	v_cvt_pk_bf16_f32 v40, v40, v41
	s_nop 0
	v_cvt_pk_bf16_f32 v41, v42, v43
	v_cvt_pk_bf16_f32 v42, v46, v47
	v_cvt_pk_bf16_f32 v43, v44, v45
	global_store_dwordx4 v153, v[40:43], s[58:59] sc1
	s_mov_b64 s[58:59], 0
	s_nop 0
	v_and_b32_e32 v41, 64, v238
	v_xor_b32_e32 v40, 16, v238
	v_add_u32_e32 v41, 64, v41
	v_cmp_lt_i32_e32 vcc, v40, v41
	v_xor_b32_e32 v42, 32, v238
	s_nop 0
	v_cndmask_b32_e32 v40, v238, v40, vcc
	v_lshlrev_b32_e32 v40, 2, v40
	v_cmp_lt_i32_e32 vcc, v42, v41
	ds_bpermute_b32 v44, v40, v52
	s_waitcnt lgkmcnt(0)
	v_add_f32_e32 v44, v52, v44
	v_cndmask_b32_e32 v41, v238, v42, vcc
	ds_bpermute_b32 v42, v40, v64
	v_lshlrev_b32_e32 v41, 2, v41
	ds_bpermute_b32 v45, v41, v44
	v_cmp_lt_i32_e32 vcc, 0, v198
	s_waitcnt lgkmcnt(1)
	v_add_f32_e32 v46, v64, v42
	ds_bpermute_b32 v42, v40, v56
	ds_bpermute_b32 v47, v41, v46
	s_waitcnt lgkmcnt(1)
	v_add_f32_e32 v48, v56, v42
	ds_bpermute_b32 v42, v40, v57
	ds_bpermute_b32 v49, v41, v48
	s_waitcnt lgkmcnt(1)
	v_add_f32_e32 v42, v57, v42
	ds_bpermute_b32 v43, v41, v42
	s_and_saveexec_b64 s[20:21], vcc
	s_xor_b64 s[28:29], exec, s[20:21]
	s_cbranch_execz .LBB0_1147
	v_cmp_lt_i32_e32 vcc, 1, v198
	s_and_saveexec_b64 s[20:21], vcc
	s_xor_b64 s[60:61], exec, s[20:21]
	s_cbranch_execz .LBB0_1134
	v_cmp_eq_u32_e32 vcc, 2, v198
	s_mov_b64 s[58:59], -1
	s_and_saveexec_b64 s[62:63], vcc
	s_xor_b64 s[58:59], exec, -1
	s_or_b64 exec, exec, s[62:63]
	s_and_b64 s[58:59], s[58:59], exec

; #define GAS __attribute__((address_space(1)))
; __device__ __forceinline__ float h16_lo(unsigned u) { return (float)__builtin_bit_cast(h16x2, u).x; }
; __device__ __forceinline__ float h16_hi(unsigned u) { return (float)__builtin_bit_cast(h16x2, u).y; }
; __device__ __forceinline__ unsigned cvt_pk_bf16(float lo, float hi) { unsigned r; asm volatile("v_cvt_pk_bf16_f32 %0, %1, %2" : "=v"(r) : "v"(lo), "v"(hi)); return r; }
; __device__ __forceinline__ void atomic_add_f32(gf32* p, float v) { (void)__builtin_amdgcn_global_atomic_fadd_f32(p, v); }
;     __device__ __forceinline__ void strip(const f32x4 (&accS)[2], const Unit& u, int wr, int wc, int fr, int fq) const {
;     ...
;         const unsigned co = (unsigned)(wc * 32 + 8 * fq + 4 * wr) * 4u, lo = (unsigned)(fr * DM) * 2u + (co >> 1), so = (unsigned)fr * 4u;
;         float q = 0.f;
; #pragma unroll
;         for (int bj = 0; bj < 2; ++bj) { const unsigned c = co + (unsigned)(bj * HALF) * 4u, o = lo + (unsigned)(bj * HALF) * 2u;
;             f32x4 gv = *(const gf32x4*)(gate + c); if (ls) gv = gv * *(const gf32x4*)(lsp + c);
;             const u32x2 b = *(const gu32x2*)(bt + o);
;             const f32x4 x0 = (f32x4){h16_lo(b.x), h16_hi(b.x), h16_lo(b.y), h16_hi(b.y)} + accS[bj] * gv; { u32x2 w; w.x = pk_h16(x0.x, x0.y); w.y = pk_h16(x0.z, x0.w); *(gu32x2*)(ot + o) = w; }
;             q += (x0.x * x0.x + x0.y * x0.y) + (x0.z * x0.z + x0.w * x0.w);
;             if (An) { const f32x4 y0 = x0 * (*(const gf32x4*)(gnp + c) * (*(const gf32x4*)(scp + c) + 1.0f));
;                 u32x2 w; w.x = cvt_pk_bf16(y0.x, y0.y); w.y = cvt_pk_bf16(y0.z, y0.w); *(gu32x2*)(at + o) = w; } }
;         if (stats) { q += __shfl_xor(q, 16); q += __shfl_xor(q, 32); if (fq == 0) atomic_add_f32((gf32*)((GAS char*)(stats + u.srow) + so), q); }
.LBB0_1155:
	s_add_u32 s40, s95, s12
	s_addc_u32 s41, s96, s13
	s_ashr_i32 s1, s0, 31
	s_lshl_b64 s[12:13], s[0:1], 12
	s_add_u32 s5, s73, s12
	s_addc_u32 s20, s74, s13
	s_add_u32 s28, s5, s14
	v_lshrrev_b32_e32 v14, 1, v160
	s_addc_u32 s29, s20, s15
	v_lshl_add_u32 v14, v12, 12, v14
	global_load_dwordx2 v[16:17], v14, s[28:29]
	s_add_u32 s5, s75, s12
	s_addc_u32 s13, s76, s13
	s_add_u32 s12, s5, s14
	s_addc_u32 s13, s13, s15
	s_and_b64 vcc, exec, s[38:39]
	s_waitcnt vmcnt(0)
	v_cvt_f32_f16_e32 v18, v16
	v_cvt_f32_f16_sdwa v19, v16 dst_sel:DWORD dst_unused:UNUSED_PAD src0_sel:WORD_1
	v_cvt_f32_f16_e32 v16, v17
	v_cvt_f32_f16_sdwa v17, v17 dst_sel:DWORD dst_unused:UNUSED_PAD src0_sel:WORD_1
	v_pk_fma_f32 v[8:9], v[4:5], v[8:9], v[18:19]
	s_nop 0
	v_cvt_pk_f16_f32 v4, v8, v9
	v_pk_fma_f32 v[10:11], v[6:7], v[10:11], v[16:17]
	v_lshl_add_u64 v[16:17], s[40:41], 0, v[160:161]
	v_cvt_pk_f16_f32 v5, v10, v11
	global_store_dwordx2 v14, v[4:5], s[28:29] sc1
	v_lshl_add_u64 v[4:5], s[10:11], 0, v[160:161]
	global_load_dwordx4 v[16:19], v[16:17], off
	v_add_u32_e32 v160, 0x200, v160
	global_load_dwordx4 v[4:7], v[4:5], off
	s_waitcnt vmcnt(1)
	v_pk_add_f32 v[16:17], v[16:17], 1.0 op_sel_hi:[1,0]
	v_pk_add_f32 v[18:19], v[18:19], 1.0 op_sel_hi:[1,0]
	s_waitcnt vmcnt(0)
	v_pk_mul_f32 v[4:5], v[4:5], v[16:17]
	v_pk_mul_f32 v[6:7], v[6:7], v[18:19]
	v_pk_mul_f32 v[4:5], v[4:5], v[8:9]
	v_pk_mul_f32 v[6:7], v[6:7], v[10:11]
	v_cvt_pk_bf16_f32 v4, v4, v5
	s_nop 0
	v_cvt_pk_bf16_f32 v5, v6, v7
	global_store_dwordx2 v14, v[4:5], s[12:13] sc1
	global_load_dwordx4 v[4:7], v160, s[58:59]
	s_cbranch_vccnz .LBB0_1157
	v_lshl_add_u64 v[16:17], s[56:57], 0, v[160:161]
	global_load_dwordx4 v[16:19], v[16:17], off
	s_waitcnt vmcnt(0)
	v_pk_mul_f32 v[6:7], v[6:7], v[18:19]
	v_pk_mul_f32 v[4:5], v[4:5], v[16:17]
.LBB0_1157:
	v_mul_f32_e32 v9, v9, v9
	v_fmac_f32_e32 v9, v8, v8
	v_mul_f32_e32 v8, v11, v11
	v_fmac_f32_e32 v8, v10, v10
	v_add_u32_e32 v14, 0x100, v14
	s_waitcnt lgkmcnt(0)
	v_add_f32_e32 v15, v9, v8
	global_load_dwordx2 v[8:9], v14, s[28:29]
	v_cmp_eq_u32_e32 vcc, 0, v13
	s_waitcnt vmcnt(0)
	v_cvt_f32_f16_e32 v10, v8
	v_cvt_f32_f16_sdwa v11, v8 dst_sel:DWORD dst_unused:UNUSED_PAD src0_sel:WORD_1
	v_cvt_f32_f16_e32 v8, v9
	v_cvt_f32_f16_sdwa v9, v9 dst_sel:DWORD dst_unused:UNUSED_PAD src0_sel:WORD_1
	v_pk_fma_f32 v[10:11], v[0:1], v[4:5], v[10:11]
	s_nop 0
	v_cvt_pk_f16_f32 v0, v10, v11
	v_pk_fma_f32 v[8:9], v[2:3], v[6:7], v[8:9]
	v_lshl_add_u64 v[4:5], s[40:41], 0, v[160:161]
	v_cvt_pk_f16_f32 v1, v8, v9
	global_store_dwordx2 v14, v[0:1], s[28:29] sc1
	v_mul_f32_e32 v0, v11, v11
	v_mul_f32_e32 v1, v9, v9
	v_fmac_f32_e32 v0, v10, v10
	v_fmac_f32_e32 v1, v8, v8
	v_add_f32_e32 v0, v0, v1
	v_add_f32_e32 v15, v15, v0
	v_lshl_add_u64 v[0:1], s[10:11], 0, v[160:161]
	global_load_dwordx4 v[4:7], v[4:5], off
	s_waitcnt vmcnt(0)
	v_pk_add_f32 v[4:5], v[4:5], 1.0 op_sel_hi:[1,0]
	global_load_dwordx4 v[0:3], v[0:1], off
	v_pk_add_f32 v[6:7], v[6:7], 1.0 op_sel_hi:[1,0]
	s_waitcnt vmcnt(0)
	v_pk_mul_f32 v[0:1], v[0:1], v[4:5]
	s_nop 0
	v_pk_mul_f32 v[0:1], v[0:1], v[10:11]
	v_pk_mul_f32 v[2:3], v[2:3], v[6:7]
	v_cvt_pk_bf16_f32 v0, v0, v1
	s_nop 0
	v_pk_mul_f32 v[2:3], v[2:3], v[8:9]
	s_nop 0
	v_cvt_pk_bf16_f32 v1, v2, v3
	global_store_dwordx2 v14, v[0:1], s[12:13] sc1
	ds_bpermute_b32 v0, v40, v15
	s_waitcnt lgkmcnt(0)
	v_add_f32_e32 v0, v15, v0
	ds_bpermute_b32 v1, v41, v0
	s_and_saveexec_b64 s[10:11], vcc
	s_cbranch_execz .LBB0_1159
	s_lshl_b64 s[0:1], s[0:1], 2
	v_readlane_b32 s5, v254, 50
	s_add_u32 s0, s5, s0
	v_readlane_b32 s5, v254, 52
	s_addc_u32 s1, s5, s1
	v_lshlrev_b32_e32 v2, 2, v12
	s_waitcnt lgkmcnt(0)
	v_add_f32_e32 v0, v0, v1
	global_atomic_add_f32 v2, v0, s[0:1]

; __device__ __forceinline__ float h16_lo(unsigned u) { return (float)__builtin_bit_cast(h16x2, u).x; }
; __device__ __forceinline__ float h16_hi(unsigned u) { return (float)__builtin_bit_cast(h16x2, u).y; }
; __device__ __forceinline__ unsigned cvt_pk_bf16(float lo, float hi) { unsigned r; asm volatile("v_cvt_pk_bf16_f32 %0, %1, %2" : "=v"(r) : "v"(lo), "v"(hi)); return r; }
;     __device__ __forceinline__ void operator()(const f32x4 (&acc)[2][2][4][2], const Unit& u, int wr, int wc, int fr, int fq, const PG8_LAS float*) const {
;     ...
;         for (int bj = 0; bj < 2; ++bj) {
;             f32x4 gv[2], gm[2];
; #pragma unroll
;             for (int n = 0; n < 2; ++n) { const unsigned c = co + (unsigned)(bj * HALF + n * 4) * 4u;
;                 gv[n] = *(const gf32x4*)(gate + c); if (ls) gv[n] = gv[n] * *(const gf32x4*)(lsp + c);
;                 gm[n] = An ? *(const gf32x4*)(gnp + c) * (*(const gf32x4*)(scp + c) + 1.0f) : (f32x4){0.f, 0.f, 0.f, 0.f}; }
;             u32x4 bs[2][4];
; #pragma unroll
;             for (int ai = 0; ai < 2; ++ai)
; #pragma unroll
;                 for (int m = 0; m < 4; ++m) { const unsigned o = lo + (unsigned)((ai * HALF + m * 16) * DM + bj * HALF) * 2u; bs[ai][m] = *(const gu32x4*)(bt + o); }
;             asm volatile("" ::: "memory");
; #pragma unroll
;             for (int ai = 0; ai < 2; ++ai)
; #pragma unroll
;                 for (int m = 0; m < 4; ++m) { const unsigned o = lo + (unsigned)((ai * HALF + m * 16) * DM + bj * HALF) * 2u; const u32x4 b = bs[ai][m];
;                     const f32x4 x0 = (f32x4){h16_lo(b.x), h16_hi(b.x), h16_lo(b.y), h16_hi(b.y)} + acc[ai][bj][m][0] * gv[0], x1 = (f32x4){h16_lo(b.z), h16_hi(b.z), h16_lo(b.w), h16_hi(b.w)} + acc[ai][bj][m][1] * gv[1];
;                     { u32x4 w; w.x = pk_h16(x0.x, x0.y); w.y = pk_h16(x0.z, x0.w); w.z = pk_h16(x1.x, x1.y); w.w = pk_h16(x1.z, x1.w); *(gu32x4*)(ot + o) = w; }
;                     ssq[ai][m] += (x0.x * x0.x + x0.y * x0.y) + (x0.z * x0.z + x0.w * x0.w) + (x1.x * x1.x + x1.y * x1.y) + (x1.z * x1.z + x1.w * x1.w);
;                     if (An) { const f32x4 y0 = x0 * gm[0], y1 = x1 * gm[1]; u32x4 w; w.x = cvt_pk_bf16(y0.x, y0.y); w.y = cvt_pk_bf16(y0.z, y0.w); w.z = cvt_pk_bf16(y1.x, y1.y); w.w = cvt_pk_bf16(y1.z, y1.w); *(gu32x4*)(at + o) = w; } }
.LBB0_1193:
	s_waitcnt vmcnt(0)
	v_pk_add_f32 v[140:141], v[140:141], 1.0 op_sel_hi:[1,0]
	v_add_u32_e32 v207, s53, v151
	v_pk_add_f32 v[142:143], v[142:143], 1.0 op_sel_hi:[1,0]
	v_pk_mul_f32 v[176:177], v[136:137], v[140:141]
	v_lshlrev_b32_e32 v136, 12, v207
	v_pk_mul_f32 v[174:175], v[138:139], v[142:143]
	v_lshl_add_u32 v208, v150, 1, v136
	global_load_dwordx4 v[136:139], v[146:147], off offset:16
	global_load_dwordx4 v[140:143], v[144:145], off offset:16
	s_ashr_i32 s5, s4, 31
	s_lshl_b64 s[14:15], s[4:5], 20
	s_add_u32 s5, s73, s14
	s_addc_u32 s11, s74, s15
	s_add_u32 s20, s75, s14
	s_addc_u32 s21, s76, s15
	s_lshl_b64 s[12:13], s[12:13], 1
	s_add_u32 s14, s5, s12
	s_addc_u32 s15, s11, s13
	global_load_dwordx4 v[184:187], v208, s[14:15]
	v_add_u32_e32 v198, 0x10000, v208
	global_load_dwordx4 v[192:195], v198, s[14:15]
	v_add_u32_e32 v218, 0x20000, v208
	global_load_dwordx4 v[156:159], v218, s[14:15]
	v_add_u32_e32 v217, 0x30000, v208
	global_load_dwordx4 v[152:155], v217, s[14:15]
	v_add_u32_e32 v216, 0x80000, v208
	global_load_dwordx4 v[148:151], v216, s[14:15]
	v_add_u32_e32 v215, 0x90000, v208
	global_load_dwordx4 v[144:147], v215, s[14:15]
	v_add_u32_e32 v214, 0xa0000, v208
	v_add_u32_e32 v209, 0xb0000, v208
	s_add_u32 s12, s20, s12
	s_addc_u32 s13, s21, s13
	s_and_b64 vcc, exec, s[36:37]
	s_waitcnt vmcnt(6)
	v_pk_add_f32 v[142:143], v[142:143], 1.0 op_sel_hi:[1,0]
	v_pk_add_f32 v[140:141], v[140:141], 1.0 op_sel_hi:[1,0]
	v_pk_mul_f32 v[178:179], v[138:139], v[142:143]
	v_pk_mul_f32 v[180:181], v[136:137], v[140:141]
	global_load_dwordx4 v[140:143], v214, s[14:15]
	global_load_dwordx4 v[136:139], v209, s[14:15]
	s_waitcnt vmcnt(7)
	v_cvt_f32_f16_e32 v188, v184
	v_cvt_f32_f16_sdwa v189, v184 dst_sel:DWORD dst_unused:UNUSED_PAD src0_sel:WORD_1
	v_cvt_f32_f16_e32 v182, v185
	v_cvt_f32_f16_sdwa v183, v185 dst_sel:DWORD dst_unused:UNUSED_PAD src0_sel:WORD_1
	v_pk_fma_f32 v[184:185], v[132:133], v[120:121], v[188:189]
	v_cvt_f32_f16_e32 v132, v186
	v_pk_fma_f32 v[182:183], v[134:135], v[122:123], v[182:183]
	v_cvt_f32_f16_sdwa v133, v186 dst_sel:DWORD dst_unused:UNUSED_PAD src0_sel:WORD_1
	v_cvt_f32_f16_e32 v134, v187
	v_cvt_f32_f16_sdwa v135, v187 dst_sel:DWORD dst_unused:UNUSED_PAD src0_sel:WORD_1
	v_pk_fma_f32 v[188:189], v[128:129], v[124:125], v[132:133]
	v_cvt_pk_f16_f32 v128, v184, v185
	v_pk_fma_f32 v[186:187], v[130:131], v[126:127], v[134:135]
	v_cvt_pk_f16_f32 v129, v182, v183
	v_cvt_pk_f16_f32 v130, v188, v189
	v_cvt_pk_f16_f32 v131, v186, v187
	global_store_dwordx4 v208, v[128:131], s[14:15] sc1
	v_pk_mul_f32 v[132:133], v[178:179], v[186:187]
	v_pk_mul_f32 v[134:135], v[180:181], v[188:189]
	v_pk_mul_f32 v[130:131], v[174:175], v[182:183]
	v_pk_mul_f32 v[128:129], v[176:177], v[184:185]
	s_nop 0
	v_cvt_pk_bf16_f32 v128, v128, v129
	v_cvt_pk_bf16_f32 v129, v130, v131
	v_cvt_pk_bf16_f32 v130, v134, v135
	v_cvt_pk_bf16_f32 v131, v132, v133
	global_store_dwordx4 v208, v[128:131], s[12:13] sc1
	s_waitcnt vmcnt(8)
	s_nop 0
	v_cvt_f32_f16_e32 v128, v192
	v_cvt_f32_f16_sdwa v129, v192 dst_sel:DWORD dst_unused:UNUSED_PAD src0_sel:WORD_1
	v_cvt_f32_f16_e32 v130, v193
	v_cvt_f32_f16_sdwa v131, v193 dst_sel:DWORD dst_unused:UNUSED_PAD src0_sel:WORD_1
	v_pk_fma_f32 v[192:193], v[116:117], v[120:121], v[128:129]
	v_cvt_f32_f16_e32 v116, v194
	v_pk_fma_f32 v[190:191], v[118:119], v[122:123], v[130:131]
	v_cvt_f32_f16_sdwa v117, v194 dst_sel:DWORD dst_unused:UNUSED_PAD src0_sel:WORD_1
	v_cvt_f32_f16_e32 v118, v195
	v_cvt_f32_f16_sdwa v119, v195 dst_sel:DWORD dst_unused:UNUSED_PAD src0_sel:WORD_1
	v_pk_fma_f32 v[196:197], v[112:113], v[124:125], v[116:117]
	v_cvt_pk_f16_f32 v112, v192, v193
	v_pk_fma_f32 v[194:195], v[114:115], v[126:127], v[118:119]
	v_cvt_pk_f16_f32 v113, v190, v191
	v_cvt_pk_f16_f32 v114, v196, v197
	v_cvt_pk_f16_f32 v115, v194, v195
	global_store_dwordx4 v198, v[112:115], s[14:15] sc1
	v_pk_mul_f32 v[116:117], v[178:179], v[194:195]
	v_pk_mul_f32 v[118:119], v[180:181], v[196:197]
	v_pk_mul_f32 v[114:115], v[174:175], v[190:191]
	v_pk_mul_f32 v[112:113], v[176:177], v[192:193]
	s_nop 0
	v_cvt_pk_bf16_f32 v112, v112, v113
	v_cvt_pk_bf16_f32 v113, v114, v115
	v_cvt_pk_bf16_f32 v114, v118, v119
	v_cvt_pk_bf16_f32 v115, v116, v117
	global_store_dwordx4 v198, v[112:115], s[12:13] sc1
	s_waitcnt vmcnt(9)
	s_nop 0
	v_cvt_f32_f16_e32 v112, v156
	v_cvt_f32_f16_sdwa v113, v156 dst_sel:DWORD dst_unused:UNUSED_PAD src0_sel:WORD_1
	v_cvt_f32_f16_e32 v114, v157
	v_cvt_f32_f16_sdwa v115, v157 dst_sel:DWORD dst_unused:UNUSED_PAD src0_sel:WORD_1
	v_pk_fma_f32 v[198:199], v[108:109], v[120:121], v[112:113]
	v_cvt_f32_f16_e32 v108, v158
	v_pk_fma_f32 v[156:157], v[110:111], v[122:123], v[114:115]
	v_cvt_f32_f16_sdwa v109, v158 dst_sel:DWORD dst_unused:UNUSED_PAD src0_sel:WORD_1
	v_cvt_f32_f16_e32 v110, v159
	v_cvt_f32_f16_sdwa v111, v159 dst_sel:DWORD dst_unused:UNUSED_PAD src0_sel:WORD_1
	v_pk_fma_f32 v[200:201], v[104:105], v[124:125], v[108:109]
	v_cvt_pk_f16_f32 v104, v198, v199
	v_pk_fma_f32 v[158:159], v[106:107], v[126:127], v[110:111]
	v_cvt_pk_f16_f32 v105, v156, v157
	v_cvt_pk_f16_f32 v106, v200, v201
	v_cvt_pk_f16_f32 v107, v158, v159
	global_store_dwordx4 v218, v[104:107], s[14:15] sc1
	v_pk_mul_f32 v[108:109], v[178:179], v[158:159]
	v_pk_mul_f32 v[110:111], v[180:181], v[200:201]
	v_pk_mul_f32 v[106:107], v[174:175], v[156:157]
	v_pk_mul_f32 v[104:105], v[176:177], v[198:199]
	s_nop 0
	v_cvt_pk_bf16_f32 v104, v104, v105
	v_cvt_pk_bf16_f32 v105, v106, v107
	v_cvt_pk_bf16_f32 v106, v110, v111
	v_cvt_pk_bf16_f32 v107, v108, v109
	global_store_dwordx4 v218, v[104:107], s[12:13] sc1
	s_waitcnt vmcnt(10)
; __device__ __forceinline__ float h16_lo(unsigned u) { return (float)__builtin_bit_cast(h16x2, u).x; }
; __device__ __forceinline__ float h16_hi(unsigned u) { return (float)__builtin_bit_cast(h16x2, u).y; }
; __device__ __forceinline__ unsigned cvt_pk_bf16(float lo, float hi) { unsigned r; asm volatile("v_cvt_pk_bf16_f32 %0, %1, %2" : "=v"(r) : "v"(lo), "v"(hi)); return r; }
;     __device__ __forceinline__ void operator()(const f32x4 (&acc)[2][2][4][2], const Unit& u, int wr, int wc, int fr, int fq, const PG8_LAS float*) const {
;     ...
;             for (int n = 0; n < 2; ++n) { const unsigned c = co + (unsigned)(bj * HALF + n * 4) * 4u;
;                 gv[n] = *(const gf32x4*)(gate + c); if (ls) gv[n] = gv[n] * *(const gf32x4*)(lsp + c);
;                 gm[n] = An ? *(const gf32x4*)(gnp + c) * (*(const gf32x4*)(scp + c) + 1.0f) : (f32x4){0.f, 0.f, 0.f, 0.f}; }
;     ...
;                 for (int m = 0; m < 4; ++m) { const unsigned o = lo + (unsigned)((ai * HALF + m * 16) * DM + bj * HALF) * 2u; const u32x4 b = bs[ai][m];
;                     const f32x4 x0 = (f32x4){h16_lo(b.x), h16_hi(b.x), h16_lo(b.y), h16_hi(b.y)} + acc[ai][bj][m][0] * gv[0], x1 = (f32x4){h16_lo(b.z), h16_hi(b.z), h16_lo(b.w), h16_hi(b.w)} + acc[ai][bj][m][1] * gv[1];
;                     { u32x4 w; w.x = pk_h16(x0.x, x0.y); w.y = pk_h16(x0.z, x0.w); w.z = pk_h16(x1.x, x1.y); w.w = pk_h16(x1.z, x1.w); *(gu32x4*)(ot + o) = w; }
;                     ssq[ai][m] += (x0.x * x0.x + x0.y * x0.y) + (x0.z * x0.z + x0.w * x0.w) + (x1.x * x1.x + x1.y * x1.y) + (x1.z * x1.z + x1.w * x1.w);
;                     if (An) { const f32x4 y0 = x0 * gm[0], y1 = x1 * gm[1]; u32x4 w; w.x = cvt_pk_bf16(y0.x, y0.y); w.y = cvt_pk_bf16(y0.z, y0.w); w.z = cvt_pk_bf16(y1.x, y1.y); w.w = cvt_pk_bf16(y1.z, y1.w); *(gu32x4*)(at + o) = w; } }
	s_nop 0
	v_cvt_f32_f16_e32 v104, v152
	v_cvt_f32_f16_sdwa v105, v152 dst_sel:DWORD dst_unused:UNUSED_PAD src0_sel:WORD_1
	v_cvt_f32_f16_e32 v106, v153
	v_cvt_f32_f16_sdwa v107, v153 dst_sel:DWORD dst_unused:UNUSED_PAD src0_sel:WORD_1
	v_pk_fma_f32 v[100:101], v[100:101], v[120:121], v[104:105]
	v_cvt_f32_f16_e32 v104, v154
	v_pk_fma_f32 v[102:103], v[102:103], v[122:123], v[106:107]
	v_cvt_f32_f16_sdwa v105, v154 dst_sel:DWORD dst_unused:UNUSED_PAD src0_sel:WORD_1
	v_cvt_f32_f16_e32 v106, v155
	v_cvt_f32_f16_sdwa v107, v155 dst_sel:DWORD dst_unused:UNUSED_PAD src0_sel:WORD_1
	v_pk_fma_f32 v[96:97], v[96:97], v[124:125], v[104:105]
	v_cvt_pk_f16_f32 v104, v100, v101
	v_pk_fma_f32 v[98:99], v[98:99], v[126:127], v[106:107]
	v_cvt_pk_f16_f32 v105, v102, v103
	v_cvt_pk_f16_f32 v106, v96, v97
	v_cvt_pk_f16_f32 v107, v98, v99
	global_store_dwordx4 v217, v[104:107], s[14:15] sc1
	v_pk_mul_f32 v[108:109], v[178:179], v[98:99]
	v_pk_mul_f32 v[110:111], v[180:181], v[96:97]
	v_pk_mul_f32 v[106:107], v[174:175], v[102:103]
	v_pk_mul_f32 v[104:105], v[176:177], v[100:101]
	s_nop 0
	v_cvt_pk_bf16_f32 v104, v104, v105
	v_cvt_pk_bf16_f32 v105, v106, v107
	v_cvt_pk_bf16_f32 v106, v110, v111
	v_cvt_pk_bf16_f32 v107, v108, v109
	global_store_dwordx4 v217, v[104:107], s[12:13] sc1
	s_waitcnt vmcnt(11)
	s_nop 0
	v_cvt_f32_f16_e32 v106, v148
	v_cvt_f32_f16_sdwa v107, v148 dst_sel:DWORD dst_unused:UNUSED_PAD src0_sel:WORD_1
	v_cvt_f32_f16_e32 v104, v149
	v_cvt_f32_f16_sdwa v105, v149 dst_sel:DWORD dst_unused:UNUSED_PAD src0_sel:WORD_1
	v_pk_fma_f32 v[106:107], v[92:93], v[120:121], v[106:107]
	v_cvt_f32_f16_e32 v92, v150
	v_pk_fma_f32 v[104:105], v[94:95], v[122:123], v[104:105]
	v_cvt_f32_f16_sdwa v93, v150 dst_sel:DWORD dst_unused:UNUSED_PAD src0_sel:WORD_1
	v_cvt_f32_f16_e32 v94, v151
	v_cvt_f32_f16_sdwa v95, v151 dst_sel:DWORD dst_unused:UNUSED_PAD src0_sel:WORD_1
	v_pk_fma_f32 v[110:111], v[88:89], v[124:125], v[92:93]
	v_cvt_pk_f16_f32 v88, v106, v107
	v_pk_fma_f32 v[108:109], v[90:91], v[126:127], v[94:95]
	v_cvt_pk_f16_f32 v89, v104, v105
	v_cvt_pk_f16_f32 v90, v110, v111
	v_cvt_pk_f16_f32 v91, v108, v109
	global_store_dwordx4 v216, v[88:91], s[14:15] sc1
	v_pk_mul_f32 v[92:93], v[178:179], v[108:109]
	v_pk_mul_f32 v[94:95], v[180:181], v[110:111]
	v_pk_mul_f32 v[90:91], v[174:175], v[104:105]
	v_pk_mul_f32 v[88:89], v[176:177], v[106:107]
	s_nop 0
	v_cvt_pk_bf16_f32 v88, v88, v89
	v_cvt_pk_bf16_f32 v89, v90, v91
	v_cvt_pk_bf16_f32 v90, v94, v95
	v_cvt_pk_bf16_f32 v91, v92, v93
	global_store_dwordx4 v216, v[88:91], s[12:13] sc1
	s_waitcnt vmcnt(12)
	s_nop 0
	v_cvt_f32_f16_e32 v88, v144
	v_cvt_f32_f16_sdwa v89, v144 dst_sel:DWORD dst_unused:UNUSED_PAD src0_sel:WORD_1
	v_cvt_f32_f16_e32 v90, v145
	v_cvt_f32_f16_sdwa v91, v145 dst_sel:DWORD dst_unused:UNUSED_PAD src0_sel:WORD_1
	v_pk_fma_f32 v[116:117], v[84:85], v[120:121], v[88:89]
	v_cvt_f32_f16_e32 v84, v146
	v_pk_fma_f32 v[114:115], v[86:87], v[122:123], v[90:91]
	v_cvt_f32_f16_sdwa v85, v146 dst_sel:DWORD dst_unused:UNUSED_PAD src0_sel:WORD_1
	v_cvt_f32_f16_e32 v86, v147
	v_cvt_f32_f16_sdwa v87, v147 dst_sel:DWORD dst_unused:UNUSED_PAD src0_sel:WORD_1
	v_pk_fma_f32 v[130:131], v[80:81], v[124:125], v[84:85]
	v_cvt_pk_f16_f32 v80, v116, v117
	v_pk_fma_f32 v[128:129], v[82:83], v[126:127], v[86:87]
	v_cvt_pk_f16_f32 v81, v114, v115
	v_cvt_pk_f16_f32 v82, v130, v131
	v_cvt_pk_f16_f32 v83, v128, v129
	global_store_dwordx4 v215, v[80:83], s[14:15] sc1
	v_pk_mul_f32 v[84:85], v[178:179], v[128:129]
	v_pk_mul_f32 v[86:87], v[180:181], v[130:131]
	v_pk_mul_f32 v[82:83], v[174:175], v[114:115]
	v_pk_mul_f32 v[80:81], v[176:177], v[116:117]
	s_nop 0
	v_cvt_pk_bf16_f32 v80, v80, v81
	v_cvt_pk_bf16_f32 v81, v82, v83
	v_cvt_pk_bf16_f32 v82, v86, v87
	v_cvt_pk_bf16_f32 v83, v84, v85
	global_store_dwordx4 v215, v[80:83], s[12:13] sc1
	s_waitcnt vmcnt(13)
	s_nop 0
	v_cvt_f32_f16_e32 v80, v140
	v_cvt_f32_f16_sdwa v81, v140 dst_sel:DWORD dst_unused:UNUSED_PAD src0_sel:WORD_1
	v_cvt_f32_f16_e32 v82, v141
	v_cvt_f32_f16_sdwa v83, v141 dst_sel:DWORD dst_unused:UNUSED_PAD src0_sel:WORD_1
	v_pk_fma_f32 v[134:135], v[76:77], v[120:121], v[80:81]
	v_cvt_f32_f16_e32 v76, v142
	v_pk_fma_f32 v[132:133], v[78:79], v[122:123], v[82:83]
	v_cvt_f32_f16_sdwa v77, v142 dst_sel:DWORD dst_unused:UNUSED_PAD src0_sel:WORD_1
	v_cvt_f32_f16_e32 v78, v143
	v_cvt_f32_f16_sdwa v79, v143 dst_sel:DWORD dst_unused:UNUSED_PAD src0_sel:WORD_1
	v_pk_fma_f32 v[140:141], v[72:73], v[124:125], v[76:77]
	v_cvt_pk_f16_f32 v72, v134, v135
	v_pk_fma_f32 v[112:113], v[74:75], v[126:127], v[78:79]
	v_cvt_pk_f16_f32 v73, v132, v133
	v_cvt_pk_f16_f32 v74, v140, v141
	v_cvt_pk_f16_f32 v75, v112, v113
	global_store_dwordx4 v214, v[72:75], s[14:15] sc1
	v_pk_mul_f32 v[76:77], v[178:179], v[112:113]
	v_pk_mul_f32 v[78:79], v[180:181], v[140:141]
	v_pk_mul_f32 v[74:75], v[174:175], v[132:133]
	v_pk_mul_f32 v[72:73], v[176:177], v[134:135]
	s_nop 0
	v_cvt_pk_bf16_f32 v72, v72, v73
	v_cvt_pk_bf16_f32 v73, v74, v75
	v_cvt_pk_bf16_f32 v74, v78, v79
	v_cvt_pk_bf16_f32 v75, v76, v77
	global_store_dwordx4 v214, v[72:75], s[12:13] sc1
	s_waitcnt vmcnt(14)
	s_nop 0
	v_cvt_f32_f16_e32 v72, v136
	v_cvt_f32_f16_sdwa v73, v136 dst_sel:DWORD dst_unused:UNUSED_PAD src0_sel:WORD_1
	v_cvt_f32_f16_e32 v74, v137
	v_cvt_f32_f16_sdwa v75, v137 dst_sel:DWORD dst_unused:UNUSED_PAD src0_sel:WORD_1
	v_pk_fma_f32 v[120:121], v[68:69], v[120:121], v[72:73]
	v_cvt_f32_f16_e32 v68, v138
	v_pk_fma_f32 v[118:119], v[70:71], v[122:123], v[74:75]
	v_cvt_f32_f16_sdwa v69, v138 dst_sel:DWORD dst_unused:UNUSED_PAD src0_sel:WORD_1
	v_cvt_f32_f16_e32 v70, v139
	v_cvt_f32_f16_sdwa v71, v139 dst_sel:DWORD dst_unused:UNUSED_PAD src0_sel:WORD_1
	v_pk_fma_f32 v[124:125], v[64:65], v[124:125], v[68:69]
	v_cvt_pk_f16_f32 v64, v120, v121
	v_pk_fma_f32 v[122:123], v[66:67], v[126:127], v[70:71]
	v_cvt_pk_f16_f32 v65, v118, v119
	v_cvt_pk_f16_f32 v66, v124, v125
	v_cvt_pk_f16_f32 v67, v122, v123
	global_store_dwordx4 v209, v[64:67], s[14:15] sc1
	v_pk_mul_f32 v[68:69], v[178:179], v[122:123]
	v_pk_mul_f32 v[70:71], v[180:181], v[124:125]
	v_pk_mul_f32 v[66:67], v[174:175], v[118:119]
	v_pk_mul_f32 v[64:65], v[176:177], v[120:121]
	s_nop 0
	v_cvt_pk_bf16_f32 v64, v64, v65
	v_cvt_pk_bf16_f32 v65, v66, v67
	v_cvt_pk_bf16_f32 v66, v70, v71
	v_cvt_pk_bf16_f32 v67, v68, v69
	global_store_dwordx4 v209, v[64:67], s[12:13] sc1
	v_add_u32_e32 v68, 0x200, v160
	global_load_dwordx4 v[64:67], v68, s[46:47]
	v_mov_b32_e32 v69, v161
	s_cbranch_vccnz .LBB0_1195
	v_lshl_add_u64 v[70:71], s[50:51], 0, v[68:69]
	global_load_dwordx4 v[70:73], v[70:71], off
	s_waitcnt vmcnt(0)
	v_pk_mul_f32 v[66:67], v[66:67], v[72:73]
	v_pk_mul_f32 v[64:65], v[64:65], v[70:71]

; __device__ __forceinline__ float h16_lo(unsigned u) { return (float)__builtin_bit_cast(h16x2, u).x; }
; __device__ __forceinline__ float h16_hi(unsigned u) { return (float)__builtin_bit_cast(h16x2, u).y; }
; __device__ __forceinline__ unsigned cvt_pk_bf16(float lo, float hi) { unsigned r; asm volatile("v_cvt_pk_bf16_f32 %0, %1, %2" : "=v"(r) : "v"(lo), "v"(hi)); return r; }
;     __device__ __forceinline__ void operator()(const f32x4 (&acc)[2][2][4][2], const Unit& u, int wr, int wc, int fr, int fq, const PG8_LAS float*) const {
;     ...
;             for (int n = 0; n < 2; ++n) { const unsigned c = co + (unsigned)(bj * HALF + n * 4) * 4u;
;                 gv[n] = *(const gf32x4*)(gate + c); if (ls) gv[n] = gv[n] * *(const gf32x4*)(lsp + c);
;                 gm[n] = An ? *(const gf32x4*)(gnp + c) * (*(const gf32x4*)(scp + c) + 1.0f) : (f32x4){0.f, 0.f, 0.f, 0.f}; }
;             u32x4 bs[2][4];
; #pragma unroll
;             for (int ai = 0; ai < 2; ++ai)
; #pragma unroll
;                 for (int m = 0; m < 4; ++m) { const unsigned o = lo + (unsigned)((ai * HALF + m * 16) * DM + bj * HALF) * 2u; bs[ai][m] = *(const gu32x4*)(bt + o); }
;             asm volatile("" ::: "memory");
; #pragma unroll
;             for (int ai = 0; ai < 2; ++ai)
; #pragma unroll
;                 for (int m = 0; m < 4; ++m) { const unsigned o = lo + (unsigned)((ai * HALF + m * 16) * DM + bj * HALF) * 2u; const u32x4 b = bs[ai][m];
;                     const f32x4 x0 = (f32x4){h16_lo(b.x), h16_hi(b.x), h16_lo(b.y), h16_hi(b.y)} + acc[ai][bj][m][0] * gv[0], x1 = (f32x4){h16_lo(b.z), h16_hi(b.z), h16_lo(b.w), h16_hi(b.w)} + acc[ai][bj][m][1] * gv[1];
;                     { u32x4 w; w.x = pk_h16(x0.x, x0.y); w.y = pk_h16(x0.z, x0.w); w.z = pk_h16(x1.x, x1.y); w.w = pk_h16(x1.z, x1.w); *(gu32x4*)(ot + o) = w; }
;                     ssq[ai][m] += (x0.x * x0.x + x0.y * x0.y) + (x0.z * x0.z + x0.w * x0.w) + (x1.x * x1.x + x1.y * x1.y) + (x1.z * x1.z + x1.w * x1.w);
;                     if (An) { const f32x4 y0 = x0 * gm[0], y1 = x1 * gm[1]; u32x4 w; w.x = cvt_pk_bf16(y0.x, y0.y); w.y = cvt_pk_bf16(y0.z, y0.w); w.z = cvt_pk_bf16(y1.x, y1.y); w.w = cvt_pk_bf16(y1.z, y1.w); *(gu32x4*)(at + o) = w; } }
.LBB0_1197:
	s_waitcnt vmcnt(1)
	v_pk_add_f32 v[76:77], v[76:77], 1.0 op_sel_hi:[1,0]
	v_pk_add_f32 v[78:79], v[78:79], 1.0 op_sel_hi:[1,0]
	v_pk_mul_f32 v[136:137], v[72:73], v[76:77]
	v_mul_f32_e32 v72, v185, v185
	v_mul_f32_e32 v73, v183, v183
	v_fmac_f32_e32 v72, v184, v184
	v_fmac_f32_e32 v73, v182, v182
	v_add_f32_e32 v72, v72, v73
	v_mul_f32_e32 v73, v189, v189
	v_fmac_f32_e32 v73, v188, v188
	v_add_f32_e32 v72, v73, v72
	v_mul_f32_e32 v73, v187, v187
	v_fmac_f32_e32 v73, v186, v186
	v_add_f32_e32 v150, v73, v72
	v_mul_f32_e32 v72, v193, v193
	v_mul_f32_e32 v73, v191, v191
	v_fmac_f32_e32 v72, v192, v192
	v_fmac_f32_e32 v73, v190, v190
	v_add_f32_e32 v72, v72, v73
	v_mul_f32_e32 v73, v197, v197
	v_fmac_f32_e32 v73, v196, v196
	v_add_f32_e32 v72, v73, v72
	v_mul_f32_e32 v73, v195, v195
	v_fmac_f32_e32 v73, v194, v194
	v_add_f32_e32 v148, v73, v72
	v_mul_f32_e32 v72, v199, v199
	v_mul_f32_e32 v73, v157, v157
	v_fmac_f32_e32 v72, v198, v198
	v_fmac_f32_e32 v73, v156, v156
	v_add_f32_e32 v72, v72, v73
	v_mul_f32_e32 v73, v201, v201
	v_fmac_f32_e32 v73, v200, v200
	v_add_f32_e32 v72, v73, v72
	v_mul_f32_e32 v73, v159, v159
	v_fmac_f32_e32 v73, v158, v158
	v_add_f32_e32 v146, v73, v72
	v_mul_f32_e32 v72, v101, v101
	v_mul_f32_e32 v73, v103, v103
	v_fmac_f32_e32 v72, v100, v100
	v_fmac_f32_e32 v73, v102, v102
	v_add_f32_e32 v72, v72, v73
	v_mul_f32_e32 v73, v97, v97
	v_fmac_f32_e32 v73, v96, v96
	v_add_f32_e32 v72, v73, v72
	v_mul_f32_e32 v73, v99, v99
	v_fmac_f32_e32 v73, v98, v98
	v_add_f32_e32 v144, v73, v72
	v_lshl_add_u64 v[72:73], s[44:45], 0, v[160:161]
	v_lshl_add_u64 v[76:77], s[42:43], 0, v[160:161]
	v_add_u32_e32 v153, 0x100, v208
	v_pk_mul_f32 v[126:127], v[74:75], v[78:79]
	global_load_dwordx4 v[72:75], v[72:73], off
	s_nop 0
	global_load_dwordx4 v[76:79], v[76:77], off
	v_add_u32_e32 v158, 0x10100, v208
	global_load_dwordx4 v[100:103], v153, s[14:15]
	global_load_dwordx4 v[96:99], v158, s[14:15]
	v_add_u32_e32 v159, 0x20100, v208
	global_load_dwordx4 v[92:95], v159, s[14:15]
	v_add_u32_e32 v152, 0x30100, v208
	global_load_dwordx4 v[88:91], v152, s[14:15]
	v_add_u32_e32 v151, 0x80100, v208
	global_load_dwordx4 v[84:87], v151, s[14:15]
	v_add_u32_e32 v149, 0x90100, v208
	global_load_dwordx4 v[80:83], v149, s[14:15]
	v_add_u32_e32 v147, 0xa0100, v208
	v_add_u32_e32 v145, 0xb0100, v208
	s_waitcnt vmcnt(6)
	v_pk_add_f32 v[78:79], v[78:79], 1.0 op_sel_hi:[1,0]
	v_pk_add_f32 v[76:77], v[76:77], 1.0 op_sel_hi:[1,0]
	s_waitcnt vmcnt(5)
	v_cvt_f32_f16_e32 v154, v100
	v_cvt_f32_f16_sdwa v155, v100 dst_sel:DWORD dst_unused:UNUSED_PAD src0_sel:WORD_1
	v_cvt_f32_f16_e32 v100, v101
	v_cvt_f32_f16_sdwa v101, v101 dst_sel:DWORD dst_unused:UNUSED_PAD src0_sel:WORD_1
	v_pk_mul_f32 v[138:139], v[74:75], v[78:79]
	v_pk_fma_f32 v[60:61], v[60:61], v[64:65], v[154:155]
	v_pk_mul_f32 v[142:143], v[72:73], v[76:77]
	v_pk_fma_f32 v[62:63], v[62:63], v[66:67], v[100:101]
	v_cvt_f32_f16_e32 v100, v102
	v_cvt_f32_f16_sdwa v101, v102 dst_sel:DWORD dst_unused:UNUSED_PAD src0_sel:WORD_1
	v_cvt_f32_f16_e32 v102, v103
	v_cvt_f32_f16_sdwa v103, v103 dst_sel:DWORD dst_unused:UNUSED_PAD src0_sel:WORD_1
	global_load_dwordx4 v[72:75], v147, s[14:15]
	global_load_dwordx4 v[76:79], v145, s[14:15]
	v_pk_fma_f32 v[100:101], v[56:57], v[68:69], v[100:101]
	v_pk_fma_f32 v[102:103], v[58:59], v[70:71], v[102:103]
	v_cvt_pk_f16_f32 v56, v60, v61
	v_cvt_pk_f16_f32 v57, v62, v63
	v_cvt_pk_f16_f32 v58, v100, v101
	v_cvt_pk_f16_f32 v59, v102, v103
	global_store_dwordx4 v153, v[56:59], s[14:15] sc1
	s_nop 1
	v_pk_mul_f32 v[56:57], v[62:63], v[62:63]
	v_pk_mul_f32 v[58:59], v[60:61], v[60:61]
	v_pk_mul_f32 v[62:63], v[126:127], v[62:63]
	v_pk_mov_b32 v[154:155], v[58:59], v[56:57] op_sel:[1,0]
	v_mov_b32_e32 v59, v57
	v_pk_add_f32 v[56:57], v[154:155], v[58:59]
	v_pk_mul_f32 v[58:59], v[102:103], v[102:103]
	v_pk_mul_f32 v[154:155], v[100:101], v[100:101]
	v_mov_b32_e32 v156, v58
	v_mov_b32_e32 v157, v154
	v_mov_b32_e32 v154, v59
	v_pk_add_f32 v[58:59], v[156:157], v[154:155]
	v_add_f32_e32 v56, v56, v57
	v_add_f32_e32 v56, v59, v56
	v_add_f32_e32 v56, v58, v56
	v_pk_mul_f32 v[58:59], v[136:137], v[60:61]
	v_pk_mul_f32 v[60:61], v[142:143], v[100:101]
	v_pk_mul_f32 v[102:103], v[138:139], v[102:103]
	v_cvt_pk_bf16_f32 v58, v58, v59
	v_cvt_pk_bf16_f32 v59, v62, v63
	v_cvt_pk_bf16_f32 v60, v60, v61
	v_add_f32_e32 v56, v150, v56
	v_cvt_pk_bf16_f32 v61, v102, v103
	global_store_dwordx4 v153, v[58:61], s[12:13] sc1
	s_waitcnt vmcnt(8)
	s_nop 0
	v_cvt_f32_f16_e32 v58, v96
	v_cvt_f32_f16_sdwa v59, v96 dst_sel:DWORD dst_unused:UNUSED_PAD src0_sel:WORD_1
	v_cvt_f32_f16_e32 v60, v97
	v_cvt_f32_f16_sdwa v61, v97 dst_sel:DWORD dst_unused:UNUSED_PAD src0_sel:WORD_1
	v_pk_fma_f32 v[52:53], v[52:53], v[64:65], v[58:59]
	v_cvt_f32_f16_e32 v58, v98
	v_pk_fma_f32 v[54:55], v[54:55], v[66:67], v[60:61]
	v_cvt_f32_f16_sdwa v59, v98 dst_sel:DWORD dst_unused:UNUSED_PAD src0_sel:WORD_1
	v_cvt_f32_f16_e32 v60, v99
	v_cvt_f32_f16_sdwa v61, v99 dst_sel:DWORD dst_unused:UNUSED_PAD src0_sel:WORD_1
	v_pk_fma_f32 v[58:59], v[48:49], v[68:69], v[58:59]
	v_cvt_pk_f16_f32 v48, v52, v53
	v_pk_fma_f32 v[60:61], v[50:51], v[70:71], v[60:61]
	v_cvt_pk_f16_f32 v49, v54, v55
	v_cvt_pk_f16_f32 v50, v58, v59
	v_cvt_pk_f16_f32 v51, v60, v61
	global_store_dwordx4 v158, v[48:51], s[14:15] sc1
	s_nop 1
	v_mul_f32_e32 v48, v53, v53
	v_mul_f32_e32 v49, v55, v55
	v_fmac_f32_e32 v48, v52, v52
	v_fmac_f32_e32 v49, v54, v54
	v_add_f32_e32 v48, v48, v49
	v_mul_f32_e32 v49, v59, v59
	v_fmac_f32_e32 v49, v58, v58
	v_add_f32_e32 v48, v49, v48
	v_mul_f32_e32 v49, v61, v61
	v_pk_mul_f32 v[50:51], v[136:137], v[52:53]
	v_pk_mul_f32 v[52:53], v[142:143], v[58:59]
	v_fmac_f32_e32 v49, v60, v60
	v_pk_mul_f32 v[54:55], v[126:127], v[54:55]
	v_pk_mul_f32 v[60:61], v[138:139], v[60:61]
	v_cvt_pk_bf16_f32 v50, v50, v51
	v_cvt_pk_bf16_f32 v51, v54, v55
	v_cvt_pk_bf16_f32 v52, v52, v53
	v_add_f32_e32 v48, v49, v48
	v_cvt_pk_bf16_f32 v53, v60, v61
	global_store_dwordx4 v158, v[50:53], s[12:13] sc1
	v_add_f32_e32 v48, v148, v48
	s_waitcnt vmcnt(9)
; __device__ __forceinline__ float h16_lo(unsigned u) { return (float)__builtin_bit_cast(h16x2, u).x; }
; __device__ __forceinline__ float h16_hi(unsigned u) { return (float)__builtin_bit_cast(h16x2, u).y; }
; __device__ __forceinline__ unsigned cvt_pk_bf16(float lo, float hi) { unsigned r; asm volatile("v_cvt_pk_bf16_f32 %0, %1, %2" : "=v"(r) : "v"(lo), "v"(hi)); return r; }
;     __device__ __forceinline__ void operator()(const f32x4 (&acc)[2][2][4][2], const Unit& u, int wr, int wc, int fr, int fq, const PG8_LAS float*) const {
;     ...
;                 for (int m = 0; m < 4; ++m) { const unsigned o = lo + (unsigned)((ai * HALF + m * 16) * DM + bj * HALF) * 2u; const u32x4 b = bs[ai][m];
;                     const f32x4 x0 = (f32x4){h16_lo(b.x), h16_hi(b.x), h16_lo(b.y), h16_hi(b.y)} + acc[ai][bj][m][0] * gv[0], x1 = (f32x4){h16_lo(b.z), h16_hi(b.z), h16_lo(b.w), h16_hi(b.w)} + acc[ai][bj][m][1] * gv[1];
;                     { u32x4 w; w.x = pk_h16(x0.x, x0.y); w.y = pk_h16(x0.z, x0.w); w.z = pk_h16(x1.x, x1.y); w.w = pk_h16(x1.z, x1.w); *(gu32x4*)(ot + o) = w; }
;                     ssq[ai][m] += (x0.x * x0.x + x0.y * x0.y) + (x0.z * x0.z + x0.w * x0.w) + (x1.x * x1.x + x1.y * x1.y) + (x1.z * x1.z + x1.w * x1.w);
;                     if (An) { const f32x4 y0 = x0 * gm[0], y1 = x1 * gm[1]; u32x4 w; w.x = cvt_pk_bf16(y0.x, y0.y); w.y = cvt_pk_bf16(y0.z, y0.w); w.z = cvt_pk_bf16(y1.x, y1.y); w.w = cvt_pk_bf16(y1.z, y1.w); *(gu32x4*)(at + o) = w; } }
	v_cvt_f32_f16_e32 v50, v92
	v_cvt_f32_f16_sdwa v51, v92 dst_sel:DWORD dst_unused:UNUSED_PAD src0_sel:WORD_1
	v_cvt_f32_f16_e32 v52, v93
	v_cvt_f32_f16_sdwa v53, v93 dst_sel:DWORD dst_unused:UNUSED_PAD src0_sel:WORD_1
	v_pk_fma_f32 v[44:45], v[44:45], v[64:65], v[50:51]
	v_cvt_f32_f16_e32 v50, v94
	v_pk_fma_f32 v[46:47], v[46:47], v[66:67], v[52:53]
	v_cvt_f32_f16_sdwa v51, v94 dst_sel:DWORD dst_unused:UNUSED_PAD src0_sel:WORD_1
	v_cvt_f32_f16_e32 v52, v95
	v_cvt_f32_f16_sdwa v53, v95 dst_sel:DWORD dst_unused:UNUSED_PAD src0_sel:WORD_1
	v_pk_fma_f32 v[50:51], v[40:41], v[68:69], v[50:51]
	v_cvt_pk_f16_f32 v40, v44, v45
	v_pk_fma_f32 v[52:53], v[42:43], v[70:71], v[52:53]
	v_cvt_pk_f16_f32 v41, v46, v47
	v_cvt_pk_f16_f32 v42, v50, v51
	v_cvt_pk_f16_f32 v43, v52, v53
	global_store_dwordx4 v159, v[40:43], s[14:15] sc1
	s_nop 1
	v_mul_f32_e32 v40, v45, v45
	v_mul_f32_e32 v41, v47, v47
	v_fmac_f32_e32 v40, v44, v44
	v_fmac_f32_e32 v41, v46, v46
	v_add_f32_e32 v40, v40, v41
	v_mul_f32_e32 v41, v51, v51
	v_fmac_f32_e32 v41, v50, v50
	v_add_f32_e32 v40, v41, v40
	v_mul_f32_e32 v41, v53, v53
	v_fmac_f32_e32 v41, v52, v52
	v_add_f32_e32 v40, v41, v40
	v_add_f32_e32 v49, v146, v40
	v_pk_mul_f32 v[42:43], v[126:127], v[46:47]
	v_pk_mul_f32 v[40:41], v[136:137], v[44:45]
	v_pk_mul_f32 v[44:45], v[138:139], v[52:53]
	v_pk_mul_f32 v[46:47], v[142:143], v[50:51]
	v_cvt_pk_bf16_f32 v40, v40, v41
	v_cvt_pk_bf16_f32 v41, v42, v43
	s_nop 0
	v_cvt_pk_bf16_f32 v42, v46, v47
	v_cvt_pk_bf16_f32 v43, v44, v45
	global_store_dwordx4 v159, v[40:43], s[12:13] sc1
	s_waitcnt vmcnt(10)
	s_nop 0
	v_cvt_f32_f16_e32 v40, v88
	v_cvt_f32_f16_sdwa v41, v88 dst_sel:DWORD dst_unused:UNUSED_PAD src0_sel:WORD_1
	v_cvt_f32_f16_e32 v42, v89
	v_cvt_f32_f16_sdwa v43, v89 dst_sel:DWORD dst_unused:UNUSED_PAD src0_sel:WORD_1
	v_pk_fma_f32 v[36:37], v[36:37], v[64:65], v[40:41]
	v_cvt_f32_f16_e32 v40, v90
	v_pk_fma_f32 v[38:39], v[38:39], v[66:67], v[42:43]
	v_cvt_f32_f16_sdwa v41, v90 dst_sel:DWORD dst_unused:UNUSED_PAD src0_sel:WORD_1
	v_cvt_f32_f16_e32 v42, v91
	v_cvt_f32_f16_sdwa v43, v91 dst_sel:DWORD dst_unused:UNUSED_PAD src0_sel:WORD_1
	v_pk_fma_f32 v[40:41], v[32:33], v[68:69], v[40:41]
	v_cvt_pk_f16_f32 v32, v36, v37
	v_pk_fma_f32 v[42:43], v[34:35], v[70:71], v[42:43]
	v_cvt_pk_f16_f32 v33, v38, v39
	v_cvt_pk_f16_f32 v34, v40, v41
	v_cvt_pk_f16_f32 v35, v42, v43
	global_store_dwordx4 v152, v[32:35], s[14:15] sc1
	s_nop 1
	v_mul_f32_e32 v32, v37, v37
	v_mul_f32_e32 v33, v39, v39
	v_fmac_f32_e32 v32, v36, v36
	v_fmac_f32_e32 v33, v38, v38
	v_add_f32_e32 v32, v32, v33
	v_mul_f32_e32 v33, v41, v41
	v_fmac_f32_e32 v33, v40, v40
	v_add_f32_e32 v32, v33, v32
	v_mul_f32_e32 v33, v43, v43
	v_fmac_f32_e32 v33, v42, v42
	v_add_f32_e32 v32, v33, v32
	v_add_f32_e32 v44, v144, v32
	v_pk_mul_f32 v[34:35], v[126:127], v[38:39]
	v_pk_mul_f32 v[32:33], v[136:137], v[36:37]
	v_pk_mul_f32 v[36:37], v[138:139], v[42:43]
	v_pk_mul_f32 v[38:39], v[142:143], v[40:41]
	v_cvt_pk_bf16_f32 v32, v32, v33
	v_cvt_pk_bf16_f32 v33, v34, v35
	s_nop 0
	v_cvt_pk_bf16_f32 v34, v38, v39
	v_cvt_pk_bf16_f32 v35, v36, v37
	global_store_dwordx4 v152, v[32:35], s[12:13] sc1
	s_waitcnt vmcnt(11)
	s_nop 0
	v_cvt_f32_f16_e32 v32, v84
	v_cvt_f32_f16_sdwa v33, v84 dst_sel:DWORD dst_unused:UNUSED_PAD src0_sel:WORD_1
	v_cvt_f32_f16_e32 v34, v85
	v_cvt_f32_f16_sdwa v35, v85 dst_sel:DWORD dst_unused:UNUSED_PAD src0_sel:WORD_1
	v_pk_fma_f32 v[28:29], v[28:29], v[64:65], v[32:33]
	v_cvt_f32_f16_e32 v32, v86
	v_pk_fma_f32 v[30:31], v[30:31], v[66:67], v[34:35]
	v_cvt_f32_f16_sdwa v33, v86 dst_sel:DWORD dst_unused:UNUSED_PAD src0_sel:WORD_1
	v_cvt_f32_f16_e32 v34, v87
	v_cvt_f32_f16_sdwa v35, v87 dst_sel:DWORD dst_unused:UNUSED_PAD src0_sel:WORD_1
	v_pk_fma_f32 v[24:25], v[24:25], v[68:69], v[32:33]
	v_cvt_pk_f16_f32 v32, v28, v29
	v_pk_fma_f32 v[26:27], v[26:27], v[70:71], v[34:35]
	v_cvt_pk_f16_f32 v33, v30, v31
	v_cvt_pk_f16_f32 v34, v24, v25
	v_cvt_pk_f16_f32 v35, v26, v27
	global_store_dwordx4 v151, v[32:35], s[14:15] sc1
	v_pk_mul_f32 v[36:37], v[138:139], v[26:27]
	v_pk_mul_f32 v[38:39], v[142:143], v[24:25]
	v_pk_mul_f32 v[34:35], v[126:127], v[30:31]
	v_pk_mul_f32 v[32:33], v[136:137], v[28:29]
	s_nop 0
	v_cvt_pk_bf16_f32 v32, v32, v33
	v_cvt_pk_bf16_f32 v33, v34, v35
	v_cvt_pk_bf16_f32 v34, v38, v39
	v_cvt_pk_bf16_f32 v35, v36, v37
	global_store_dwordx4 v151, v[32:35], s[12:13] sc1
	s_waitcnt vmcnt(12)
; #define GAS __attribute__((address_space(1)))
; __device__ __forceinline__ float h16_lo(unsigned u) { return (float)__builtin_bit_cast(h16x2, u).x; }
; __device__ __forceinline__ float h16_hi(unsigned u) { return (float)__builtin_bit_cast(h16x2, u).y; }
; __device__ __forceinline__ unsigned cvt_pk_bf16(float lo, float hi) { unsigned r; asm volatile("v_cvt_pk_bf16_f32 %0, %1, %2" : "=v"(r) : "v"(lo), "v"(hi)); return r; }
; __device__ __forceinline__ void atomic_add_f32(gf32* p, float v) { (void)__builtin_amdgcn_global_atomic_fadd_f32(p, v); }
;     __device__ __forceinline__ void operator()(const f32x4 (&acc)[2][2][4][2], const Unit& u, int wr, int wc, int fr, int fq, const PG8_LAS float*) const {
;     ...
;                 for (int m = 0; m < 4; ++m) { const unsigned o = lo + (unsigned)((ai * HALF + m * 16) * DM + bj * HALF) * 2u; const u32x4 b = bs[ai][m];
;                     const f32x4 x0 = (f32x4){h16_lo(b.x), h16_hi(b.x), h16_lo(b.y), h16_hi(b.y)} + acc[ai][bj][m][0] * gv[0], x1 = (f32x4){h16_lo(b.z), h16_hi(b.z), h16_lo(b.w), h16_hi(b.w)} + acc[ai][bj][m][1] * gv[1];
;                     { u32x4 w; w.x = pk_h16(x0.x, x0.y); w.y = pk_h16(x0.z, x0.w); w.z = pk_h16(x1.x, x1.y); w.w = pk_h16(x1.z, x1.w); *(gu32x4*)(ot + o) = w; }
;                     ssq[ai][m] += (x0.x * x0.x + x0.y * x0.y) + (x0.z * x0.z + x0.w * x0.w) + (x1.x * x1.x + x1.y * x1.y) + (x1.z * x1.z + x1.w * x1.w);
;                     if (An) { const f32x4 y0 = x0 * gm[0], y1 = x1 * gm[1]; u32x4 w; w.x = cvt_pk_bf16(y0.x, y0.y); w.y = cvt_pk_bf16(y0.z, y0.w); w.z = cvt_pk_bf16(y1.x, y1.y); w.w = cvt_pk_bf16(y1.z, y1.w); *(gu32x4*)(at + o) = w; } }
;             asm volatile("" ::: "memory");
;         }
;         if (stats) {
; #pragma unroll
;             for (int ai = 0; ai < 2; ++ai) {
; #pragma unroll
;                 for (int m = 0; m < 4; ++m) { ssq[ai][m] += __shfl_xor(ssq[ai][m], 16); ssq[ai][m] += __shfl_xor(ssq[ai][m], 32); }
;                 const float v = fq == 0 ? ssq[ai][0] : fq == 1 ? ssq[ai][1] : fq == 2 ? ssq[ai][2] : ssq[ai][3];
;                 atomic_add_f32((gf32*)((GAS char*)(stats + u.pm * BM + ai * HALF) + so), v); }
	s_nop 0
	v_cvt_f32_f16_e32 v32, v80
	v_cvt_f32_f16_sdwa v33, v80 dst_sel:DWORD dst_unused:UNUSED_PAD src0_sel:WORD_1
	v_cvt_f32_f16_e32 v34, v81
	v_cvt_f32_f16_sdwa v35, v81 dst_sel:DWORD dst_unused:UNUSED_PAD src0_sel:WORD_1
	v_pk_fma_f32 v[20:21], v[20:21], v[64:65], v[32:33]
	v_cvt_f32_f16_e32 v32, v82
	v_pk_fma_f32 v[22:23], v[22:23], v[66:67], v[34:35]
	v_cvt_f32_f16_sdwa v33, v82 dst_sel:DWORD dst_unused:UNUSED_PAD src0_sel:WORD_1
	v_cvt_f32_f16_e32 v34, v83
	v_cvt_f32_f16_sdwa v35, v83 dst_sel:DWORD dst_unused:UNUSED_PAD src0_sel:WORD_1
	v_pk_fma_f32 v[16:17], v[16:17], v[68:69], v[32:33]
	v_cvt_pk_f16_f32 v32, v20, v21
	v_pk_fma_f32 v[18:19], v[18:19], v[70:71], v[34:35]
	v_cvt_pk_f16_f32 v33, v22, v23
	v_cvt_pk_f16_f32 v34, v16, v17
	v_cvt_pk_f16_f32 v35, v18, v19
	global_store_dwordx4 v149, v[32:35], s[14:15] sc1
	v_pk_mul_f32 v[36:37], v[138:139], v[18:19]
	v_pk_mul_f32 v[38:39], v[142:143], v[16:17]
	v_pk_mul_f32 v[34:35], v[126:127], v[22:23]
	v_pk_mul_f32 v[32:33], v[136:137], v[20:21]
	s_nop 0
	v_cvt_pk_bf16_f32 v32, v32, v33
	v_cvt_pk_bf16_f32 v33, v34, v35
	v_cvt_pk_bf16_f32 v34, v38, v39
	v_cvt_pk_bf16_f32 v35, v36, v37
	global_store_dwordx4 v149, v[32:35], s[12:13] sc1
	s_waitcnt vmcnt(13)
	s_nop 0
	v_cvt_f32_f16_e32 v32, v72
	v_cvt_f32_f16_sdwa v33, v72 dst_sel:DWORD dst_unused:UNUSED_PAD src0_sel:WORD_1
	v_cvt_f32_f16_e32 v34, v73
	v_cvt_f32_f16_sdwa v35, v73 dst_sel:DWORD dst_unused:UNUSED_PAD src0_sel:WORD_1
	v_pk_fma_f32 v[12:13], v[12:13], v[64:65], v[32:33]
	v_cvt_f32_f16_e32 v32, v74
	v_pk_fma_f32 v[14:15], v[14:15], v[66:67], v[34:35]
	v_cvt_f32_f16_sdwa v33, v74 dst_sel:DWORD dst_unused:UNUSED_PAD src0_sel:WORD_1
	v_cvt_f32_f16_e32 v34, v75
	v_cvt_f32_f16_sdwa v35, v75 dst_sel:DWORD dst_unused:UNUSED_PAD src0_sel:WORD_1
	v_pk_fma_f32 v[8:9], v[8:9], v[68:69], v[32:33]
	v_cvt_pk_f16_f32 v32, v12, v13
	v_pk_fma_f32 v[10:11], v[10:11], v[70:71], v[34:35]
	v_cvt_pk_f16_f32 v33, v14, v15
	v_cvt_pk_f16_f32 v34, v8, v9
	v_cvt_pk_f16_f32 v35, v10, v11
	global_store_dwordx4 v147, v[32:35], s[14:15] sc1
	v_pk_mul_f32 v[36:37], v[138:139], v[10:11]
	v_pk_mul_f32 v[38:39], v[142:143], v[8:9]
	v_pk_mul_f32 v[34:35], v[126:127], v[14:15]
	v_pk_mul_f32 v[32:33], v[136:137], v[12:13]
	s_nop 0
	v_cvt_pk_bf16_f32 v32, v32, v33
	v_cvt_pk_bf16_f32 v33, v34, v35
	v_cvt_pk_bf16_f32 v34, v38, v39
	v_cvt_pk_bf16_f32 v35, v36, v37
	global_store_dwordx4 v147, v[32:35], s[12:13] sc1
	s_waitcnt vmcnt(14)
	s_nop 0
	v_cvt_f32_f16_e32 v32, v76
	v_cvt_f32_f16_sdwa v33, v76 dst_sel:DWORD dst_unused:UNUSED_PAD src0_sel:WORD_1
	v_cvt_f32_f16_e32 v34, v77
	v_cvt_f32_f16_sdwa v35, v77 dst_sel:DWORD dst_unused:UNUSED_PAD src0_sel:WORD_1
	v_pk_fma_f32 v[4:5], v[4:5], v[64:65], v[32:33]
	v_cvt_f32_f16_e32 v32, v78
	v_pk_fma_f32 v[6:7], v[6:7], v[66:67], v[34:35]
	v_cvt_f32_f16_sdwa v33, v78 dst_sel:DWORD dst_unused:UNUSED_PAD src0_sel:WORD_1
	v_cvt_f32_f16_e32 v34, v79
	v_cvt_f32_f16_sdwa v35, v79 dst_sel:DWORD dst_unused:UNUSED_PAD src0_sel:WORD_1
	v_pk_fma_f32 v[0:1], v[0:1], v[68:69], v[32:33]
	v_cvt_pk_f16_f32 v32, v4, v5
	v_pk_fma_f32 v[2:3], v[2:3], v[70:71], v[34:35]
	v_cvt_pk_f16_f32 v33, v6, v7
	v_cvt_pk_f16_f32 v34, v0, v1
	v_cvt_pk_f16_f32 v35, v2, v3
	global_store_dwordx4 v145, v[32:35], s[14:15] sc1
	v_pk_mul_f32 v[36:37], v[138:139], v[2:3]
	v_pk_mul_f32 v[38:39], v[142:143], v[0:1]
	v_pk_mul_f32 v[32:33], v[136:137], v[4:5]
	v_pk_mul_f32 v[34:35], v[126:127], v[6:7]
	v_cvt_pk_bf16_f32 v32, v32, v33
	s_mov_b64 s[14:15], 0
	v_cvt_pk_bf16_f32 v33, v34, v35
	v_cvt_pk_bf16_f32 v34, v38, v39
	v_cvt_pk_bf16_f32 v35, v36, v37
	global_store_dwordx4 v145, v[32:35], s[12:13] sc1
	s_nop 1
	v_and_b32_e32 v33, 64, v238
	v_xor_b32_e32 v32, 16, v238
	v_add_u32_e32 v34, 64, v33
	v_cmp_lt_i32_e32 vcc, v32, v34
	s_nop 1
	v_cndmask_b32_e32 v32, v238, v32, vcc
	v_lshlrev_b32_e32 v33, 2, v32
	v_xor_b32_e32 v32, 32, v238
	v_cmp_lt_i32_e32 vcc, v32, v34
	ds_bpermute_b32 v34, v33, v56
	ds_bpermute_b32 v36, v33, v44
	v_cndmask_b32_e32 v32, v238, v32, vcc
	v_lshlrev_b32_e32 v32, 2, v32
	v_cmp_lt_i32_e32 vcc, 0, v206
	s_waitcnt lgkmcnt(1)
	v_add_f32_e32 v38, v56, v34
	ds_bpermute_b32 v34, v33, v48
	s_waitcnt lgkmcnt(1)
	v_add_f32_e32 v36, v44, v36
	ds_bpermute_b32 v39, v32, v38
	ds_bpermute_b32 v37, v32, v36
	s_waitcnt lgkmcnt(2)
	v_add_f32_e32 v40, v48, v34
	ds_bpermute_b32 v34, v33, v49
	ds_bpermute_b32 v41, v32, v40
	s_waitcnt lgkmcnt(1)
	v_add_f32_e32 v34, v49, v34
	ds_bpermute_b32 v35, v32, v34
	s_and_saveexec_b64 s[12:13], vcc
	s_xor_b64 s[12:13], exec, s[12:13]
	s_cbranch_execz .LBB0_1215
	v_cmp_lt_i32_e32 vcc, 1, v206
	s_and_saveexec_b64 s[20:21], vcc
	s_xor_b64 s[28:29], exec, s[20:21]
	s_cbranch_execz .LBB0_1202
	v_cmp_eq_u32_e32 vcc, 2, v206
	s_mov_b64 s[14:15], -1
	s_and_saveexec_b64 s[36:37], vcc
	s_xor_b64 s[14:15], exec, -1
	s_or_b64 exec, exec, s[36:37]
	s_and_b64 s[14:15], s[14:15], exec

; #define GAS __attribute__((address_space(1)))
;     __device__ __forceinline__ void operator()(const f32x4 (&acc)[2][2][4][2], const Unit& u, int wr, int wc, int fr, int fq, const PG8_LAS float*) const {
;         const int vec = (u.pm % PTILES == 0) ? 2 : (u.pm / PTILES);
;         const GAS char* gate = (const GAS char*)(ada_l + (size_t)(vec * 6 + chunk) * DM + u.pn * BM);
;         const GAS char* lsp = (const GAS char*)(ls + u.pn * BM);
;         const GAS char* gnp = (const GAS char*)(gnext + u.pn * BM);
;         const GAS char* scp = (const GAS char*)(ada_n + (size_t)(vec * 6 + sc_chunk) * DM + u.pn * BM);
;         const GAS char* bt = (const GAS char*)(base + (size_t)u.pm * BM * DM + u.pn * BM);
;         GAS char* ot = (GAS char*)(out + (size_t)u.pm * BM * DM + u.pn * BM);
;         GAS char* at = (GAS char*)(An + (size_t)u.pm * BM * DM + u.pn * BM);
;         asm volatile("" : "+v"(fr), "+v"(fq));
;         const unsigned lo = (unsigned)((wr * 64 + fr) * DM + wc * 32 + 8 * fq) * 2u, co = (unsigned)(wc * 32 + 8 * fq) * 4u;
;         const unsigned so = (unsigned)(wr * 64 + fq * 16 + fr) * 4u;
;         float ssq[2][4];
; #pragma unroll
;         for (int ai = 0; ai < 2; ++ai)
; #pragma unroll
;             for (int m = 0; m < 4; ++m) ssq[ai][m] = 0.f;
; #pragma unroll
;         for (int bj = 0; bj < 2; ++bj) {
;             f32x4 gv[2], gm[2];
; #pragma unroll
;             for (int n = 0; n < 2; ++n) { const unsigned c = co + (unsigned)(bj * HALF + n * 4) * 4u;
;                 gv[n] = *(const gf32x4*)(gate + c); if (ls) gv[n] = gv[n] * *(const gf32x4*)(lsp + c);
;                 gm[n] = An ? *(const gf32x4*)(gnp + c) * (*(const gf32x4*)(scp + c) + 1.0f) : (f32x4){0.f, 0.f, 0.f, 0.f}; }
;             u32x4 bs[2][4];
; #pragma unroll
;             for (int ai = 0; ai < 2; ++ai)
; #pragma unroll
;                 for (int m = 0; m < 4; ++m) { const unsigned o = lo + (unsigned)((ai * HALF + m * 16) * DM + bj * HALF) * 2u; bs[ai][m] = *(const gu32x4*)(bt + o); }
;             asm volatile("" ::: "memory");
; #pragma unroll
;             for (int ai = 0; ai < 2; ++ai)
; #pragma unroll
;                 for (int m = 0; m < 4; ++m) { const unsigned o = lo + (unsigned)((ai * HALF + m * 16) * DM + bj * HALF) * 2u; const u32x4 b = bs[ai][m];
.LBB0_1317:
	s_mul_hi_i32 s1, s4, 0x78787879
	s_lshr_b32 s5, s1, 31
	s_ashr_i32 s1, s1, 3
	s_add_i32 s1, s1, s5
	s_mul_i32 s5, s1, 17
	s_sub_i32 s5, s4, s5
	s_mul_i32 s1, s1, 6
	s_cmp_lg_u32 s5, 0
	s_cselect_b32 s14, s1, 12
	s_lshl_b32 s20, s12, 8
	s_ashr_i32 s15, s14, 31
	s_ashr_i32 s21, s20, 31
	s_lshl_b64 s[12:13], s[14:15], 13
	v_readlane_b32 s1, v254, 46
	s_add_u32 s1, s1, s12
	v_readlane_b32 s5, v254, 47
	s_addc_u32 s11, s5, s13
	s_ashr_i32 s5, s4, 31
	s_lshl_b64 s[12:13], s[4:5], 20
	s_add_u32 s5, s68, s12
	s_addc_u32 s22, s69, s13
	s_add_u32 s23, s72, s12
	s_addc_u32 s24, s73, s13
	s_lshl_b64 s[52:53], s[20:21], 2
	s_add_u32 s1, s1, s52
	s_addc_u32 s11, s11, s53
	s_add_u32 s58, s1, 0x4000
	s_addc_u32 s59, s11, 0
	v_mov_b32_e32 v128, v232
	v_mov_b32_e32 v188, v231
	s_add_u32 s12, s48, s52
	s_addc_u32 s13, s74, s53
	v_lshl_add_u32 v129, v188, 3, s75
	v_add_u32_e32 v160, s63, v128
	s_add_u32 s56, s1, 0x8000
	v_lshlrev_b32_e32 v128, 12, v160
	v_lshlrev_b32_e32 v190, 2, v129
	s_addc_u32 s57, s11, 0
	v_lshl_add_u32 v189, v129, 1, v128
	global_load_dwordx4 v[128:131], v190, s[58:59] offset:16
	global_load_dwordx4 v[136:139], v190, s[58:59]
	global_load_dwordx4 v[144:147], v190, s[12:13] offset:16
	global_load_dwordx4 v[148:151], v190, s[12:13]
	global_load_dwordx4 v[152:155], v190, s[56:57] offset:16
	global_load_dwordx4 v[156:159], v190, s[56:57]
	s_lshl_b64 s[14:15], s[20:21], 1
	s_add_u32 s54, s5, s14
	s_addc_u32 s55, s22, s15
	global_load_dwordx4 v[174:177], v189, s[54:55]
	v_add_u32_e32 v197, 0x10000, v189
	global_load_dwordx4 v[170:173], v197, s[54:55]
	v_add_u32_e32 v196, 0x20000, v189
	global_load_dwordx4 v[166:169], v196, s[54:55]
	v_add_u32_e32 v195, 0x30000, v189
	global_load_dwordx4 v[162:165], v195, s[54:55]
	v_add_u32_e32 v194, 0x80000, v189
	v_add_u32_e32 v193, 0x90000, v189
	v_add_u32_e32 v191, 0xb0000, v189
	v_add_u32_e32 v192, 0xa0000, v189
	s_add_u32 s38, s23, s14
	s_addc_u32 s39, s24, s15
	s_waitcnt vmcnt(0)
	v_pk_add_f32 v[158:159], v[158:159], 1.0 op_sel_hi:[1,0]
	v_pk_add_f32 v[156:157], v[156:157], 1.0 op_sel_hi:[1,0]
	v_pk_mul_f32 v[180:181], v[150:151], v[158:159]
	v_pk_mul_f32 v[182:183], v[148:149], v[156:157]
	global_load_dwordx4 v[156:159], v194, s[54:55]
	v_pk_add_f32 v[148:149], v[154:155], 1.0 op_sel_hi:[1,0]
	v_pk_add_f32 v[150:151], v[152:153], 1.0 op_sel_hi:[1,0]
	global_load_dwordx4 v[152:155], v193, s[54:55]
	v_pk_mul_f32 v[184:185], v[146:147], v[148:149]
	v_pk_mul_f32 v[186:187], v[144:145], v[150:151]
	global_load_dwordx4 v[144:147], v191, s[54:55]
	v_cvt_f32_f16_e32 v178, v174
	v_cvt_f32_f16_sdwa v179, v174 dst_sel:DWORD dst_unused:UNUSED_PAD src0_sel:WORD_1
	v_cvt_f32_f16_e32 v174, v175
	v_cvt_f32_f16_sdwa v175, v175 dst_sel:DWORD dst_unused:UNUSED_PAD src0_sel:WORD_1
	global_load_dwordx4 v[148:151], v192, s[54:55]
	v_pk_fma_f32 v[142:143], v[142:143], v[138:139], v[174:175]
	v_pk_fma_f32 v[174:175], v[140:141], v[136:137], v[178:179]
	v_cvt_f32_f16_e32 v140, v176
	v_cvt_f32_f16_sdwa v141, v176 dst_sel:DWORD dst_unused:UNUSED_PAD src0_sel:WORD_1
	v_cvt_f32_f16_e32 v176, v177
	v_cvt_f32_f16_sdwa v177, v177 dst_sel:DWORD dst_unused:UNUSED_PAD src0_sel:WORD_1
	v_pk_fma_f32 v[178:179], v[132:133], v[128:129], v[140:141]
	v_cvt_pk_f16_f32 v132, v174, v175
	v_pk_fma_f32 v[176:177], v[134:135], v[130:131], v[176:177]
	v_cvt_pk_f16_f32 v133, v142, v143
	v_cvt_pk_f16_f32 v134, v178, v179
	v_cvt_pk_f16_f32 v135, v176, v177
	global_store_dwordx4 v189, v[132:135], s[54:55] sc1
	v_pk_mul_f32 v[140:141], v[184:185], v[176:177]
	v_pk_mul_f32 v[198:199], v[186:187], v[178:179]
	v_pk_mul_f32 v[134:135], v[180:181], v[142:143]
	v_pk_mul_f32 v[132:133], v[182:183], v[174:175]
	s_nop 0
	v_cvt_pk_bf16_f32 v132, v132, v133
	v_cvt_pk_bf16_f32 v133, v134, v135
	v_cvt_pk_bf16_f32 v134, v198, v199
	v_cvt_pk_bf16_f32 v135, v140, v141
	global_store_dwordx4 v189, v[132:135], s[38:39] sc1
	s_nop 1
	v_cvt_f32_f16_e32 v132, v170
	v_cvt_f32_f16_sdwa v133, v170 dst_sel:DWORD dst_unused:UNUSED_PAD src0_sel:WORD_1
	v_cvt_f32_f16_e32 v134, v171
	v_cvt_f32_f16_sdwa v135, v171 dst_sel:DWORD dst_unused:UNUSED_PAD src0_sel:WORD_1
	v_pk_fma_f32 v[124:125], v[124:125], v[136:137], v[132:133]
	v_cvt_f32_f16_e32 v132, v172
	v_pk_fma_f32 v[126:127], v[126:127], v[138:139], v[134:135]
	v_cvt_f32_f16_sdwa v133, v172 dst_sel:DWORD dst_unused:UNUSED_PAD src0_sel:WORD_1
	v_cvt_f32_f16_e32 v134, v173
	v_cvt_f32_f16_sdwa v135, v173 dst_sel:DWORD dst_unused:UNUSED_PAD src0_sel:WORD_1
	v_pk_fma_f32 v[132:133], v[120:121], v[128:129], v[132:133]
	v_cvt_pk_f16_f32 v120, v124, v125
	v_pk_fma_f32 v[134:135], v[122:123], v[130:131], v[134:135]
	v_cvt_pk_f16_f32 v121, v126, v127
	v_cvt_pk_f16_f32 v122, v132, v133
	v_cvt_pk_f16_f32 v123, v134, v135
	global_store_dwordx4 v197, v[120:123], s[54:55] sc1
	s_nop 1
	v_mul_f32_e32 v120, v125, v125
	v_mul_f32_e32 v121, v127, v127
	v_fmac_f32_e32 v120, v124, v124
	v_fmac_f32_e32 v121, v126, v126
	v_add_f32_e32 v120, v120, v121
	v_mul_f32_e32 v121, v133, v133
	v_fmac_f32_e32 v121, v132, v132
	v_add_f32_e32 v120, v121, v120
	v_mul_f32_e32 v121, v135, v135
	v_fmac_f32_e32 v121, v134, v134
	v_add_f32_e32 v170, v121, v120
	v_pk_mul_f32 v[122:123], v[180:181], v[126:127]
	v_pk_mul_f32 v[120:121], v[182:183], v[124:125]
	v_pk_mul_f32 v[124:125], v[184:185], v[134:135]
	v_pk_mul_f32 v[126:127], v[186:187], v[132:133]
	v_cvt_pk_bf16_f32 v120, v120, v121
	v_cvt_pk_bf16_f32 v121, v122, v123
	s_nop 0
	v_cvt_pk_bf16_f32 v122, v126, v127
	v_cvt_pk_bf16_f32 v123, v124, v125
	global_store_dwordx4 v197, v[120:123], s[38:39] sc1
	s_nop 1
	v_cvt_f32_f16_e32 v120, v166
	v_cvt_f32_f16_sdwa v121, v166 dst_sel:DWORD dst_unused:UNUSED_PAD src0_sel:WORD_1
; __device__ __forceinline__ float h16_lo(unsigned u) { return (float)__builtin_bit_cast(h16x2, u).x; }
; __device__ __forceinline__ float h16_hi(unsigned u) { return (float)__builtin_bit_cast(h16x2, u).y; }
; __device__ __forceinline__ unsigned cvt_pk_bf16(float lo, float hi) { unsigned r; asm volatile("v_cvt_pk_bf16_f32 %0, %1, %2" : "=v"(r) : "v"(lo), "v"(hi)); return r; }
;     __device__ __forceinline__ void operator()(const f32x4 (&acc)[2][2][4][2], const Unit& u, int wr, int wc, int fr, int fq, const PG8_LAS float*) const {
;     ...
;                 for (int m = 0; m < 4; ++m) { const unsigned o = lo + (unsigned)((ai * HALF + m * 16) * DM + bj * HALF) * 2u; const u32x4 b = bs[ai][m];
;                     const f32x4 x0 = (f32x4){h16_lo(b.x), h16_hi(b.x), h16_lo(b.y), h16_hi(b.y)} + acc[ai][bj][m][0] * gv[0], x1 = (f32x4){h16_lo(b.z), h16_hi(b.z), h16_lo(b.w), h16_hi(b.w)} + acc[ai][bj][m][1] * gv[1];
;                     { u32x4 w; w.x = pk_h16(x0.x, x0.y); w.y = pk_h16(x0.z, x0.w); w.z = pk_h16(x1.x, x1.y); w.w = pk_h16(x1.z, x1.w); *(gu32x4*)(ot + o) = w; }
;                     ssq[ai][m] += (x0.x * x0.x + x0.y * x0.y) + (x0.z * x0.z + x0.w * x0.w) + (x1.x * x1.x + x1.y * x1.y) + (x1.z * x1.z + x1.w * x1.w);
;                     if (An) { const f32x4 y0 = x0 * gm[0], y1 = x1 * gm[1]; u32x4 w; w.x = cvt_pk_bf16(y0.x, y0.y); w.y = cvt_pk_bf16(y0.z, y0.w); w.z = cvt_pk_bf16(y1.x, y1.y); w.w = cvt_pk_bf16(y1.z, y1.w); *(gu32x4*)(at + o) = w; } }
	v_cvt_f32_f16_e32 v122, v167
	v_cvt_f32_f16_sdwa v123, v167 dst_sel:DWORD dst_unused:UNUSED_PAD src0_sel:WORD_1
	v_add_u32_e32 v167, 0x80100, v189
	v_pk_fma_f32 v[116:117], v[116:117], v[136:137], v[120:121]
	v_cvt_f32_f16_e32 v120, v168
	v_pk_fma_f32 v[118:119], v[118:119], v[138:139], v[122:123]
	v_cvt_f32_f16_sdwa v121, v168 dst_sel:DWORD dst_unused:UNUSED_PAD src0_sel:WORD_1
	v_cvt_f32_f16_e32 v122, v169
	v_cvt_f32_f16_sdwa v123, v169 dst_sel:DWORD dst_unused:UNUSED_PAD src0_sel:WORD_1
	v_pk_fma_f32 v[120:121], v[112:113], v[128:129], v[120:121]
	v_cvt_pk_f16_f32 v112, v116, v117
	v_pk_fma_f32 v[122:123], v[114:115], v[130:131], v[122:123]
	v_cvt_pk_f16_f32 v113, v118, v119
	v_cvt_pk_f16_f32 v114, v120, v121
	v_cvt_pk_f16_f32 v115, v122, v123
	global_store_dwordx4 v196, v[112:115], s[54:55] sc1
	s_nop 1
	v_mul_f32_e32 v112, v117, v117
	v_mul_f32_e32 v113, v119, v119
	v_fmac_f32_e32 v112, v116, v116
	v_fmac_f32_e32 v113, v118, v118
	v_add_f32_e32 v112, v112, v113
	v_mul_f32_e32 v113, v121, v121
	v_fmac_f32_e32 v113, v120, v120
	v_add_f32_e32 v112, v113, v112
	v_mul_f32_e32 v113, v123, v123
	v_fmac_f32_e32 v113, v122, v122
	v_add_f32_e32 v166, v113, v112
	v_pk_mul_f32 v[114:115], v[180:181], v[118:119]
	v_pk_mul_f32 v[112:113], v[182:183], v[116:117]
	v_pk_mul_f32 v[116:117], v[184:185], v[122:123]
	v_pk_mul_f32 v[118:119], v[186:187], v[120:121]
	v_cvt_pk_bf16_f32 v112, v112, v113
	v_cvt_pk_bf16_f32 v113, v114, v115
	s_nop 0
	v_cvt_pk_bf16_f32 v114, v118, v119
	v_cvt_pk_bf16_f32 v115, v116, v117
	global_store_dwordx4 v196, v[112:115], s[38:39] sc1
	s_nop 1
	v_cvt_f32_f16_e32 v112, v162
	v_cvt_f32_f16_sdwa v113, v162 dst_sel:DWORD dst_unused:UNUSED_PAD src0_sel:WORD_1
	v_cvt_f32_f16_e32 v114, v163
	v_cvt_f32_f16_sdwa v115, v163 dst_sel:DWORD dst_unused:UNUSED_PAD src0_sel:WORD_1
	v_add_u32_e32 v163, 0x10100, v189
	v_pk_fma_f32 v[108:109], v[108:109], v[136:137], v[112:113]
	v_cvt_f32_f16_e32 v112, v164
	v_pk_fma_f32 v[110:111], v[110:111], v[138:139], v[114:115]
	v_cvt_f32_f16_sdwa v113, v164 dst_sel:DWORD dst_unused:UNUSED_PAD src0_sel:WORD_1
	v_cvt_f32_f16_e32 v114, v165
	v_cvt_f32_f16_sdwa v115, v165 dst_sel:DWORD dst_unused:UNUSED_PAD src0_sel:WORD_1
	v_add_u32_e32 v164, 0x20100, v189
	v_pk_fma_f32 v[112:113], v[104:105], v[128:129], v[112:113]
	v_cvt_pk_f16_f32 v104, v108, v109
	v_pk_fma_f32 v[114:115], v[106:107], v[130:131], v[114:115]
	v_cvt_pk_f16_f32 v105, v110, v111
	v_cvt_pk_f16_f32 v106, v112, v113
	v_cvt_pk_f16_f32 v107, v114, v115
	global_store_dwordx4 v195, v[104:107], s[54:55] sc1
	v_add_u32_e32 v165, 0x30100, v189
	s_nop 0
	v_mul_f32_e32 v104, v109, v109
	v_mul_f32_e32 v105, v111, v111
	v_fmac_f32_e32 v104, v108, v108
	v_fmac_f32_e32 v105, v110, v110
	v_add_f32_e32 v104, v104, v105
	v_mul_f32_e32 v105, v113, v113
	v_fmac_f32_e32 v105, v112, v112
	v_add_f32_e32 v104, v105, v104
	v_mul_f32_e32 v105, v115, v115
	v_fmac_f32_e32 v105, v114, v114
	v_add_f32_e32 v162, v105, v104
	v_pk_mul_f32 v[106:107], v[180:181], v[110:111]
	v_pk_mul_f32 v[104:105], v[182:183], v[108:109]
	v_pk_mul_f32 v[108:109], v[184:185], v[114:115]
	v_pk_mul_f32 v[110:111], v[186:187], v[112:113]
	v_cvt_pk_bf16_f32 v104, v104, v105
	v_cvt_pk_bf16_f32 v105, v106, v107
	s_nop 0
	v_cvt_pk_bf16_f32 v106, v110, v111
	v_cvt_pk_bf16_f32 v107, v108, v109
	global_store_dwordx4 v195, v[104:107], s[38:39] sc1
	s_waitcnt vmcnt(11)
	s_nop 0
	v_cvt_f32_f16_e32 v106, v156
	v_cvt_f32_f16_sdwa v107, v156 dst_sel:DWORD dst_unused:UNUSED_PAD src0_sel:WORD_1
	v_cvt_f32_f16_e32 v104, v157
	v_cvt_f32_f16_sdwa v105, v157 dst_sel:DWORD dst_unused:UNUSED_PAD src0_sel:WORD_1
	v_pk_fma_f32 v[106:107], v[100:101], v[136:137], v[106:107]
	v_cvt_f32_f16_e32 v100, v158
	v_pk_fma_f32 v[104:105], v[102:103], v[138:139], v[104:105]
	v_cvt_f32_f16_sdwa v101, v158 dst_sel:DWORD dst_unused:UNUSED_PAD src0_sel:WORD_1
	v_cvt_f32_f16_e32 v102, v159
	v_cvt_f32_f16_sdwa v103, v159 dst_sel:DWORD dst_unused:UNUSED_PAD src0_sel:WORD_1
	v_pk_fma_f32 v[110:111], v[96:97], v[128:129], v[100:101]
	v_cvt_pk_f16_f32 v96, v106, v107
	v_pk_fma_f32 v[108:109], v[98:99], v[130:131], v[102:103]
	v_cvt_pk_f16_f32 v97, v104, v105
	v_cvt_pk_f16_f32 v98, v110, v111
	v_cvt_pk_f16_f32 v99, v108, v109
	global_store_dwordx4 v194, v[96:99], s[54:55] sc1
	v_pk_mul_f32 v[100:101], v[184:185], v[108:109]
	v_pk_mul_f32 v[102:103], v[186:187], v[110:111]
	v_pk_mul_f32 v[98:99], v[180:181], v[104:105]
	v_pk_mul_f32 v[96:97], v[182:183], v[106:107]
	s_nop 0
	v_cvt_pk_bf16_f32 v96, v96, v97
	v_cvt_pk_bf16_f32 v97, v98, v99
	v_cvt_pk_bf16_f32 v98, v102, v103
	v_cvt_pk_bf16_f32 v99, v100, v101
	global_store_dwordx4 v194, v[96:99], s[38:39] sc1
	s_waitcnt vmcnt(12)
	s_nop 0
	v_cvt_f32_f16_e32 v96, v152
	v_cvt_f32_f16_sdwa v97, v152 dst_sel:DWORD dst_unused:UNUSED_PAD src0_sel:WORD_1
	v_cvt_f32_f16_e32 v98, v153
	v_cvt_f32_f16_sdwa v99, v153 dst_sel:DWORD dst_unused:UNUSED_PAD src0_sel:WORD_1
	v_pk_fma_f32 v[116:117], v[92:93], v[136:137], v[96:97]
	v_cvt_f32_f16_e32 v92, v154
	v_pk_fma_f32 v[114:115], v[94:95], v[138:139], v[98:99]
	v_cvt_f32_f16_sdwa v93, v154 dst_sel:DWORD dst_unused:UNUSED_PAD src0_sel:WORD_1
	v_cvt_f32_f16_e32 v94, v155
	v_cvt_f32_f16_sdwa v95, v155 dst_sel:DWORD dst_unused:UNUSED_PAD src0_sel:WORD_1
	v_pk_fma_f32 v[124:125], v[88:89], v[128:129], v[92:93]
	v_cvt_pk_f16_f32 v88, v116, v117
	v_pk_fma_f32 v[122:123], v[90:91], v[130:131], v[94:95]
	v_cvt_pk_f16_f32 v89, v114, v115
	v_cvt_pk_f16_f32 v90, v124, v125
	v_cvt_pk_f16_f32 v91, v122, v123
	global_store_dwordx4 v193, v[88:91], s[54:55] sc1
	v_pk_mul_f32 v[92:93], v[184:185], v[122:123]
	v_pk_mul_f32 v[94:95], v[186:187], v[124:125]
	v_pk_mul_f32 v[90:91], v[180:181], v[114:115]
	v_pk_mul_f32 v[88:89], v[182:183], v[116:117]
	s_nop 0
	v_cvt_pk_bf16_f32 v88, v88, v89
	v_cvt_pk_bf16_f32 v89, v90, v91
	v_cvt_pk_bf16_f32 v90, v94, v95
	v_cvt_pk_bf16_f32 v91, v92, v93
	global_store_dwordx4 v193, v[88:91], s[38:39] sc1
	v_add_u32_e32 v92, 0x200, v190
	s_waitcnt vmcnt(12)
; __device__ __forceinline__ float h16_lo(unsigned u) { return (float)__builtin_bit_cast(h16x2, u).x; }
; __device__ __forceinline__ float h16_hi(unsigned u) { return (float)__builtin_bit_cast(h16x2, u).y; }
; __device__ __forceinline__ unsigned cvt_pk_bf16(float lo, float hi) { unsigned r; asm volatile("v_cvt_pk_bf16_f32 %0, %1, %2" : "=v"(r) : "v"(lo), "v"(hi)); return r; }
;     __device__ __forceinline__ void operator()(const f32x4 (&acc)[2][2][4][2], const Unit& u, int wr, int wc, int fr, int fq, const PG8_LAS float*) const {
;     ...
;             for (int n = 0; n < 2; ++n) { const unsigned c = co + (unsigned)(bj * HALF + n * 4) * 4u;
;                 gv[n] = *(const gf32x4*)(gate + c); if (ls) gv[n] = gv[n] * *(const gf32x4*)(lsp + c);
;                 gm[n] = An ? *(const gf32x4*)(gnp + c) * (*(const gf32x4*)(scp + c) + 1.0f) : (f32x4){0.f, 0.f, 0.f, 0.f}; }
;             u32x4 bs[2][4];
; #pragma unroll
;             for (int ai = 0; ai < 2; ++ai)
; #pragma unroll
;                 for (int m = 0; m < 4; ++m) { const unsigned o = lo + (unsigned)((ai * HALF + m * 16) * DM + bj * HALF) * 2u; bs[ai][m] = *(const gu32x4*)(bt + o); }
;             asm volatile("" ::: "memory");
; #pragma unroll
;             for (int ai = 0; ai < 2; ++ai)
; #pragma unroll
;                 for (int m = 0; m < 4; ++m) { const unsigned o = lo + (unsigned)((ai * HALF + m * 16) * DM + bj * HALF) * 2u; const u32x4 b = bs[ai][m];
;                     const f32x4 x0 = (f32x4){h16_lo(b.x), h16_hi(b.x), h16_lo(b.y), h16_hi(b.y)} + acc[ai][bj][m][0] * gv[0], x1 = (f32x4){h16_lo(b.z), h16_hi(b.z), h16_lo(b.w), h16_hi(b.w)} + acc[ai][bj][m][1] * gv[1];
;                     { u32x4 w; w.x = pk_h16(x0.x, x0.y); w.y = pk_h16(x0.z, x0.w); w.z = pk_h16(x1.x, x1.y); w.w = pk_h16(x1.z, x1.w); *(gu32x4*)(ot + o) = w; }
;                     ssq[ai][m] += (x0.x * x0.x + x0.y * x0.y) + (x0.z * x0.z + x0.w * x0.w) + (x1.x * x1.x + x1.y * x1.y) + (x1.z * x1.z + x1.w * x1.w);
;                     if (An) { const f32x4 y0 = x0 * gm[0], y1 = x1 * gm[1]; u32x4 w; w.x = cvt_pk_bf16(y0.x, y0.y); w.y = cvt_pk_bf16(y0.z, y0.w); w.z = cvt_pk_bf16(y1.x, y1.y); w.w = cvt_pk_bf16(y1.z, y1.w); *(gu32x4*)(at + o) = w; } }
	v_cvt_f32_f16_e32 v88, v148
	v_cvt_f32_f16_sdwa v89, v148 dst_sel:DWORD dst_unused:UNUSED_PAD src0_sel:WORD_1
	v_cvt_f32_f16_e32 v90, v149
	v_cvt_f32_f16_sdwa v91, v149 dst_sel:DWORD dst_unused:UNUSED_PAD src0_sel:WORD_1
	v_add_u32_e32 v149, 0x100, v189
	v_pk_fma_f32 v[134:135], v[84:85], v[136:137], v[88:89]
	v_cvt_f32_f16_e32 v84, v150
	v_pk_fma_f32 v[132:133], v[86:87], v[138:139], v[90:91]
	v_cvt_f32_f16_sdwa v85, v150 dst_sel:DWORD dst_unused:UNUSED_PAD src0_sel:WORD_1
	v_cvt_f32_f16_e32 v86, v151
	v_cvt_f32_f16_sdwa v87, v151 dst_sel:DWORD dst_unused:UNUSED_PAD src0_sel:WORD_1
	v_add_u32_e32 v148, 0x90100, v189
	v_pk_fma_f32 v[140:141], v[80:81], v[128:129], v[84:85]
	v_cvt_pk_f16_f32 v80, v134, v135
	v_pk_fma_f32 v[112:113], v[82:83], v[130:131], v[86:87]
	v_cvt_pk_f16_f32 v81, v132, v133
	v_cvt_pk_f16_f32 v82, v140, v141
	v_cvt_pk_f16_f32 v83, v112, v113
	global_store_dwordx4 v192, v[80:83], s[54:55] sc1
	v_pk_mul_f32 v[84:85], v[184:185], v[112:113]
	v_pk_mul_f32 v[86:87], v[186:187], v[140:141]
	v_pk_mul_f32 v[82:83], v[180:181], v[132:133]
	v_pk_mul_f32 v[80:81], v[182:183], v[134:135]
	s_nop 0
	v_cvt_pk_bf16_f32 v80, v80, v81
	v_cvt_pk_bf16_f32 v81, v82, v83
	v_cvt_pk_bf16_f32 v82, v86, v87
	v_cvt_pk_bf16_f32 v83, v84, v85
	global_store_dwordx4 v192, v[80:83], s[38:39] sc1
	s_nop 1
	v_cvt_f32_f16_e32 v80, v144
	v_cvt_f32_f16_sdwa v81, v144 dst_sel:DWORD dst_unused:UNUSED_PAD src0_sel:WORD_1
	v_cvt_f32_f16_e32 v82, v145
	v_cvt_f32_f16_sdwa v83, v145 dst_sel:DWORD dst_unused:UNUSED_PAD src0_sel:WORD_1
	v_pk_fma_f32 v[120:121], v[76:77], v[136:137], v[80:81]
	v_cvt_f32_f16_e32 v76, v146
	v_pk_fma_f32 v[118:119], v[78:79], v[138:139], v[82:83]
	v_cvt_f32_f16_sdwa v77, v146 dst_sel:DWORD dst_unused:UNUSED_PAD src0_sel:WORD_1
	v_cvt_f32_f16_e32 v78, v147
	v_cvt_f32_f16_sdwa v79, v147 dst_sel:DWORD dst_unused:UNUSED_PAD src0_sel:WORD_1
	v_add_u32_e32 v147, 0xa0100, v189
	v_pk_fma_f32 v[128:129], v[72:73], v[128:129], v[76:77]
	v_cvt_pk_f16_f32 v72, v120, v121
	v_pk_fma_f32 v[126:127], v[74:75], v[130:131], v[78:79]
	v_cvt_pk_f16_f32 v73, v118, v119
	v_cvt_pk_f16_f32 v74, v128, v129
	v_cvt_pk_f16_f32 v75, v126, v127
	global_store_dwordx4 v191, v[72:75], s[54:55] sc1
	v_pk_mul_f32 v[76:77], v[184:185], v[126:127]
	v_pk_mul_f32 v[78:79], v[186:187], v[128:129]
	v_pk_mul_f32 v[74:75], v[180:181], v[118:119]
	v_pk_mul_f32 v[72:73], v[182:183], v[120:121]
	v_add_u32_e32 v146, 0xb0100, v189
	v_cvt_pk_bf16_f32 v72, v72, v73
	v_cvt_pk_bf16_f32 v73, v74, v75
	v_cvt_pk_bf16_f32 v74, v78, v79
	v_cvt_pk_bf16_f32 v75, v76, v77
	global_store_dwordx4 v191, v[72:75], s[38:39] sc1
	global_load_dwordx4 v[72:75], v92, s[58:59] offset:16
	global_load_dwordx4 v[76:79], v92, s[58:59]
	global_load_dwordx4 v[80:83], v92, s[12:13] offset:16
	global_load_dwordx4 v[84:87], v92, s[12:13]
	global_load_dwordx4 v[88:91], v92, s[56:57] offset:16
	s_nop 0
	global_load_dwordx4 v[92:95], v92, s[56:57]
	s_waitcnt vmcnt(0)
	v_pk_add_f32 v[94:95], v[94:95], 1.0 op_sel_hi:[1,0]
	global_load_dwordx4 v[150:153], v149, s[54:55]
	global_load_dwordx4 v[154:157], v163, s[54:55]
	global_load_dwordx4 v[100:103], v164, s[54:55]
	global_load_dwordx4 v[96:99], v165, s[54:55]
	v_pk_add_f32 v[92:93], v[92:93], 1.0 op_sel_hi:[1,0]
	v_pk_mul_f32 v[130:131], v[86:87], v[94:95]
	v_pk_mul_f32 v[136:137], v[84:85], v[92:93]
	global_load_dwordx4 v[92:95], v167, s[54:55]
	v_pk_add_f32 v[84:85], v[90:91], 1.0 op_sel_hi:[1,0]
	v_pk_add_f32 v[86:87], v[88:89], 1.0 op_sel_hi:[1,0]
	global_load_dwordx4 v[88:91], v148, s[54:55]
	v_pk_mul_f32 v[138:139], v[82:83], v[84:85]
	v_pk_mul_f32 v[144:145], v[80:81], v[86:87]
	global_load_dwordx4 v[84:87], v147, s[54:55]
	global_load_dwordx4 v[80:83], v146, s[54:55]
	s_waitcnt vmcnt(7)
	v_cvt_f32_f16_e32 v158, v150
	v_cvt_f32_f16_sdwa v159, v150 dst_sel:DWORD dst_unused:UNUSED_PAD src0_sel:WORD_1
	v_cvt_f32_f16_e32 v150, v151
	v_cvt_f32_f16_sdwa v151, v151 dst_sel:DWORD dst_unused:UNUSED_PAD src0_sel:WORD_1
	v_pk_fma_f32 v[68:69], v[68:69], v[76:77], v[158:159]
	v_pk_fma_f32 v[70:71], v[70:71], v[78:79], v[150:151]
	v_cvt_f32_f16_e32 v150, v152
	v_cvt_f32_f16_sdwa v151, v152 dst_sel:DWORD dst_unused:UNUSED_PAD src0_sel:WORD_1
	v_cvt_f32_f16_e32 v152, v153
	v_cvt_f32_f16_sdwa v153, v153 dst_sel:DWORD dst_unused:UNUSED_PAD src0_sel:WORD_1
	v_pk_fma_f32 v[150:151], v[64:65], v[72:73], v[150:151]
	v_cvt_pk_f16_f32 v64, v68, v69
	v_pk_fma_f32 v[152:153], v[66:67], v[74:75], v[152:153]
	v_cvt_pk_f16_f32 v65, v70, v71
	v_cvt_pk_f16_f32 v66, v150, v151
	v_cvt_pk_f16_f32 v67, v152, v153
	global_store_dwordx4 v149, v[64:67], s[54:55] sc1
	s_nop 1
	v_mov_b32_e32 v66, v175
	v_mov_b32_e32 v67, v69
	v_mov_b32_e32 v64, v174
	v_mov_b32_e32 v65, v68
	v_pk_mul_f32 v[66:67], v[66:67], v[66:67]
	s_nop 0
	v_pk_fma_f32 v[64:65], v[64:65], v[64:65], v[66:67]
	v_mov_b32_e32 v66, v142
	v_mov_b32_e32 v142, v143
	v_mov_b32_e32 v143, v71
	v_mov_b32_e32 v67, v70
	v_pk_mul_f32 v[142:143], v[142:143], v[142:143]
	v_pk_mul_f32 v[70:71], v[130:131], v[70:71]
	v_pk_fma_f32 v[66:67], v[66:67], v[66:67], v[142:143]
	v_mov_b32_e32 v142, v179
	v_mov_b32_e32 v143, v151
	v_pk_add_f32 v[64:65], v[64:65], v[66:67]
	v_mov_b32_e32 v66, v178
	v_mov_b32_e32 v67, v150
	v_pk_mul_f32 v[142:143], v[142:143], v[142:143]
	s_nop 0
	v_pk_fma_f32 v[66:67], v[66:67], v[66:67], v[142:143]
	v_mov_b32_e32 v142, v177
	v_mov_b32_e32 v143, v153
	v_pk_add_f32 v[64:65], v[66:67], v[64:65]
	v_mov_b32_e32 v66, v176
	v_mov_b32_e32 v67, v152
	v_pk_mul_f32 v[142:143], v[142:143], v[142:143]
	s_nop 0
	v_pk_fma_f32 v[66:67], v[66:67], v[66:67], v[142:143]
	v_pk_mul_f32 v[142:143], v[138:139], v[152:153]
	v_pk_add_f32 v[64:65], v[66:67], v[64:65]
	v_pk_mul_f32 v[66:67], v[136:137], v[68:69]
	v_pk_mul_f32 v[68:69], v[144:145], v[150:151]
	v_cvt_pk_bf16_f32 v66, v66, v67
	v_cvt_pk_bf16_f32 v67, v70, v71
	v_add_f32_e32 v64, v64, v65
	v_cvt_pk_bf16_f32 v68, v68, v69
	v_cvt_pk_bf16_f32 v69, v142, v143
	global_store_dwordx4 v149, v[66:69], s[38:39] sc1
	s_waitcnt vmcnt(8)
; __device__ __forceinline__ float h16_lo(unsigned u) { return (float)__builtin_bit_cast(h16x2, u).x; }
; __device__ __forceinline__ float h16_hi(unsigned u) { return (float)__builtin_bit_cast(h16x2, u).y; }
; __device__ __forceinline__ unsigned cvt_pk_bf16(float lo, float hi) { unsigned r; asm volatile("v_cvt_pk_bf16_f32 %0, %1, %2" : "=v"(r) : "v"(lo), "v"(hi)); return r; }
;     __device__ __forceinline__ void operator()(const f32x4 (&acc)[2][2][4][2], const Unit& u, int wr, int wc, int fr, int fq, const PG8_LAS float*) const {
;     ...
;                 for (int m = 0; m < 4; ++m) { const unsigned o = lo + (unsigned)((ai * HALF + m * 16) * DM + bj * HALF) * 2u; const u32x4 b = bs[ai][m];
;                     const f32x4 x0 = (f32x4){h16_lo(b.x), h16_hi(b.x), h16_lo(b.y), h16_hi(b.y)} + acc[ai][bj][m][0] * gv[0], x1 = (f32x4){h16_lo(b.z), h16_hi(b.z), h16_lo(b.w), h16_hi(b.w)} + acc[ai][bj][m][1] * gv[1];
;                     { u32x4 w; w.x = pk_h16(x0.x, x0.y); w.y = pk_h16(x0.z, x0.w); w.z = pk_h16(x1.x, x1.y); w.w = pk_h16(x1.z, x1.w); *(gu32x4*)(ot + o) = w; }
;                     ssq[ai][m] += (x0.x * x0.x + x0.y * x0.y) + (x0.z * x0.z + x0.w * x0.w) + (x1.x * x1.x + x1.y * x1.y) + (x1.z * x1.z + x1.w * x1.w);
;                     if (An) { const f32x4 y0 = x0 * gm[0], y1 = x1 * gm[1]; u32x4 w; w.x = cvt_pk_bf16(y0.x, y0.y); w.y = cvt_pk_bf16(y0.z, y0.w); w.z = cvt_pk_bf16(y1.x, y1.y); w.w = cvt_pk_bf16(y1.z, y1.w); *(gu32x4*)(at + o) = w; } }
	s_nop 0
	v_cvt_f32_f16_e32 v66, v154
	v_cvt_f32_f16_sdwa v67, v154 dst_sel:DWORD dst_unused:UNUSED_PAD src0_sel:WORD_1
	v_cvt_f32_f16_e32 v68, v155
	v_cvt_f32_f16_sdwa v69, v155 dst_sel:DWORD dst_unused:UNUSED_PAD src0_sel:WORD_1
	v_pk_fma_f32 v[60:61], v[60:61], v[76:77], v[66:67]
	v_cvt_f32_f16_e32 v66, v156
	v_pk_fma_f32 v[62:63], v[62:63], v[78:79], v[68:69]
	v_cvt_f32_f16_sdwa v67, v156 dst_sel:DWORD dst_unused:UNUSED_PAD src0_sel:WORD_1
	v_cvt_f32_f16_e32 v68, v157
	v_cvt_f32_f16_sdwa v69, v157 dst_sel:DWORD dst_unused:UNUSED_PAD src0_sel:WORD_1
	v_pk_fma_f32 v[66:67], v[56:57], v[72:73], v[66:67]
	v_cvt_pk_f16_f32 v56, v60, v61
	v_pk_fma_f32 v[68:69], v[58:59], v[74:75], v[68:69]
	v_cvt_pk_f16_f32 v57, v62, v63
	v_cvt_pk_f16_f32 v58, v66, v67
	v_cvt_pk_f16_f32 v59, v68, v69
	global_store_dwordx4 v163, v[56:59], s[54:55] sc1
	s_nop 1
	v_mul_f32_e32 v56, v61, v61
	v_mul_f32_e32 v57, v63, v63
	v_fmac_f32_e32 v56, v60, v60
	v_fmac_f32_e32 v57, v62, v62
	v_add_f32_e32 v56, v56, v57
	v_mul_f32_e32 v57, v67, v67
	v_fmac_f32_e32 v57, v66, v66
	v_add_f32_e32 v56, v57, v56
	v_mul_f32_e32 v57, v69, v69
	v_pk_mul_f32 v[58:59], v[136:137], v[60:61]
	v_pk_mul_f32 v[60:61], v[144:145], v[66:67]
	v_fmac_f32_e32 v57, v68, v68
	v_pk_mul_f32 v[62:63], v[130:131], v[62:63]
	v_pk_mul_f32 v[68:69], v[138:139], v[68:69]
	v_cvt_pk_bf16_f32 v58, v58, v59
	v_cvt_pk_bf16_f32 v59, v62, v63
	v_cvt_pk_bf16_f32 v60, v60, v61
	v_add_f32_e32 v56, v57, v56
	v_cvt_pk_bf16_f32 v61, v68, v69
	global_store_dwordx4 v163, v[58:61], s[38:39] sc1
	v_add_f32_e32 v56, v170, v56
	s_waitcnt vmcnt(9)
	v_cvt_f32_f16_e32 v58, v100
	v_cvt_f32_f16_sdwa v59, v100 dst_sel:DWORD dst_unused:UNUSED_PAD src0_sel:WORD_1
	v_cvt_f32_f16_e32 v60, v101
	v_cvt_f32_f16_sdwa v61, v101 dst_sel:DWORD dst_unused:UNUSED_PAD src0_sel:WORD_1
	v_pk_fma_f32 v[52:53], v[52:53], v[76:77], v[58:59]
	v_cvt_f32_f16_e32 v58, v102
	v_pk_fma_f32 v[54:55], v[54:55], v[78:79], v[60:61]
	v_cvt_f32_f16_sdwa v59, v102 dst_sel:DWORD dst_unused:UNUSED_PAD src0_sel:WORD_1
	v_cvt_f32_f16_e32 v60, v103
	v_cvt_f32_f16_sdwa v61, v103 dst_sel:DWORD dst_unused:UNUSED_PAD src0_sel:WORD_1
	v_pk_fma_f32 v[58:59], v[48:49], v[72:73], v[58:59]
	v_cvt_pk_f16_f32 v48, v52, v53
	v_pk_fma_f32 v[60:61], v[50:51], v[74:75], v[60:61]
	v_cvt_pk_f16_f32 v49, v54, v55
	v_cvt_pk_f16_f32 v50, v58, v59
	v_cvt_pk_f16_f32 v51, v60, v61
	global_store_dwordx4 v164, v[48:51], s[54:55] sc1
	s_nop 1
	v_mul_f32_e32 v48, v53, v53
	v_mul_f32_e32 v49, v55, v55
	v_fmac_f32_e32 v48, v52, v52
	v_fmac_f32_e32 v49, v54, v54
	v_add_f32_e32 v48, v48, v49
	v_mul_f32_e32 v49, v59, v59
	v_fmac_f32_e32 v49, v58, v58
	v_add_f32_e32 v48, v49, v48
	v_mul_f32_e32 v49, v61, v61
	v_fmac_f32_e32 v49, v60, v60
	v_add_f32_e32 v48, v49, v48
	v_add_f32_e32 v57, v166, v48
	v_pk_mul_f32 v[50:51], v[130:131], v[54:55]
	v_pk_mul_f32 v[48:49], v[136:137], v[52:53]
	v_pk_mul_f32 v[52:53], v[138:139], v[60:61]
	v_pk_mul_f32 v[54:55], v[144:145], v[58:59]
	v_cvt_pk_bf16_f32 v48, v48, v49
	v_cvt_pk_bf16_f32 v49, v50, v51
	s_nop 0
	v_cvt_pk_bf16_f32 v50, v54, v55
	v_cvt_pk_bf16_f32 v51, v52, v53
	global_store_dwordx4 v164, v[48:51], s[38:39] sc1
	s_waitcnt vmcnt(10)
	s_nop 0
	v_cvt_f32_f16_e32 v48, v96
	v_cvt_f32_f16_sdwa v49, v96 dst_sel:DWORD dst_unused:UNUSED_PAD src0_sel:WORD_1
	v_cvt_f32_f16_e32 v50, v97
	v_cvt_f32_f16_sdwa v51, v97 dst_sel:DWORD dst_unused:UNUSED_PAD src0_sel:WORD_1
	v_pk_fma_f32 v[44:45], v[44:45], v[76:77], v[48:49]
	v_cvt_f32_f16_e32 v48, v98
	v_pk_fma_f32 v[46:47], v[46:47], v[78:79], v[50:51]
	v_cvt_f32_f16_sdwa v49, v98 dst_sel:DWORD dst_unused:UNUSED_PAD src0_sel:WORD_1
	v_cvt_f32_f16_e32 v50, v99
	v_cvt_f32_f16_sdwa v51, v99 dst_sel:DWORD dst_unused:UNUSED_PAD src0_sel:WORD_1
	v_pk_fma_f32 v[48:49], v[40:41], v[72:73], v[48:49]
	v_cvt_pk_f16_f32 v40, v44, v45
	v_pk_fma_f32 v[50:51], v[42:43], v[74:75], v[50:51]
	v_cvt_pk_f16_f32 v41, v46, v47
	v_cvt_pk_f16_f32 v42, v48, v49
	v_cvt_pk_f16_f32 v43, v50, v51
	global_store_dwordx4 v165, v[40:43], s[54:55] sc1
	s_nop 1
	v_mul_f32_e32 v40, v45, v45
	v_mul_f32_e32 v41, v47, v47
	v_fmac_f32_e32 v40, v44, v44
	v_fmac_f32_e32 v41, v46, v46
	v_add_f32_e32 v40, v40, v41
	v_mul_f32_e32 v41, v49, v49
	v_fmac_f32_e32 v41, v48, v48
	v_add_f32_e32 v40, v41, v40
	v_mul_f32_e32 v41, v51, v51
	v_fmac_f32_e32 v41, v50, v50
	v_add_f32_e32 v40, v41, v40
	v_add_f32_e32 v52, v162, v40
	v_pk_mul_f32 v[42:43], v[130:131], v[46:47]
	v_pk_mul_f32 v[40:41], v[136:137], v[44:45]
	v_pk_mul_f32 v[44:45], v[138:139], v[50:51]
	v_pk_mul_f32 v[46:47], v[144:145], v[48:49]
	v_cvt_pk_bf16_f32 v40, v40, v41
	v_cvt_pk_bf16_f32 v41, v42, v43
	s_nop 0
	v_cvt_pk_bf16_f32 v42, v46, v47
	v_cvt_pk_bf16_f32 v43, v44, v45
	global_store_dwordx4 v165, v[40:43], s[38:39] sc1
	s_waitcnt vmcnt(11)
	s_nop 0
	v_cvt_f32_f16_e32 v40, v92
	v_cvt_f32_f16_sdwa v41, v92 dst_sel:DWORD dst_unused:UNUSED_PAD src0_sel:WORD_1
	v_cvt_f32_f16_e32 v42, v93
	v_cvt_f32_f16_sdwa v43, v93 dst_sel:DWORD dst_unused:UNUSED_PAD src0_sel:WORD_1
	v_pk_fma_f32 v[36:37], v[36:37], v[76:77], v[40:41]
	v_cvt_f32_f16_e32 v40, v94
	v_pk_fma_f32 v[38:39], v[38:39], v[78:79], v[42:43]
	v_cvt_f32_f16_sdwa v41, v94 dst_sel:DWORD dst_unused:UNUSED_PAD src0_sel:WORD_1
	v_cvt_f32_f16_e32 v42, v95
	v_cvt_f32_f16_sdwa v43, v95 dst_sel:DWORD dst_unused:UNUSED_PAD src0_sel:WORD_1
	v_pk_fma_f32 v[32:33], v[32:33], v[72:73], v[40:41]
	v_cvt_pk_f16_f32 v40, v36, v37
	v_pk_fma_f32 v[34:35], v[34:35], v[74:75], v[42:43]
	v_cvt_pk_f16_f32 v41, v38, v39
	v_cvt_pk_f16_f32 v42, v32, v33
	v_cvt_pk_f16_f32 v43, v34, v35
	global_store_dwordx4 v167, v[40:43], s[54:55] sc1
	v_pk_mul_f32 v[44:45], v[138:139], v[34:35]
	v_pk_mul_f32 v[46:47], v[144:145], v[32:33]
	v_pk_mul_f32 v[42:43], v[130:131], v[38:39]
	v_pk_mul_f32 v[40:41], v[136:137], v[36:37]
	s_nop 0
	v_cvt_pk_bf16_f32 v40, v40, v41
	v_cvt_pk_bf16_f32 v41, v42, v43
	v_cvt_pk_bf16_f32 v42, v46, v47
	v_cvt_pk_bf16_f32 v43, v44, v45
	global_store_dwordx4 v167, v[40:43], s[38:39] sc1
	s_waitcnt vmcnt(12)
; #define GAS __attribute__((address_space(1)))
; __device__ __forceinline__ float h16_lo(unsigned u) { return (float)__builtin_bit_cast(h16x2, u).x; }
; __device__ __forceinline__ float h16_hi(unsigned u) { return (float)__builtin_bit_cast(h16x2, u).y; }
; __device__ __forceinline__ unsigned cvt_pk_bf16(float lo, float hi) { unsigned r; asm volatile("v_cvt_pk_bf16_f32 %0, %1, %2" : "=v"(r) : "v"(lo), "v"(hi)); return r; }
; __device__ __forceinline__ void atomic_add_f32(gf32* p, float v) { (void)__builtin_amdgcn_global_atomic_fadd_f32(p, v); }
;     __device__ __forceinline__ void operator()(const f32x4 (&acc)[2][2][4][2], const Unit& u, int wr, int wc, int fr, int fq, const PG8_LAS float*) const {
;     ...
;                 for (int m = 0; m < 4; ++m) { const unsigned o = lo + (unsigned)((ai * HALF + m * 16) * DM + bj * HALF) * 2u; const u32x4 b = bs[ai][m];
;                     const f32x4 x0 = (f32x4){h16_lo(b.x), h16_hi(b.x), h16_lo(b.y), h16_hi(b.y)} + acc[ai][bj][m][0] * gv[0], x1 = (f32x4){h16_lo(b.z), h16_hi(b.z), h16_lo(b.w), h16_hi(b.w)} + acc[ai][bj][m][1] * gv[1];
;                     { u32x4 w; w.x = pk_h16(x0.x, x0.y); w.y = pk_h16(x0.z, x0.w); w.z = pk_h16(x1.x, x1.y); w.w = pk_h16(x1.z, x1.w); *(gu32x4*)(ot + o) = w; }
;                     ssq[ai][m] += (x0.x * x0.x + x0.y * x0.y) + (x0.z * x0.z + x0.w * x0.w) + (x1.x * x1.x + x1.y * x1.y) + (x1.z * x1.z + x1.w * x1.w);
;                     if (An) { const f32x4 y0 = x0 * gm[0], y1 = x1 * gm[1]; u32x4 w; w.x = cvt_pk_bf16(y0.x, y0.y); w.y = cvt_pk_bf16(y0.z, y0.w); w.z = cvt_pk_bf16(y1.x, y1.y); w.w = cvt_pk_bf16(y1.z, y1.w); *(gu32x4*)(at + o) = w; } }
;             asm volatile("" ::: "memory");
;         }
;         if (stats) {
; #pragma unroll
;             for (int ai = 0; ai < 2; ++ai) {
; #pragma unroll
;                 for (int m = 0; m < 4; ++m) { ssq[ai][m] += __shfl_xor(ssq[ai][m], 16); ssq[ai][m] += __shfl_xor(ssq[ai][m], 32); }
;                 const float v = fq == 0 ? ssq[ai][0] : fq == 1 ? ssq[ai][1] : fq == 2 ? ssq[ai][2] : ssq[ai][3];
;                 atomic_add_f32((gf32*)((GAS char*)(stats + u.pm * BM + ai * HALF) + so), v); }
	s_nop 0
	v_cvt_f32_f16_e32 v40, v88
	v_cvt_f32_f16_sdwa v41, v88 dst_sel:DWORD dst_unused:UNUSED_PAD src0_sel:WORD_1
	v_cvt_f32_f16_e32 v42, v89
	v_cvt_f32_f16_sdwa v43, v89 dst_sel:DWORD dst_unused:UNUSED_PAD src0_sel:WORD_1
	v_pk_fma_f32 v[28:29], v[28:29], v[76:77], v[40:41]
	v_cvt_f32_f16_e32 v40, v90
	v_pk_fma_f32 v[30:31], v[30:31], v[78:79], v[42:43]
	v_cvt_f32_f16_sdwa v41, v90 dst_sel:DWORD dst_unused:UNUSED_PAD src0_sel:WORD_1
	v_cvt_f32_f16_e32 v42, v91
	v_cvt_f32_f16_sdwa v43, v91 dst_sel:DWORD dst_unused:UNUSED_PAD src0_sel:WORD_1
	v_pk_fma_f32 v[24:25], v[24:25], v[72:73], v[40:41]
	v_cvt_pk_f16_f32 v40, v28, v29
	v_pk_fma_f32 v[26:27], v[26:27], v[74:75], v[42:43]
	v_cvt_pk_f16_f32 v41, v30, v31
	v_cvt_pk_f16_f32 v42, v24, v25
	v_cvt_pk_f16_f32 v43, v26, v27
	global_store_dwordx4 v148, v[40:43], s[54:55] sc1
	v_pk_mul_f32 v[44:45], v[138:139], v[26:27]
	v_pk_mul_f32 v[46:47], v[144:145], v[24:25]
	v_pk_mul_f32 v[42:43], v[130:131], v[30:31]
	v_pk_mul_f32 v[40:41], v[136:137], v[28:29]
	s_nop 0
	v_cvt_pk_bf16_f32 v40, v40, v41
	v_cvt_pk_bf16_f32 v41, v42, v43
	v_cvt_pk_bf16_f32 v42, v46, v47
	v_cvt_pk_bf16_f32 v43, v44, v45
	global_store_dwordx4 v148, v[40:43], s[38:39] sc1
	s_waitcnt vmcnt(13)
	s_nop 0
	v_cvt_f32_f16_e32 v40, v84
	v_cvt_f32_f16_sdwa v41, v84 dst_sel:DWORD dst_unused:UNUSED_PAD src0_sel:WORD_1
	v_cvt_f32_f16_e32 v42, v85
	v_cvt_f32_f16_sdwa v43, v85 dst_sel:DWORD dst_unused:UNUSED_PAD src0_sel:WORD_1
	v_pk_fma_f32 v[20:21], v[20:21], v[76:77], v[40:41]
	v_cvt_f32_f16_e32 v40, v86
	v_pk_fma_f32 v[22:23], v[22:23], v[78:79], v[42:43]
	v_cvt_f32_f16_sdwa v41, v86 dst_sel:DWORD dst_unused:UNUSED_PAD src0_sel:WORD_1
	v_cvt_f32_f16_e32 v42, v87
	v_cvt_f32_f16_sdwa v43, v87 dst_sel:DWORD dst_unused:UNUSED_PAD src0_sel:WORD_1
	v_pk_fma_f32 v[16:17], v[16:17], v[72:73], v[40:41]
	v_cvt_pk_f16_f32 v40, v20, v21
	v_pk_fma_f32 v[18:19], v[18:19], v[74:75], v[42:43]
	v_cvt_pk_f16_f32 v41, v22, v23
	v_cvt_pk_f16_f32 v42, v16, v17
	v_cvt_pk_f16_f32 v43, v18, v19
	global_store_dwordx4 v147, v[40:43], s[54:55] sc1
	v_pk_mul_f32 v[44:45], v[138:139], v[18:19]
	v_pk_mul_f32 v[46:47], v[144:145], v[16:17]
	v_pk_mul_f32 v[42:43], v[130:131], v[22:23]
	v_pk_mul_f32 v[40:41], v[136:137], v[20:21]
	s_nop 0
	v_cvt_pk_bf16_f32 v40, v40, v41
	v_cvt_pk_bf16_f32 v41, v42, v43
	v_cvt_pk_bf16_f32 v42, v46, v47
	v_cvt_pk_bf16_f32 v43, v44, v45
	global_store_dwordx4 v147, v[40:43], s[38:39] sc1
	s_waitcnt vmcnt(14)
	s_nop 0
	v_cvt_f32_f16_e32 v40, v80
	v_cvt_f32_f16_sdwa v41, v80 dst_sel:DWORD dst_unused:UNUSED_PAD src0_sel:WORD_1
	v_cvt_f32_f16_e32 v42, v81
	v_cvt_f32_f16_sdwa v43, v81 dst_sel:DWORD dst_unused:UNUSED_PAD src0_sel:WORD_1
	v_pk_fma_f32 v[12:13], v[12:13], v[76:77], v[40:41]
	v_cvt_f32_f16_e32 v40, v82
	v_pk_fma_f32 v[14:15], v[14:15], v[78:79], v[42:43]
	v_cvt_f32_f16_sdwa v41, v82 dst_sel:DWORD dst_unused:UNUSED_PAD src0_sel:WORD_1
	v_cvt_f32_f16_e32 v42, v83
	v_cvt_f32_f16_sdwa v43, v83 dst_sel:DWORD dst_unused:UNUSED_PAD src0_sel:WORD_1
	v_pk_fma_f32 v[8:9], v[8:9], v[72:73], v[40:41]
	v_cvt_pk_f16_f32 v40, v12, v13
	v_pk_fma_f32 v[10:11], v[10:11], v[74:75], v[42:43]
	v_cvt_pk_f16_f32 v41, v14, v15
	v_cvt_pk_f16_f32 v42, v8, v9
	v_cvt_pk_f16_f32 v43, v10, v11
	global_store_dwordx4 v146, v[40:43], s[54:55] sc1
	v_pk_mul_f32 v[44:45], v[138:139], v[10:11]
	v_pk_mul_f32 v[46:47], v[144:145], v[8:9]
	v_pk_mul_f32 v[40:41], v[136:137], v[12:13]
	v_pk_mul_f32 v[42:43], v[130:131], v[14:15]
	v_cvt_pk_bf16_f32 v40, v40, v41
	s_nop 0
	v_cvt_pk_bf16_f32 v41, v42, v43
	v_cvt_pk_bf16_f32 v42, v46, v47
	v_cvt_pk_bf16_f32 v43, v44, v45
	global_store_dwordx4 v146, v[40:43], s[38:39] sc1
	s_mov_b64 s[38:39], 0
	s_nop 0
	v_and_b32_e32 v41, 64, v238
	v_xor_b32_e32 v40, 16, v238
	v_add_u32_e32 v41, 64, v41
	v_cmp_lt_i32_e32 vcc, v40, v41
	v_xor_b32_e32 v42, 32, v238
	s_nop 0
	v_cndmask_b32_e32 v40, v238, v40, vcc
	v_lshlrev_b32_e32 v40, 2, v40
	v_cmp_lt_i32_e32 vcc, v42, v41
	ds_bpermute_b32 v44, v40, v52
	s_waitcnt lgkmcnt(0)
	v_add_f32_e32 v44, v52, v44
	v_cndmask_b32_e32 v41, v238, v42, vcc
	ds_bpermute_b32 v42, v40, v64
	v_lshlrev_b32_e32 v41, 2, v41
	ds_bpermute_b32 v45, v41, v44
	v_cmp_lt_i32_e32 vcc, 0, v188
	s_waitcnt lgkmcnt(1)
	v_add_f32_e32 v46, v64, v42
	ds_bpermute_b32 v42, v40, v56
	ds_bpermute_b32 v47, v41, v46
	s_waitcnt lgkmcnt(1)
	v_add_f32_e32 v48, v56, v42
	ds_bpermute_b32 v42, v40, v57
	ds_bpermute_b32 v49, v41, v48
	s_waitcnt lgkmcnt(1)
	v_add_f32_e32 v42, v57, v42
	ds_bpermute_b32 v43, v41, v42
	s_and_saveexec_b64 s[20:21], vcc
	s_xor_b64 s[28:29], exec, s[20:21]
	s_cbranch_execz .LBB0_1335
	v_cmp_lt_i32_e32 vcc, 1, v188
	s_and_saveexec_b64 s[20:21], vcc
	s_xor_b64 s[54:55], exec, s[20:21]
	s_cbranch_execz .LBB0_1322
	v_cmp_eq_u32_e32 vcc, 2, v188
	s_mov_b64 s[38:39], -1
	s_and_saveexec_b64 s[56:57], vcc
	s_xor_b64 s[38:39], exec, -1
	s_or_b64 exec, exec, s[56:57]
	s_and_b64 s[38:39], s[38:39], exec

; #define GAS __attribute__((address_space(1)))
; __device__ __forceinline__ float h16_lo(unsigned u) { return (float)__builtin_bit_cast(h16x2, u).x; }
; __device__ __forceinline__ float h16_hi(unsigned u) { return (float)__builtin_bit_cast(h16x2, u).y; }
; __device__ __forceinline__ unsigned cvt_pk_bf16(float lo, float hi) { unsigned r; asm volatile("v_cvt_pk_bf16_f32 %0, %1, %2" : "=v"(r) : "v"(lo), "v"(hi)); return r; }
; __device__ __forceinline__ void atomic_add_f32(gf32* p, float v) { (void)__builtin_amdgcn_global_atomic_fadd_f32(p, v); }
;     __device__ __forceinline__ void operator()(const f32x4 (&acc)[2][2][4][2], const Unit& u, int wr, int wc, int fr, int fq, const PG8_LAS float*) const {
;     ...
;                 atomic_add_f32((gf32*)((GAS char*)(stats + u.pm * BM + ai * HALF) + so), v); }
;     __device__ __forceinline__ void strip(const f32x4 (&accS)[2], const Unit& u, int wr, int wc, int fr, int fq) const {
;     ...
;         const GAS char* bt = (const GAS char*)(base + (size_t)u.srow * DM + u.pn * BM);
;         GAS char* ot = (GAS char*)(out + (size_t)u.srow * DM + u.pn * BM);
;         GAS char* at = (GAS char*)(An + (size_t)u.srow * DM + u.pn * BM);
;         asm volatile("" : "+v"(fr), "+v"(fq));
;         const unsigned co = (unsigned)(wc * 32 + 8 * fq + 4 * wr) * 4u, lo = (unsigned)(fr * DM) * 2u + (co >> 1), so = (unsigned)fr * 4u;
;         float q = 0.f;
; #pragma unroll
;         for (int bj = 0; bj < 2; ++bj) { const unsigned c = co + (unsigned)(bj * HALF) * 4u, o = lo + (unsigned)(bj * HALF) * 2u;
;             f32x4 gv = *(const gf32x4*)(gate + c); if (ls) gv = gv * *(const gf32x4*)(lsp + c);
;             const u32x2 b = *(const gu32x2*)(bt + o);
;             const f32x4 x0 = (f32x4){h16_lo(b.x), h16_hi(b.x), h16_lo(b.y), h16_hi(b.y)} + accS[bj] * gv; { u32x2 w; w.x = pk_h16(x0.x, x0.y); w.y = pk_h16(x0.z, x0.w); *(gu32x2*)(ot + o) = w; }
;             q += (x0.x * x0.x + x0.y * x0.y) + (x0.z * x0.z + x0.w * x0.w);
;             if (An) { const f32x4 y0 = x0 * (*(const gf32x4*)(gnp + c) * (*(const gf32x4*)(scp + c) + 1.0f));
;                 u32x2 w; w.x = cvt_pk_bf16(y0.x, y0.y); w.y = cvt_pk_bf16(y0.z, y0.w); *(gu32x2*)(at + o) = w; } }
;         if (stats) { q += __shfl_xor(q, 16); q += __shfl_xor(q, 32); if (fq == 0) atomic_add_f32((gf32*)((GAS char*)(stats + u.srow) + so), q); }
.LBB0_1341:
	s_or_b64 exec, exec, s[28:29]
	s_add_u32 s38, s87, s52
	s_addc_u32 s39, s88, s53
	s_add_u32 s4, s89, s52
	s_addc_u32 s5, s90, s53
	s_ashr_i32 s1, s0, 31
	s_waitcnt lgkmcnt(1)
	v_add_f32_e32 v10, v12, v13
	s_lshl_b64 s[20:21], s[0:1], 12
	global_atomic_add_f32 v[8:9], v10, off offset:512
	s_add_u32 s11, s68, s20
	v_mov_b32_e32 v9, v231
	v_mov_b32_e32 v8, v232
	s_addc_u32 s22, s69, s21
	s_add_u32 s28, s11, s14
	v_lshl_add_u32 v20, v9, 5, s84
	v_lshrrev_b32_e32 v10, 1, v20
	s_addc_u32 s29, s22, s15
	v_lshl_add_u32 v21, v8, 12, v10
	s_waitcnt lgkmcnt(0)
	global_load_dwordx2 v[14:15], v21, s[28:29]
	global_load_dwordx4 v[10:13], v20, s[38:39]
	s_add_u32 s11, s72, s20
	s_addc_u32 s20, s73, s21
	s_add_u32 s14, s11, s14
	s_addc_u32 s15, s20, s15
	v_add_u32_e32 v22, 0x100, v21
	v_cmp_eq_u32_e32 vcc, 0, v9
	s_waitcnt vmcnt(1)
	v_cvt_f32_f16_e32 v16, v14
	v_cvt_f32_f16_e32 v18, v15
	v_cvt_f32_f16_sdwa v19, v15 dst_sel:DWORD dst_unused:UNUSED_PAD src0_sel:WORD_1
	v_cvt_f32_f16_sdwa v17, v14 dst_sel:DWORD dst_unused:UNUSED_PAD src0_sel:WORD_1
	s_waitcnt vmcnt(0)
	v_pk_fma_f32 v[14:15], v[6:7], v[12:13], v[18:19]
	v_pk_fma_f32 v[16:17], v[4:5], v[10:11], v[16:17]
	v_cvt_pk_f16_f32 v5, v14, v15
	v_cvt_pk_f16_f32 v4, v16, v17
	global_store_dwordx2 v21, v[4:5], s[28:29] sc1
	global_load_dwordx4 v[4:7], v20, s[4:5]
	s_nop 0
	global_load_dwordx4 v[10:13], v20, s[12:13]
	v_add_u32_e32 v20, 0x200, v20
	s_waitcnt vmcnt(1)
	v_pk_add_f32 v[4:5], v[4:5], 1.0 op_sel_hi:[1,0]
	v_pk_add_f32 v[6:7], v[6:7], 1.0 op_sel_hi:[1,0]
	s_waitcnt vmcnt(0)
	v_pk_mul_f32 v[4:5], v[10:11], v[4:5]
	v_pk_mul_f32 v[6:7], v[12:13], v[6:7]
	v_pk_mul_f32 v[4:5], v[4:5], v[16:17]
	v_pk_mul_f32 v[6:7], v[6:7], v[14:15]
	v_cvt_pk_bf16_f32 v4, v4, v5
	s_nop 0
	v_cvt_pk_bf16_f32 v5, v6, v7
	global_store_dwordx2 v21, v[4:5], s[14:15] sc1
	global_load_dwordx2 v[10:11], v22, s[28:29]
	s_waitcnt vmcnt(0)
	v_cvt_f32_f16_e32 v12, v10
	global_load_dwordx4 v[4:7], v20, s[38:39]
	v_cvt_f32_f16_e32 v18, v11
	v_cvt_f32_f16_sdwa v19, v11 dst_sel:DWORD dst_unused:UNUSED_PAD src0_sel:WORD_1
	v_cvt_f32_f16_sdwa v13, v10 dst_sel:DWORD dst_unused:UNUSED_PAD src0_sel:WORD_1
	s_waitcnt vmcnt(0)
	v_pk_fma_f32 v[6:7], v[2:3], v[6:7], v[18:19]
	v_pk_fma_f32 v[18:19], v[0:1], v[4:5], v[12:13]
	v_cvt_pk_f16_f32 v1, v6, v7
	v_cvt_pk_f16_f32 v0, v18, v19
	global_store_dwordx2 v22, v[0:1], s[28:29] sc1
	global_load_dwordx4 v[2:5], v20, s[4:5]
	global_load_dwordx4 v[10:13], v20, s[12:13]
	v_mul_f32_e32 v0, v17, v17
	v_mul_f32_e32 v1, v15, v15
	v_fmac_f32_e32 v0, v16, v16
	v_fmac_f32_e32 v1, v14, v14
	v_add_f32_e32 v0, v0, v1
	v_mul_f32_e32 v1, v19, v19
	v_mul_f32_e32 v14, v7, v7
	v_fmac_f32_e32 v1, v18, v18
	v_fmac_f32_e32 v14, v6, v6
	v_add_f32_e32 v1, v1, v14
	v_add_f32_e32 v0, v0, v1
	ds_bpermute_b32 v1, v40, v0
	s_waitcnt lgkmcnt(0)
	v_add_f32_e32 v0, v0, v1
	ds_bpermute_b32 v1, v41, v0
	s_waitcnt vmcnt(1)
	v_pk_add_f32 v[2:3], v[2:3], 1.0 op_sel_hi:[1,0]
	v_pk_add_f32 v[4:5], v[4:5], 1.0 op_sel_hi:[1,0]
	s_waitcnt vmcnt(0)
	v_pk_mul_f32 v[2:3], v[10:11], v[2:3]
	v_pk_mul_f32 v[4:5], v[12:13], v[4:5]
	v_pk_mul_f32 v[2:3], v[2:3], v[18:19]
	v_pk_mul_f32 v[4:5], v[4:5], v[6:7]
	v_cvt_pk_bf16_f32 v2, v2, v3
	s_nop 0
	v_cvt_pk_bf16_f32 v3, v4, v5
	global_store_dwordx2 v22, v[2:3], s[14:15] sc1
	s_and_saveexec_b64 s[4:5], vcc
	s_cbranch_execz .LBB0_1343
	s_lshl_b64 s[0:1], s[0:1], 2
	v_readlane_b32 s11, v254, 50
	s_add_u32 s0, s11, s0
	v_readlane_b32 s11, v254, 52
	s_addc_u32 s1, s11, s1
	v_lshlrev_b32_e32 v2, 2, v8
	s_waitcnt lgkmcnt(0)
	v_add_f32_e32 v0, v0, v1
	global_atomic_add_f32 v2, v0, s[0:1]

; __device__ __forceinline__ float h16_lo(unsigned u) { return (float)__builtin_bit_cast(h16x2, u).x; }
; __device__ __forceinline__ float h16_hi(unsigned u) { return (float)__builtin_bit_cast(h16x2, u).y; }
; __device__ __forceinline__ unsigned cvt_pk_bf16(float lo, float hi) { unsigned r; asm volatile("v_cvt_pk_bf16_f32 %0, %1, %2" : "=v"(r) : "v"(lo), "v"(hi)); return r; }
;     __device__ __forceinline__ void operator()(const f32x4 (&acc)[2][2][4][2], const Unit& u, int wr, int wc, int fr, int fq, const PG8_LAS float*) const {
;     ...
;                 for (int m = 0; m < 4; ++m) { const unsigned o = lo + (unsigned)((ai * HALF + m * 16) * DM + bj * HALF) * 2u; bs[ai][m] = *(const gu32x4*)(bt + o); }
;             asm volatile("" ::: "memory");
; #pragma unroll
;             for (int ai = 0; ai < 2; ++ai)
; #pragma unroll
;                 for (int m = 0; m < 4; ++m) { const unsigned o = lo + (unsigned)((ai * HALF + m * 16) * DM + bj * HALF) * 2u; const u32x4 b = bs[ai][m];
;                     const f32x4 x0 = (f32x4){h16_lo(b.x), h16_hi(b.x), h16_lo(b.y), h16_hi(b.y)} + acc[ai][bj][m][0] * gv[0], x1 = (f32x4){h16_lo(b.z), h16_hi(b.z), h16_lo(b.w), h16_hi(b.w)} + acc[ai][bj][m][1] * gv[1];
;                     { u32x4 w; w.x = pk_h16(x0.x, x0.y); w.y = pk_h16(x0.z, x0.w); w.z = pk_h16(x1.x, x1.y); w.w = pk_h16(x1.z, x1.w); *(gu32x4*)(ot + o) = w; }
;                     ssq[ai][m] += (x0.x * x0.x + x0.y * x0.y) + (x0.z * x0.z + x0.w * x0.w) + (x1.x * x1.x + x1.y * x1.y) + (x1.z * x1.z + x1.w * x1.w);
;                     if (An) { const f32x4 y0 = x0 * gm[0], y1 = x1 * gm[1]; u32x4 w; w.x = cvt_pk_bf16(y0.x, y0.y); w.y = cvt_pk_bf16(y0.z, y0.w); w.z = cvt_pk_bf16(y1.x, y1.y); w.w = cvt_pk_bf16(y1.z, y1.w); *(gu32x4*)(at + o) = w; } }
.LBB0_1579:
	s_ashr_i32 s9, s8, 31
	s_lshl_b64 s[20:21], s[8:9], 20
	s_add_u32 s3, s72, s20
	s_addc_u32 s9, s73, s21
	s_add_u32 s20, s76, s20
	s_addc_u32 s21, s75, s21
	v_add_u32_e32 v199, s65, v145
	s_lshl_b64 s[52:53], s[52:53], 1
	s_add_u32 s56, s3, s52
	v_lshlrev_b32_e32 v145, 12, v199
	s_addc_u32 s57, s9, s53
	v_lshl_add_u32 v178, v144, 1, v145
	global_load_dwordx4 v[218:221], v178, s[56:57]
	v_add_u32_e32 v176, 0x10000, v178
	v_add_u32_e32 v174, 0x20000, v178
	v_add_u32_e32 v196, 0x30000, v178
	v_add_u32_e32 v194, 0x80000, v178
	v_add_u32_e32 v192, 0x90000, v178
	v_add_u32_e32 v190, 0xa0000, v178
	v_add_u32_e32 v188, 0xb0000, v178
	global_load_dwordx4 v[170:173], v176, s[56:57]
	global_load_dwordx4 v[166:169], v174, s[56:57]
	global_load_dwordx4 v[162:165], v196, s[56:57]
	global_load_dwordx4 v[156:159], v194, s[56:57]
	global_load_dwordx4 v[152:155], v192, s[56:57]
	global_load_dwordx4 v[148:151], v190, s[56:57]
	global_load_dwordx4 v[144:147], v188, s[56:57]
	s_add_u32 s54, s20, s52
	s_addc_u32 s55, s21, s53
	s_and_b64 vcc, exec, s[40:41]
	s_waitcnt vmcnt(0)
	v_cvt_f32_f16_e32 v200, v218
	v_cvt_f32_f16_sdwa v201, v218 dst_sel:DWORD dst_unused:UNUSED_PAD src0_sel:WORD_1
	v_cvt_f32_f16_e32 v218, v219
	v_cvt_f32_f16_sdwa v219, v219 dst_sel:DWORD dst_unused:UNUSED_PAD src0_sel:WORD_1
	v_pk_fma_f32 v[132:133], v[132:133], v[136:137], v[200:201]
	v_cvt_f32_f16_e32 v200, v220
	v_pk_fma_f32 v[134:135], v[134:135], v[138:139], v[218:219]
	v_cvt_f32_f16_sdwa v201, v220 dst_sel:DWORD dst_unused:UNUSED_PAD src0_sel:WORD_1
	v_cvt_f32_f16_e32 v218, v221
	v_cvt_f32_f16_sdwa v219, v221 dst_sel:DWORD dst_unused:UNUSED_PAD src0_sel:WORD_1
	v_pk_fma_f32 v[128:129], v[128:129], v[140:141], v[200:201]
	s_nop 0
	v_cvt_pk_f16_f32 v220, v128, v129
	v_pk_fma_f32 v[130:131], v[130:131], v[142:143], v[218:219]
	v_cvt_pk_f16_f32 v218, v132, v133
	v_cvt_pk_f16_f32 v219, v134, v135
	v_cvt_pk_f16_f32 v221, v130, v131
	global_store_dwordx4 v178, v[218:221], s[56:57] sc1
	s_cbranch_vccnz .LBB0_1581
	v_mov_b32_e32 v179, v161
	v_pk_mul_f32 v[200:201], v[184:185], v[134:135]
	v_pk_mul_f32 v[218:219], v[182:183], v[132:133]
	v_pk_mul_f32 v[220:221], v[180:181], v[128:129]
	v_cvt_pk_bf16_f32 v218, v218, v219
	v_cvt_pk_bf16_f32 v219, v200, v201
	v_lshl_add_u64 v[200:201], s[54:55], 0, v[178:179]
	v_pk_mul_f32 v[222:223], v[186:187], v[130:131]
	v_cvt_pk_bf16_f32 v220, v220, v221
	s_nop 0
	v_cvt_pk_bf16_f32 v221, v222, v223
	global_store_dwordx4 v[200:201], v[218:221], off sc1
.LBB0_1581:
	s_nop 1
	v_cvt_f32_f16_sdwa v219, v170 dst_sel:DWORD dst_unused:UNUSED_PAD src0_sel:WORD_1
	v_cvt_f32_f16_e32 v218, v170
	v_cvt_f32_f16_sdwa v221, v171 dst_sel:DWORD dst_unused:UNUSED_PAD src0_sel:WORD_1
	v_cvt_f32_f16_e32 v220, v171
	v_cvt_f32_f16_sdwa v171, v172 dst_sel:DWORD dst_unused:UNUSED_PAD src0_sel:WORD_1
	v_pk_fma_f32 v[124:125], v[124:125], v[136:137], v[218:219]
	v_cvt_f32_f16_e32 v170, v172
	v_cvt_f32_f16_sdwa v219, v173 dst_sel:DWORD dst_unused:UNUSED_PAD src0_sel:WORD_1
	v_cvt_f32_f16_e32 v218, v173
	v_mov_b32_e32 v177, v161
	v_pk_fma_f32 v[126:127], v[126:127], v[138:139], v[220:221]
	v_pk_fma_f32 v[120:121], v[120:121], v[140:141], v[170:171]
	v_pk_fma_f32 v[122:123], v[122:123], v[142:143], v[218:219]
	v_lshl_add_u64 v[200:201], s[56:57], 0, v[176:177]
	v_cvt_pk_f16_f32 v170, v124, v125
	v_cvt_pk_f16_f32 v171, v126, v127
	v_cvt_pk_f16_f32 v172, v120, v121
	v_cvt_pk_f16_f32 v173, v122, v123
	s_and_b64 vcc, exec, s[40:41]
	global_store_dwordx4 v[200:201], v[170:173], off sc1
	s_cbranch_vccnz .LBB0_1583
	s_nop 0
	v_pk_mul_f32 v[172:173], v[184:185], v[126:127]
	v_pk_mul_f32 v[170:171], v[182:183], v[124:125]
	v_lshl_add_u64 v[176:177], s[54:55], 0, v[176:177]
	v_pk_mul_f32 v[200:201], v[186:187], v[122:123]
	v_pk_mul_f32 v[218:219], v[180:181], v[120:121]
	v_cvt_pk_bf16_f32 v170, v170, v171
	v_cvt_pk_bf16_f32 v171, v172, v173
	s_nop 0
	v_cvt_pk_bf16_f32 v172, v218, v219
	v_cvt_pk_bf16_f32 v173, v200, v201
	global_store_dwordx4 v[176:177], v[170:173], off sc1
.LBB0_1583:
	s_nop 1
	v_cvt_f32_f16_sdwa v171, v166 dst_sel:DWORD dst_unused:UNUSED_PAD src0_sel:WORD_1
	v_cvt_f32_f16_e32 v170, v166
	v_cvt_f32_f16_sdwa v173, v167 dst_sel:DWORD dst_unused:UNUSED_PAD src0_sel:WORD_1
	v_cvt_f32_f16_e32 v172, v167
	v_mov_b32_e32 v175, v161
	v_pk_fma_f32 v[170:171], v[116:117], v[136:137], v[170:171]
	v_cvt_f32_f16_sdwa v117, v168 dst_sel:DWORD dst_unused:UNUSED_PAD src0_sel:WORD_1
	v_pk_fma_f32 v[166:167], v[118:119], v[138:139], v[172:173]
	v_cvt_f32_f16_e32 v116, v168
	v_cvt_f32_f16_sdwa v119, v169 dst_sel:DWORD dst_unused:UNUSED_PAD src0_sel:WORD_1
	v_cvt_f32_f16_e32 v118, v169
	v_lshl_add_u64 v[176:177], s[56:57], 0, v[174:175]
	v_pk_fma_f32 v[172:173], v[112:113], v[140:141], v[116:117]
	v_cvt_pk_f16_f32 v112, v170, v171
	v_pk_fma_f32 v[168:169], v[114:115], v[142:143], v[118:119]
	v_cvt_pk_f16_f32 v113, v166, v167
	v_cvt_pk_f16_f32 v114, v172, v173
	v_cvt_pk_f16_f32 v115, v168, v169
	s_and_b64 vcc, exec, s[40:41]
	global_store_dwordx4 v[176:177], v[112:115], off sc1
	s_cbranch_vccnz .LBB0_1585
	s_nop 0
	v_pk_mul_f32 v[114:115], v[184:185], v[166:167]
	v_pk_mul_f32 v[112:113], v[182:183], v[170:171]
	v_pk_mul_f32 v[116:117], v[186:187], v[168:169]
	v_pk_mul_f32 v[118:119], v[180:181], v[172:173]
	v_cvt_pk_bf16_f32 v112, v112, v113
	v_cvt_pk_bf16_f32 v113, v114, v115
	s_nop 0
	v_cvt_pk_bf16_f32 v114, v118, v119
	v_cvt_pk_bf16_f32 v115, v116, v117
	v_lshl_add_u64 v[116:117], s[54:55], 0, v[174:175]
	global_store_dwordx4 v[116:117], v[112:115], off sc1
; __device__ __forceinline__ float h16_lo(unsigned u) { return (float)__builtin_bit_cast(h16x2, u).x; }
; __device__ __forceinline__ float h16_hi(unsigned u) { return (float)__builtin_bit_cast(h16x2, u).y; }
; __device__ __forceinline__ unsigned cvt_pk_bf16(float lo, float hi) { unsigned r; asm volatile("v_cvt_pk_bf16_f32 %0, %1, %2" : "=v"(r) : "v"(lo), "v"(hi)); return r; }
;     __device__ __forceinline__ void operator()(const f32x4 (&acc)[2][2][4][2], const Unit& u, int wr, int wc, int fr, int fq, const PG8_LAS float*) const {
;     ...
;                 for (int m = 0; m < 4; ++m) { const unsigned o = lo + (unsigned)((ai * HALF + m * 16) * DM + bj * HALF) * 2u; const u32x4 b = bs[ai][m];
;                     const f32x4 x0 = (f32x4){h16_lo(b.x), h16_hi(b.x), h16_lo(b.y), h16_hi(b.y)} + acc[ai][bj][m][0] * gv[0], x1 = (f32x4){h16_lo(b.z), h16_hi(b.z), h16_lo(b.w), h16_hi(b.w)} + acc[ai][bj][m][1] * gv[1];
;                     { u32x4 w; w.x = pk_h16(x0.x, x0.y); w.y = pk_h16(x0.z, x0.w); w.z = pk_h16(x1.x, x1.y); w.w = pk_h16(x1.z, x1.w); *(gu32x4*)(ot + o) = w; }
;                     ssq[ai][m] += (x0.x * x0.x + x0.y * x0.y) + (x0.z * x0.z + x0.w * x0.w) + (x1.x * x1.x + x1.y * x1.y) + (x1.z * x1.z + x1.w * x1.w);
;                     if (An) { const f32x4 y0 = x0 * gm[0], y1 = x1 * gm[1]; u32x4 w; w.x = cvt_pk_bf16(y0.x, y0.y); w.y = cvt_pk_bf16(y0.z, y0.w); w.z = cvt_pk_bf16(y1.x, y1.y); w.w = cvt_pk_bf16(y1.z, y1.w); *(gu32x4*)(at + o) = w; } }
.LBB0_1585:
	s_nop 1
	v_cvt_f32_f16_sdwa v115, v162 dst_sel:DWORD dst_unused:UNUSED_PAD src0_sel:WORD_1
	v_cvt_f32_f16_e32 v114, v162
	v_cvt_f32_f16_sdwa v117, v163 dst_sel:DWORD dst_unused:UNUSED_PAD src0_sel:WORD_1
	v_cvt_f32_f16_e32 v116, v163
	v_mov_b32_e32 v197, v161
	v_pk_fma_f32 v[174:175], v[108:109], v[136:137], v[114:115]
	v_cvt_f32_f16_sdwa v109, v164 dst_sel:DWORD dst_unused:UNUSED_PAD src0_sel:WORD_1
	v_pk_fma_f32 v[162:163], v[110:111], v[138:139], v[116:117]
	v_cvt_f32_f16_e32 v108, v164
	v_cvt_f32_f16_sdwa v111, v165 dst_sel:DWORD dst_unused:UNUSED_PAD src0_sel:WORD_1
	v_cvt_f32_f16_e32 v110, v165
	v_lshl_add_u64 v[112:113], s[56:57], 0, v[196:197]
	v_pk_fma_f32 v[176:177], v[104:105], v[140:141], v[108:109]
	v_cvt_pk_f16_f32 v104, v174, v175
	v_pk_fma_f32 v[164:165], v[106:107], v[142:143], v[110:111]
	v_cvt_pk_f16_f32 v105, v162, v163
	v_cvt_pk_f16_f32 v106, v176, v177
	v_cvt_pk_f16_f32 v107, v164, v165
	s_and_b64 vcc, exec, s[40:41]
	global_store_dwordx4 v[112:113], v[104:107], off sc1
	s_cbranch_vccnz .LBB0_1587
	s_nop 0
	v_pk_mul_f32 v[106:107], v[184:185], v[162:163]
	v_pk_mul_f32 v[104:105], v[182:183], v[174:175]
	v_pk_mul_f32 v[108:109], v[186:187], v[164:165]
	v_pk_mul_f32 v[110:111], v[180:181], v[176:177]
	v_cvt_pk_bf16_f32 v104, v104, v105
	v_cvt_pk_bf16_f32 v105, v106, v107
	s_nop 0
	v_cvt_pk_bf16_f32 v106, v110, v111
	v_cvt_pk_bf16_f32 v107, v108, v109
	v_lshl_add_u64 v[108:109], s[54:55], 0, v[196:197]
	global_store_dwordx4 v[108:109], v[104:107], off sc1
.LBB0_1587:
	s_nop 1
	v_cvt_f32_f16_sdwa v107, v156 dst_sel:DWORD dst_unused:UNUSED_PAD src0_sel:WORD_1
	v_cvt_f32_f16_e32 v106, v156
	v_cvt_f32_f16_sdwa v109, v157 dst_sel:DWORD dst_unused:UNUSED_PAD src0_sel:WORD_1
	v_cvt_f32_f16_e32 v108, v157
	v_mov_b32_e32 v195, v161
	v_pk_fma_f32 v[110:111], v[100:101], v[136:137], v[106:107]
	v_cvt_f32_f16_sdwa v101, v158 dst_sel:DWORD dst_unused:UNUSED_PAD src0_sel:WORD_1
	v_pk_fma_f32 v[108:109], v[102:103], v[138:139], v[108:109]
	v_cvt_f32_f16_e32 v100, v158
	v_cvt_f32_f16_sdwa v103, v159 dst_sel:DWORD dst_unused:UNUSED_PAD src0_sel:WORD_1
	v_cvt_f32_f16_e32 v102, v159
	v_lshl_add_u64 v[104:105], s[56:57], 0, v[194:195]
	v_pk_fma_f32 v[114:115], v[96:97], v[140:141], v[100:101]
	v_cvt_pk_f16_f32 v96, v110, v111
	v_pk_fma_f32 v[112:113], v[98:99], v[142:143], v[102:103]
	v_cvt_pk_f16_f32 v97, v108, v109
	v_cvt_pk_f16_f32 v98, v114, v115
	v_cvt_pk_f16_f32 v99, v112, v113
	s_and_b64 vcc, exec, s[40:41]
	global_store_dwordx4 v[104:105], v[96:99], off sc1
	s_cbranch_vccnz .LBB0_1589
	s_nop 0
	v_pk_mul_f32 v[98:99], v[184:185], v[108:109]
	v_pk_mul_f32 v[96:97], v[182:183], v[110:111]
	v_pk_mul_f32 v[100:101], v[186:187], v[112:113]
	v_pk_mul_f32 v[102:103], v[180:181], v[114:115]
	v_cvt_pk_bf16_f32 v96, v96, v97
	v_cvt_pk_bf16_f32 v97, v98, v99
	s_nop 0
	v_cvt_pk_bf16_f32 v98, v102, v103
	v_cvt_pk_bf16_f32 v99, v100, v101
	v_lshl_add_u64 v[100:101], s[54:55], 0, v[194:195]
	global_store_dwordx4 v[100:101], v[96:99], off sc1
; __device__ __forceinline__ float h16_lo(unsigned u) { return (float)__builtin_bit_cast(h16x2, u).x; }
; __device__ __forceinline__ float h16_hi(unsigned u) { return (float)__builtin_bit_cast(h16x2, u).y; }
; __device__ __forceinline__ unsigned cvt_pk_bf16(float lo, float hi) { unsigned r; asm volatile("v_cvt_pk_bf16_f32 %0, %1, %2" : "=v"(r) : "v"(lo), "v"(hi)); return r; }
;     __device__ __forceinline__ void operator()(const f32x4 (&acc)[2][2][4][2], const Unit& u, int wr, int wc, int fr, int fq, const PG8_LAS float*) const {
;     ...
;                 for (int m = 0; m < 4; ++m) { const unsigned o = lo + (unsigned)((ai * HALF + m * 16) * DM + bj * HALF) * 2u; const u32x4 b = bs[ai][m];
;                     const f32x4 x0 = (f32x4){h16_lo(b.x), h16_hi(b.x), h16_lo(b.y), h16_hi(b.y)} + acc[ai][bj][m][0] * gv[0], x1 = (f32x4){h16_lo(b.z), h16_hi(b.z), h16_lo(b.w), h16_hi(b.w)} + acc[ai][bj][m][1] * gv[1];
;                     { u32x4 w; w.x = pk_h16(x0.x, x0.y); w.y = pk_h16(x0.z, x0.w); w.z = pk_h16(x1.x, x1.y); w.w = pk_h16(x1.z, x1.w); *(gu32x4*)(ot + o) = w; }
;                     ssq[ai][m] += (x0.x * x0.x + x0.y * x0.y) + (x0.z * x0.z + x0.w * x0.w) + (x1.x * x1.x + x1.y * x1.y) + (x1.z * x1.z + x1.w * x1.w);
;                     if (An) { const f32x4 y0 = x0 * gm[0], y1 = x1 * gm[1]; u32x4 w; w.x = cvt_pk_bf16(y0.x, y0.y); w.y = cvt_pk_bf16(y0.z, y0.w); w.z = cvt_pk_bf16(y1.x, y1.y); w.w = cvt_pk_bf16(y1.z, y1.w); *(gu32x4*)(at + o) = w; } }
.LBB0_1589:
	s_nop 1
	v_cvt_f32_f16_sdwa v99, v152 dst_sel:DWORD dst_unused:UNUSED_PAD src0_sel:WORD_1
	v_cvt_f32_f16_e32 v98, v152
	v_cvt_f32_f16_sdwa v101, v153 dst_sel:DWORD dst_unused:UNUSED_PAD src0_sel:WORD_1
	v_cvt_f32_f16_e32 v100, v153
	v_mov_b32_e32 v193, v161
	v_pk_fma_f32 v[118:119], v[92:93], v[136:137], v[98:99]
	v_cvt_f32_f16_sdwa v93, v154 dst_sel:DWORD dst_unused:UNUSED_PAD src0_sel:WORD_1
	v_pk_fma_f32 v[116:117], v[94:95], v[138:139], v[100:101]
	v_cvt_f32_f16_e32 v92, v154
	v_cvt_f32_f16_sdwa v95, v155 dst_sel:DWORD dst_unused:UNUSED_PAD src0_sel:WORD_1
	v_cvt_f32_f16_e32 v94, v155
	v_lshl_add_u64 v[96:97], s[56:57], 0, v[192:193]
	v_pk_fma_f32 v[154:155], v[88:89], v[140:141], v[92:93]
	v_cvt_pk_f16_f32 v88, v118, v119
	v_pk_fma_f32 v[152:153], v[90:91], v[142:143], v[94:95]
	v_cvt_pk_f16_f32 v89, v116, v117
	v_cvt_pk_f16_f32 v90, v154, v155
	v_cvt_pk_f16_f32 v91, v152, v153
	s_and_b64 vcc, exec, s[40:41]
	global_store_dwordx4 v[96:97], v[88:91], off sc1
	s_cbranch_vccnz .LBB0_1591
	s_nop 0
	v_pk_mul_f32 v[90:91], v[184:185], v[116:117]
	v_pk_mul_f32 v[88:89], v[182:183], v[118:119]
	v_pk_mul_f32 v[92:93], v[186:187], v[152:153]
	v_pk_mul_f32 v[94:95], v[180:181], v[154:155]
	v_cvt_pk_bf16_f32 v88, v88, v89
	v_cvt_pk_bf16_f32 v89, v90, v91
	s_nop 0
	v_cvt_pk_bf16_f32 v90, v94, v95
	v_cvt_pk_bf16_f32 v91, v92, v93
	v_lshl_add_u64 v[92:93], s[54:55], 0, v[192:193]
	global_store_dwordx4 v[92:93], v[88:91], off sc1
.LBB0_1591:
	s_nop 1
	v_cvt_f32_f16_sdwa v91, v148 dst_sel:DWORD dst_unused:UNUSED_PAD src0_sel:WORD_1
	v_cvt_f32_f16_e32 v90, v148
	v_cvt_f32_f16_sdwa v93, v149 dst_sel:DWORD dst_unused:UNUSED_PAD src0_sel:WORD_1
	v_cvt_f32_f16_e32 v92, v149
	v_mov_b32_e32 v191, v161
	v_pk_fma_f32 v[158:159], v[84:85], v[136:137], v[90:91]
	v_cvt_f32_f16_sdwa v85, v150 dst_sel:DWORD dst_unused:UNUSED_PAD src0_sel:WORD_1
	v_pk_fma_f32 v[156:157], v[86:87], v[138:139], v[92:93]
	v_cvt_f32_f16_e32 v84, v150
	v_cvt_f32_f16_sdwa v87, v151 dst_sel:DWORD dst_unused:UNUSED_PAD src0_sel:WORD_1
	v_cvt_f32_f16_e32 v86, v151
	v_lshl_add_u64 v[88:89], s[56:57], 0, v[190:191]
	v_pk_fma_f32 v[150:151], v[80:81], v[140:141], v[84:85]
	v_cvt_pk_f16_f32 v80, v158, v159
	v_pk_fma_f32 v[148:149], v[82:83], v[142:143], v[86:87]
	v_cvt_pk_f16_f32 v81, v156, v157
	v_cvt_pk_f16_f32 v82, v150, v151
	v_cvt_pk_f16_f32 v83, v148, v149
	s_and_b64 vcc, exec, s[40:41]
	global_store_dwordx4 v[88:89], v[80:83], off sc1
	s_cbranch_vccnz .LBB0_1593
	s_nop 0
	v_pk_mul_f32 v[82:83], v[184:185], v[156:157]
	v_pk_mul_f32 v[80:81], v[182:183], v[158:159]
	v_pk_mul_f32 v[84:85], v[186:187], v[148:149]
	v_pk_mul_f32 v[86:87], v[180:181], v[150:151]
	v_cvt_pk_bf16_f32 v80, v80, v81
	v_cvt_pk_bf16_f32 v81, v82, v83
	s_nop 0
	v_cvt_pk_bf16_f32 v82, v86, v87
	v_cvt_pk_bf16_f32 v83, v84, v85
	v_lshl_add_u64 v[84:85], s[54:55], 0, v[190:191]
	global_store_dwordx4 v[84:85], v[80:83], off sc1
.LBB0_1593:
	s_nop 1
	v_cvt_f32_f16_sdwa v83, v144 dst_sel:DWORD dst_unused:UNUSED_PAD src0_sel:WORD_1
	v_cvt_f32_f16_e32 v82, v144
	v_cvt_f32_f16_sdwa v85, v145 dst_sel:DWORD dst_unused:UNUSED_PAD src0_sel:WORD_1
	v_cvt_f32_f16_e32 v84, v145
	v_mov_b32_e32 v189, v161
	v_pk_fma_f32 v[136:137], v[76:77], v[136:137], v[82:83]
	v_cvt_f32_f16_sdwa v77, v146 dst_sel:DWORD dst_unused:UNUSED_PAD src0_sel:WORD_1
	v_pk_fma_f32 v[138:139], v[78:79], v[138:139], v[84:85]
	v_cvt_f32_f16_e32 v76, v146
	v_cvt_f32_f16_sdwa v79, v147 dst_sel:DWORD dst_unused:UNUSED_PAD src0_sel:WORD_1
	v_cvt_f32_f16_e32 v78, v147
	v_lshl_add_u64 v[80:81], s[56:57], 0, v[188:189]
	v_pk_fma_f32 v[140:141], v[72:73], v[140:141], v[76:77]
	v_cvt_pk_f16_f32 v72, v136, v137
	v_pk_fma_f32 v[142:143], v[74:75], v[142:143], v[78:79]
	v_cvt_pk_f16_f32 v73, v138, v139
	v_cvt_pk_f16_f32 v74, v140, v141
	v_cvt_pk_f16_f32 v75, v142, v143
	s_and_b64 vcc, exec, s[40:41]
	global_store_dwordx4 v[80:81], v[72:75], off sc1
	s_cbranch_vccnz .LBB0_1595
	s_nop 0
	v_pk_mul_f32 v[74:75], v[184:185], v[138:139]
	v_pk_mul_f32 v[72:73], v[182:183], v[136:137]
	v_pk_mul_f32 v[76:77], v[186:187], v[142:143]
	v_pk_mul_f32 v[78:79], v[180:181], v[140:141]
	v_cvt_pk_bf16_f32 v72, v72, v73
	v_cvt_pk_bf16_f32 v73, v74, v75
	s_nop 0
	v_cvt_pk_bf16_f32 v74, v78, v79
	v_cvt_pk_bf16_f32 v75, v76, v77
	v_lshl_add_u64 v[76:77], s[54:55], 0, v[188:189]
	global_store_dwordx4 v[76:77], v[72:75], off sc1

; __device__ __forceinline__ float h16_lo(unsigned u) { return (float)__builtin_bit_cast(h16x2, u).x; }
; __device__ __forceinline__ float h16_hi(unsigned u) { return (float)__builtin_bit_cast(h16x2, u).y; }
; __device__ __forceinline__ unsigned cvt_pk_bf16(float lo, float hi) { unsigned r; asm volatile("v_cvt_pk_bf16_f32 %0, %1, %2" : "=v"(r) : "v"(lo), "v"(hi)); return r; }
;     __device__ __forceinline__ void operator()(const f32x4 (&acc)[2][2][4][2], const Unit& u, int wr, int wc, int fr, int fq, const PG8_LAS float*) const {
;     ...
;                 for (int m = 0; m < 4; ++m) { const unsigned o = lo + (unsigned)((ai * HALF + m * 16) * DM + bj * HALF) * 2u; bs[ai][m] = *(const gu32x4*)(bt + o); }
;             asm volatile("" ::: "memory");
; #pragma unroll
;             for (int ai = 0; ai < 2; ++ai)
; #pragma unroll
;                 for (int m = 0; m < 4; ++m) { const unsigned o = lo + (unsigned)((ai * HALF + m * 16) * DM + bj * HALF) * 2u; const u32x4 b = bs[ai][m];
;                     const f32x4 x0 = (f32x4){h16_lo(b.x), h16_hi(b.x), h16_lo(b.y), h16_hi(b.y)} + acc[ai][bj][m][0] * gv[0], x1 = (f32x4){h16_lo(b.z), h16_hi(b.z), h16_lo(b.w), h16_hi(b.w)} + acc[ai][bj][m][1] * gv[1];
;                     { u32x4 w; w.x = pk_h16(x0.x, x0.y); w.y = pk_h16(x0.z, x0.w); w.z = pk_h16(x1.x, x1.y); w.w = pk_h16(x1.z, x1.w); *(gu32x4*)(ot + o) = w; }
;                     ssq[ai][m] += (x0.x * x0.x + x0.y * x0.y) + (x0.z * x0.z + x0.w * x0.w) + (x1.x * x1.x + x1.y * x1.y) + (x1.z * x1.z + x1.w * x1.w);
;                     if (An) { const f32x4 y0 = x0 * gm[0], y1 = x1 * gm[1]; u32x4 w; w.x = cvt_pk_bf16(y0.x, y0.y); w.y = cvt_pk_bf16(y0.z, y0.w); w.z = cvt_pk_bf16(y1.x, y1.y); w.w = cvt_pk_bf16(y1.z, y1.w); *(gu32x4*)(at + o) = w; } }
.LBB0_1599:
	v_add_u32_e32 v194, 0x100, v178
	global_load_dwordx4 v[218:221], v194, s[56:57]
	v_add_u32_e32 v160, 0x10100, v178
	v_add_u32_e32 v192, 0x20100, v178
	v_add_u32_e32 v190, 0x30100, v178
	v_add_u32_e32 v188, 0x80100, v178
	v_add_u32_e32 v186, 0x90100, v178
	v_add_u32_e32 v184, 0xa0100, v178
	v_add_u32_e32 v178, 0xb0100, v178
	global_load_dwordx4 v[104:107], v160, s[56:57]
	global_load_dwordx4 v[80:83], v178, s[56:57]
	global_load_dwordx4 v[100:103], v192, s[56:57]
	global_load_dwordx4 v[96:99], v190, s[56:57]
	global_load_dwordx4 v[92:95], v188, s[56:57]
	global_load_dwordx4 v[88:91], v186, s[56:57]
	global_load_dwordx4 v[84:87], v184, s[56:57]
	s_and_b64 vcc, exec, s[40:41]
	s_waitcnt vmcnt(7)
	v_cvt_f32_f16_e32 v196, v218
	v_cvt_f32_f16_sdwa v197, v218 dst_sel:DWORD dst_unused:UNUSED_PAD src0_sel:WORD_1
	v_cvt_f32_f16_e32 v200, v219
	v_cvt_f32_f16_sdwa v201, v219 dst_sel:DWORD dst_unused:UNUSED_PAD src0_sel:WORD_1
	v_pk_fma_f32 v[68:69], v[68:69], v[72:73], v[196:197]
	v_cvt_f32_f16_e32 v196, v220
	v_pk_fma_f32 v[70:71], v[70:71], v[74:75], v[200:201]
	v_cvt_f32_f16_sdwa v197, v220 dst_sel:DWORD dst_unused:UNUSED_PAD src0_sel:WORD_1
	v_cvt_f32_f16_e32 v200, v221
	v_cvt_f32_f16_sdwa v201, v221 dst_sel:DWORD dst_unused:UNUSED_PAD src0_sel:WORD_1
	v_cvt_pk_f16_f32 v218, v68, v69
	v_pk_fma_f32 v[64:65], v[64:65], v[76:77], v[196:197]
	v_cvt_pk_f16_f32 v219, v70, v71
	v_pk_fma_f32 v[66:67], v[66:67], v[78:79], v[200:201]
	v_cvt_pk_f16_f32 v220, v64, v65
	v_cvt_pk_f16_f32 v221, v66, v67
	global_store_dwordx4 v194, v[218:221], s[56:57] sc1
	s_cbranch_vccnz .LBB0_1601
	v_mov_b32_e32 v195, v161
	v_pk_mul_f32 v[220:221], v[144:145], v[64:65]
	v_lshl_add_u64 v[194:195], s[54:55], 0, v[194:195]
	v_pk_mul_f32 v[196:197], v[180:181], v[70:71]
	v_pk_mul_f32 v[200:201], v[146:147], v[68:69]
	v_pk_mul_f32 v[222:223], v[182:183], v[66:67]
	v_cvt_pk_bf16_f32 v218, v200, v201
	v_cvt_pk_bf16_f32 v219, v196, v197
	v_cvt_pk_bf16_f32 v220, v220, v221
	s_nop 0
	v_cvt_pk_bf16_f32 v221, v222, v223
	global_store_dwordx4 v[194:195], v[218:221], off sc1
.LBB0_1601:
	s_waitcnt vmcnt(7)
	v_cvt_f32_f16_sdwa v197, v104 dst_sel:DWORD dst_unused:UNUSED_PAD src0_sel:WORD_1
	v_cvt_f32_f16_e32 v196, v104
	v_cvt_f32_f16_sdwa v201, v105 dst_sel:DWORD dst_unused:UNUSED_PAD src0_sel:WORD_1
	v_cvt_f32_f16_e32 v200, v105
	v_cvt_f32_f16_sdwa v105, v106 dst_sel:DWORD dst_unused:UNUSED_PAD src0_sel:WORD_1
	v_pk_fma_f32 v[60:61], v[60:61], v[72:73], v[196:197]
	v_cvt_f32_f16_e32 v104, v106
	v_cvt_f32_f16_sdwa v197, v107 dst_sel:DWORD dst_unused:UNUSED_PAD src0_sel:WORD_1
	v_cvt_f32_f16_e32 v196, v107
	v_pk_fma_f32 v[62:63], v[62:63], v[74:75], v[200:201]
	v_pk_fma_f32 v[56:57], v[56:57], v[76:77], v[104:105]
	v_lshl_add_u64 v[194:195], s[56:57], 0, v[160:161]
	v_pk_fma_f32 v[58:59], v[58:59], v[78:79], v[196:197]
	v_cvt_pk_f16_f32 v104, v60, v61
	v_cvt_pk_f16_f32 v105, v62, v63
	v_cvt_pk_f16_f32 v106, v56, v57
	v_cvt_pk_f16_f32 v107, v58, v59
	s_and_b64 vcc, exec, s[40:41]
	global_store_dwordx4 v[194:195], v[104:107], off sc1
	s_cbranch_vccnz .LBB0_1603
	s_nop 0
	v_pk_mul_f32 v[106:107], v[180:181], v[62:63]
	v_pk_mul_f32 v[104:105], v[146:147], v[60:61]
	v_pk_mul_f32 v[194:195], v[182:183], v[58:59]
	v_pk_mul_f32 v[196:197], v[144:145], v[56:57]
	v_cvt_pk_bf16_f32 v104, v104, v105
	v_cvt_pk_bf16_f32 v105, v106, v107
	s_nop 0
	v_cvt_pk_bf16_f32 v106, v196, v197
	v_cvt_pk_bf16_f32 v107, v194, v195
	v_lshl_add_u64 v[194:195], s[54:55], 0, v[160:161]
	global_store_dwordx4 v[194:195], v[104:107], off sc1
.LBB0_1603:
	s_waitcnt vmcnt(6)
	s_nop 0
	v_cvt_f32_f16_sdwa v107, v100 dst_sel:DWORD dst_unused:UNUSED_PAD src0_sel:WORD_1
	v_cvt_f32_f16_e32 v106, v100
	v_cvt_f32_f16_sdwa v195, v101 dst_sel:DWORD dst_unused:UNUSED_PAD src0_sel:WORD_1
	v_cvt_f32_f16_e32 v194, v101
	v_cvt_f32_f16_sdwa v101, v102 dst_sel:DWORD dst_unused:UNUSED_PAD src0_sel:WORD_1
	v_pk_fma_f32 v[52:53], v[52:53], v[72:73], v[106:107]
	v_cvt_f32_f16_e32 v100, v102
	v_cvt_f32_f16_sdwa v107, v103 dst_sel:DWORD dst_unused:UNUSED_PAD src0_sel:WORD_1
	v_cvt_f32_f16_e32 v106, v103
	v_mov_b32_e32 v193, v161
	v_pk_fma_f32 v[54:55], v[54:55], v[74:75], v[194:195]
	v_pk_fma_f32 v[48:49], v[48:49], v[76:77], v[100:101]
	v_pk_fma_f32 v[50:51], v[50:51], v[78:79], v[106:107]
	v_lshl_add_u64 v[104:105], s[56:57], 0, v[192:193]
	v_cvt_pk_f16_f32 v100, v52, v53
	v_cvt_pk_f16_f32 v101, v54, v55
	v_cvt_pk_f16_f32 v102, v48, v49
	v_cvt_pk_f16_f32 v103, v50, v51
	s_and_b64 vcc, exec, s[40:41]
	global_store_dwordx4 v[104:105], v[100:103], off sc1
	s_cbranch_vccnz .LBB0_1605
	s_nop 0
	v_pk_mul_f32 v[102:103], v[180:181], v[54:55]
	v_pk_mul_f32 v[100:101], v[146:147], v[52:53]
	v_pk_mul_f32 v[104:105], v[182:183], v[50:51]
	v_pk_mul_f32 v[106:107], v[144:145], v[48:49]
	v_cvt_pk_bf16_f32 v100, v100, v101
	v_cvt_pk_bf16_f32 v101, v102, v103
	s_nop 0
	v_cvt_pk_bf16_f32 v102, v106, v107
	v_cvt_pk_bf16_f32 v103, v104, v105
	v_lshl_add_u64 v[104:105], s[54:55], 0, v[192:193]
	global_store_dwordx4 v[104:105], v[100:103], off sc1
; __device__ __forceinline__ float h16_lo(unsigned u) { return (float)__builtin_bit_cast(h16x2, u).x; }
; __device__ __forceinline__ float h16_hi(unsigned u) { return (float)__builtin_bit_cast(h16x2, u).y; }
; __device__ __forceinline__ unsigned cvt_pk_bf16(float lo, float hi) { unsigned r; asm volatile("v_cvt_pk_bf16_f32 %0, %1, %2" : "=v"(r) : "v"(lo), "v"(hi)); return r; }
;     __device__ __forceinline__ void operator()(const f32x4 (&acc)[2][2][4][2], const Unit& u, int wr, int wc, int fr, int fq, const PG8_LAS float*) const {
;     ...
;                 for (int m = 0; m < 4; ++m) { const unsigned o = lo + (unsigned)((ai * HALF + m * 16) * DM + bj * HALF) * 2u; const u32x4 b = bs[ai][m];
;                     const f32x4 x0 = (f32x4){h16_lo(b.x), h16_hi(b.x), h16_lo(b.y), h16_hi(b.y)} + acc[ai][bj][m][0] * gv[0], x1 = (f32x4){h16_lo(b.z), h16_hi(b.z), h16_lo(b.w), h16_hi(b.w)} + acc[ai][bj][m][1] * gv[1];
;                     { u32x4 w; w.x = pk_h16(x0.x, x0.y); w.y = pk_h16(x0.z, x0.w); w.z = pk_h16(x1.x, x1.y); w.w = pk_h16(x1.z, x1.w); *(gu32x4*)(ot + o) = w; }
;                     ssq[ai][m] += (x0.x * x0.x + x0.y * x0.y) + (x0.z * x0.z + x0.w * x0.w) + (x1.x * x1.x + x1.y * x1.y) + (x1.z * x1.z + x1.w * x1.w);
;                     if (An) { const f32x4 y0 = x0 * gm[0], y1 = x1 * gm[1]; u32x4 w; w.x = cvt_pk_bf16(y0.x, y0.y); w.y = cvt_pk_bf16(y0.z, y0.w); w.z = cvt_pk_bf16(y1.x, y1.y); w.w = cvt_pk_bf16(y1.z, y1.w); *(gu32x4*)(at + o) = w; } }
.LBB0_1605:
	s_waitcnt vmcnt(6)
	s_nop 0
	v_cvt_f32_f16_sdwa v103, v96 dst_sel:DWORD dst_unused:UNUSED_PAD src0_sel:WORD_1
	v_cvt_f32_f16_e32 v102, v96
	v_cvt_f32_f16_sdwa v105, v97 dst_sel:DWORD dst_unused:UNUSED_PAD src0_sel:WORD_1
	v_cvt_f32_f16_e32 v104, v97
	v_cvt_f32_f16_sdwa v97, v98 dst_sel:DWORD dst_unused:UNUSED_PAD src0_sel:WORD_1
	v_pk_fma_f32 v[44:45], v[44:45], v[72:73], v[102:103]
	v_cvt_f32_f16_e32 v96, v98
	v_cvt_f32_f16_sdwa v103, v99 dst_sel:DWORD dst_unused:UNUSED_PAD src0_sel:WORD_1
	v_cvt_f32_f16_e32 v102, v99
	v_mov_b32_e32 v191, v161
	v_pk_fma_f32 v[46:47], v[46:47], v[74:75], v[104:105]
	v_pk_fma_f32 v[40:41], v[40:41], v[76:77], v[96:97]
	v_pk_fma_f32 v[42:43], v[42:43], v[78:79], v[102:103]
	v_lshl_add_u64 v[100:101], s[56:57], 0, v[190:191]
	v_cvt_pk_f16_f32 v96, v44, v45
	v_cvt_pk_f16_f32 v97, v46, v47
	v_cvt_pk_f16_f32 v98, v40, v41
	v_cvt_pk_f16_f32 v99, v42, v43
	s_and_b64 vcc, exec, s[40:41]
	global_store_dwordx4 v[100:101], v[96:99], off sc1
	s_cbranch_vccnz .LBB0_1607
	s_nop 0
	v_pk_mul_f32 v[98:99], v[180:181], v[46:47]
	v_pk_mul_f32 v[96:97], v[146:147], v[44:45]
	v_pk_mul_f32 v[100:101], v[182:183], v[42:43]
	v_pk_mul_f32 v[102:103], v[144:145], v[40:41]
	v_cvt_pk_bf16_f32 v96, v96, v97
	v_cvt_pk_bf16_f32 v97, v98, v99
	s_nop 0
	v_cvt_pk_bf16_f32 v98, v102, v103
	v_cvt_pk_bf16_f32 v99, v100, v101
	v_lshl_add_u64 v[100:101], s[54:55], 0, v[190:191]
	global_store_dwordx4 v[100:101], v[96:99], off sc1
.LBB0_1607:
	s_waitcnt vmcnt(6)
	s_nop 0
	v_cvt_f32_f16_sdwa v99, v92 dst_sel:DWORD dst_unused:UNUSED_PAD src0_sel:WORD_1
	v_cvt_f32_f16_e32 v98, v92
	v_cvt_f32_f16_sdwa v101, v93 dst_sel:DWORD dst_unused:UNUSED_PAD src0_sel:WORD_1
	v_cvt_f32_f16_e32 v100, v93
	v_cvt_f32_f16_sdwa v93, v94 dst_sel:DWORD dst_unused:UNUSED_PAD src0_sel:WORD_1
	v_pk_fma_f32 v[36:37], v[36:37], v[72:73], v[98:99]
	v_cvt_f32_f16_e32 v92, v94
	v_cvt_f32_f16_sdwa v99, v95 dst_sel:DWORD dst_unused:UNUSED_PAD src0_sel:WORD_1
	v_cvt_f32_f16_e32 v98, v95
	v_mov_b32_e32 v189, v161
	v_pk_fma_f32 v[38:39], v[38:39], v[74:75], v[100:101]
	v_pk_fma_f32 v[32:33], v[32:33], v[76:77], v[92:93]
	v_pk_fma_f32 v[34:35], v[34:35], v[78:79], v[98:99]
	v_lshl_add_u64 v[96:97], s[56:57], 0, v[188:189]
	v_cvt_pk_f16_f32 v92, v36, v37
	v_cvt_pk_f16_f32 v93, v38, v39
	v_cvt_pk_f16_f32 v94, v32, v33
	v_cvt_pk_f16_f32 v95, v34, v35
	s_and_b64 vcc, exec, s[40:41]
	global_store_dwordx4 v[96:97], v[92:95], off sc1
	s_cbranch_vccnz .LBB0_1609
	s_nop 0
	v_pk_mul_f32 v[94:95], v[180:181], v[38:39]
	v_pk_mul_f32 v[92:93], v[146:147], v[36:37]
	v_pk_mul_f32 v[96:97], v[182:183], v[34:35]
	v_pk_mul_f32 v[98:99], v[144:145], v[32:33]
	v_cvt_pk_bf16_f32 v92, v92, v93
	v_cvt_pk_bf16_f32 v93, v94, v95
	s_nop 0
	v_cvt_pk_bf16_f32 v94, v98, v99
	v_cvt_pk_bf16_f32 v95, v96, v97
	v_lshl_add_u64 v[96:97], s[54:55], 0, v[188:189]
	global_store_dwordx4 v[96:97], v[92:95], off sc1
; __device__ __forceinline__ float h16_lo(unsigned u) { return (float)__builtin_bit_cast(h16x2, u).x; }
; __device__ __forceinline__ float h16_hi(unsigned u) { return (float)__builtin_bit_cast(h16x2, u).y; }
; __device__ __forceinline__ unsigned cvt_pk_bf16(float lo, float hi) { unsigned r; asm volatile("v_cvt_pk_bf16_f32 %0, %1, %2" : "=v"(r) : "v"(lo), "v"(hi)); return r; }
;     __device__ __forceinline__ void operator()(const f32x4 (&acc)[2][2][4][2], const Unit& u, int wr, int wc, int fr, int fq, const PG8_LAS float*) const {
;     ...
;                 for (int m = 0; m < 4; ++m) { const unsigned o = lo + (unsigned)((ai * HALF + m * 16) * DM + bj * HALF) * 2u; const u32x4 b = bs[ai][m];
;                     const f32x4 x0 = (f32x4){h16_lo(b.x), h16_hi(b.x), h16_lo(b.y), h16_hi(b.y)} + acc[ai][bj][m][0] * gv[0], x1 = (f32x4){h16_lo(b.z), h16_hi(b.z), h16_lo(b.w), h16_hi(b.w)} + acc[ai][bj][m][1] * gv[1];
;                     { u32x4 w; w.x = pk_h16(x0.x, x0.y); w.y = pk_h16(x0.z, x0.w); w.z = pk_h16(x1.x, x1.y); w.w = pk_h16(x1.z, x1.w); *(gu32x4*)(ot + o) = w; }
;                     ssq[ai][m] += (x0.x * x0.x + x0.y * x0.y) + (x0.z * x0.z + x0.w * x0.w) + (x1.x * x1.x + x1.y * x1.y) + (x1.z * x1.z + x1.w * x1.w);
;                     if (An) { const f32x4 y0 = x0 * gm[0], y1 = x1 * gm[1]; u32x4 w; w.x = cvt_pk_bf16(y0.x, y0.y); w.y = cvt_pk_bf16(y0.z, y0.w); w.z = cvt_pk_bf16(y1.x, y1.y); w.w = cvt_pk_bf16(y1.z, y1.w); *(gu32x4*)(at + o) = w; } }
.LBB0_1609:
	s_waitcnt vmcnt(6)
	s_nop 0
	v_cvt_f32_f16_sdwa v95, v88 dst_sel:DWORD dst_unused:UNUSED_PAD src0_sel:WORD_1
	v_cvt_f32_f16_e32 v94, v88
	v_cvt_f32_f16_sdwa v97, v89 dst_sel:DWORD dst_unused:UNUSED_PAD src0_sel:WORD_1
	v_cvt_f32_f16_e32 v96, v89
	v_cvt_f32_f16_sdwa v89, v90 dst_sel:DWORD dst_unused:UNUSED_PAD src0_sel:WORD_1
	v_pk_fma_f32 v[28:29], v[28:29], v[72:73], v[94:95]
	v_cvt_f32_f16_e32 v88, v90
	v_cvt_f32_f16_sdwa v95, v91 dst_sel:DWORD dst_unused:UNUSED_PAD src0_sel:WORD_1
	v_cvt_f32_f16_e32 v94, v91
	v_mov_b32_e32 v187, v161
	v_pk_fma_f32 v[30:31], v[30:31], v[74:75], v[96:97]
	v_pk_fma_f32 v[24:25], v[24:25], v[76:77], v[88:89]
	v_pk_fma_f32 v[26:27], v[26:27], v[78:79], v[94:95]
	v_lshl_add_u64 v[92:93], s[56:57], 0, v[186:187]
	v_cvt_pk_f16_f32 v88, v28, v29
	v_cvt_pk_f16_f32 v89, v30, v31
	v_cvt_pk_f16_f32 v90, v24, v25
	v_cvt_pk_f16_f32 v91, v26, v27
	s_and_b64 vcc, exec, s[40:41]
	global_store_dwordx4 v[92:93], v[88:91], off sc1
	s_cbranch_vccnz .LBB0_1611
	s_nop 0
	v_pk_mul_f32 v[90:91], v[180:181], v[30:31]
	v_pk_mul_f32 v[88:89], v[146:147], v[28:29]
	v_pk_mul_f32 v[92:93], v[182:183], v[26:27]
	v_pk_mul_f32 v[94:95], v[144:145], v[24:25]
	v_cvt_pk_bf16_f32 v88, v88, v89
	v_cvt_pk_bf16_f32 v89, v90, v91
	s_nop 0
	v_cvt_pk_bf16_f32 v90, v94, v95
	v_cvt_pk_bf16_f32 v91, v92, v93
	v_lshl_add_u64 v[92:93], s[54:55], 0, v[186:187]
	global_store_dwordx4 v[92:93], v[88:91], off sc1
.LBB0_1611:
	s_waitcnt vmcnt(6)
	s_nop 0
	v_cvt_f32_f16_sdwa v91, v84 dst_sel:DWORD dst_unused:UNUSED_PAD src0_sel:WORD_1
	v_cvt_f32_f16_e32 v90, v84
	v_cvt_f32_f16_sdwa v93, v85 dst_sel:DWORD dst_unused:UNUSED_PAD src0_sel:WORD_1
	v_cvt_f32_f16_e32 v92, v85
	v_cvt_f32_f16_sdwa v85, v86 dst_sel:DWORD dst_unused:UNUSED_PAD src0_sel:WORD_1
	v_pk_fma_f32 v[20:21], v[20:21], v[72:73], v[90:91]
	v_cvt_f32_f16_e32 v84, v86
	v_cvt_f32_f16_sdwa v91, v87 dst_sel:DWORD dst_unused:UNUSED_PAD src0_sel:WORD_1
	v_cvt_f32_f16_e32 v90, v87
	v_mov_b32_e32 v185, v161
	v_pk_fma_f32 v[22:23], v[22:23], v[74:75], v[92:93]
	v_pk_fma_f32 v[16:17], v[16:17], v[76:77], v[84:85]
	v_pk_fma_f32 v[18:19], v[18:19], v[78:79], v[90:91]
	v_lshl_add_u64 v[88:89], s[56:57], 0, v[184:185]
	v_cvt_pk_f16_f32 v84, v20, v21
	v_cvt_pk_f16_f32 v85, v22, v23
	v_cvt_pk_f16_f32 v86, v16, v17
	v_cvt_pk_f16_f32 v87, v18, v19
	s_and_b64 vcc, exec, s[40:41]
	global_store_dwordx4 v[88:89], v[84:87], off sc1
	s_cbranch_vccnz .LBB0_1613
	s_nop 0
	v_pk_mul_f32 v[86:87], v[180:181], v[22:23]
	v_pk_mul_f32 v[84:85], v[146:147], v[20:21]
	v_pk_mul_f32 v[88:89], v[182:183], v[18:19]
	v_pk_mul_f32 v[90:91], v[144:145], v[16:17]
	v_cvt_pk_bf16_f32 v84, v84, v85
	v_cvt_pk_bf16_f32 v85, v86, v87
	s_nop 0
	v_cvt_pk_bf16_f32 v86, v90, v91
	v_cvt_pk_bf16_f32 v87, v88, v89
	v_lshl_add_u64 v[88:89], s[54:55], 0, v[184:185]
	global_store_dwordx4 v[88:89], v[84:87], off sc1
.LBB0_1613:
	s_nop 1
	v_cvt_f32_f16_sdwa v87, v80 dst_sel:DWORD dst_unused:UNUSED_PAD src0_sel:WORD_1
	v_cvt_f32_f16_e32 v86, v80
	v_cvt_f32_f16_sdwa v89, v81 dst_sel:DWORD dst_unused:UNUSED_PAD src0_sel:WORD_1
	v_cvt_f32_f16_e32 v88, v81
	v_mov_b32_e32 v179, v161
	v_pk_fma_f32 v[12:13], v[12:13], v[72:73], v[86:87]
	v_cvt_f32_f16_sdwa v73, v82 dst_sel:DWORD dst_unused:UNUSED_PAD src0_sel:WORD_1
	v_pk_fma_f32 v[14:15], v[14:15], v[74:75], v[88:89]
	v_cvt_f32_f16_e32 v72, v82
	v_cvt_f32_f16_sdwa v75, v83 dst_sel:DWORD dst_unused:UNUSED_PAD src0_sel:WORD_1
	v_cvt_f32_f16_e32 v74, v83
	v_lshl_add_u64 v[84:85], s[56:57], 0, v[178:179]
	v_pk_fma_f32 v[8:9], v[8:9], v[76:77], v[72:73]
	v_cvt_pk_f16_f32 v72, v12, v13
	v_pk_fma_f32 v[10:11], v[10:11], v[78:79], v[74:75]
	v_cvt_pk_f16_f32 v73, v14, v15
	v_cvt_pk_f16_f32 v74, v8, v9
	v_cvt_pk_f16_f32 v75, v10, v11
	s_and_b64 vcc, exec, s[40:41]
	global_store_dwordx4 v[84:85], v[72:75], off sc1
	s_cbranch_vccnz .LBB0_1615
	s_nop 0
	v_pk_mul_f32 v[74:75], v[180:181], v[14:15]
	v_pk_mul_f32 v[72:73], v[146:147], v[12:13]
	v_pk_mul_f32 v[76:77], v[182:183], v[10:11]
	v_pk_mul_f32 v[78:79], v[144:145], v[8:9]
	v_cvt_pk_bf16_f32 v72, v72, v73
	v_cvt_pk_bf16_f32 v73, v74, v75
	s_nop 0
	v_cvt_pk_bf16_f32 v74, v78, v79
	v_cvt_pk_bf16_f32 v75, v76, v77
	v_lshl_add_u64 v[76:77], s[54:55], 0, v[178:179]
	global_store_dwordx4 v[76:77], v[72:75], off sc1

; __device__ __forceinline__ float h16_lo(unsigned u) { return (float)__builtin_bit_cast(h16x2, u).x; }
; __device__ __forceinline__ float h16_hi(unsigned u) { return (float)__builtin_bit_cast(h16x2, u).y; }
; __device__ __forceinline__ unsigned cvt_pk_bf16(float lo, float hi) { unsigned r; asm volatile("v_cvt_pk_bf16_f32 %0, %1, %2" : "=v"(r) : "v"(lo), "v"(hi)); return r; }
;     __device__ __forceinline__ void strip(const f32x4 (&accS)[2], const Unit& u, int wr, int wc, int fr, int fq) const {
;     ...
;         for (int bj = 0; bj < 2; ++bj) { const unsigned c = co + (unsigned)(bj * HALF) * 4u, o = lo + (unsigned)(bj * HALF) * 2u;
;             f32x4 gv = *(const gf32x4*)(gate + c); if (ls) gv = gv * *(const gf32x4*)(lsp + c);
;             const u32x2 b = *(const gu32x2*)(bt + o);
;             const f32x4 x0 = (f32x4){h16_lo(b.x), h16_hi(b.x), h16_lo(b.y), h16_hi(b.y)} + accS[bj] * gv; { u32x2 w; w.x = pk_h16(x0.x, x0.y); w.y = pk_h16(x0.z, x0.w); *(gu32x2*)(ot + o) = w; }
;             q += (x0.x * x0.x + x0.y * x0.y) + (x0.z * x0.z + x0.w * x0.w);
;             if (An) { const f32x4 y0 = x0 * (*(const gf32x4*)(gnp + c) * (*(const gf32x4*)(scp + c) + 1.0f));
;                 u32x2 w; w.x = cvt_pk_bf16(y0.x, y0.y); w.y = cvt_pk_bf16(y0.z, y0.w); *(gu32x2*)(at + o) = w; } }
.LBB0_1639:
	s_or_b64 exec, exec, s[54:55]
	s_add_u32 s56, s94, s14
	s_addc_u32 s57, s95, s15
	s_add_u32 s8, s96, s14
	s_addc_u32 s9, s97, s15
	s_ashr_i32 s3, s2, 31
	s_waitcnt lgkmcnt(1)
	v_add_f32_e32 v10, v12, v13
	s_lshl_b64 s[14:15], s[2:3], 12
	global_atomic_add_f32 v[8:9], v10, off offset:512
	s_add_u32 s20, s72, s14
	v_mov_b32_e32 v11, v231
	v_mov_b32_e32 v10, v232
	s_addc_u32 s21, s73, s15
	s_add_u32 s54, s20, s52
	v_lshl_add_u32 v160, v11, 5, s91
	v_lshrrev_b32_e32 v8, 1, v160
	s_addc_u32 s55, s21, s53
	v_lshl_add_u32 v8, v10, 12, v8
	global_load_dwordx2 v[16:17], v8, s[54:55]
	s_waitcnt lgkmcnt(0)
	global_load_dwordx4 v[12:15], v160, s[56:57]
	s_add_u32 s14, s76, s14
	s_addc_u32 s15, s75, s15
	s_add_u32 s14, s14, s52
	s_addc_u32 s15, s15, s53
	s_and_b64 vcc, exec, s[40:41]
	s_waitcnt vmcnt(1)
	v_cvt_f32_f16_e32 v18, v16
	v_cvt_f32_f16_e32 v20, v17
	v_cvt_f32_f16_sdwa v21, v17 dst_sel:DWORD dst_unused:UNUSED_PAD src0_sel:WORD_1
	v_cvt_f32_f16_sdwa v19, v16 dst_sel:DWORD dst_unused:UNUSED_PAD src0_sel:WORD_1
	s_waitcnt vmcnt(0)
	v_pk_fma_f32 v[6:7], v[6:7], v[14:15], v[20:21]
	v_pk_fma_f32 v[4:5], v[4:5], v[12:13], v[18:19]
	v_cvt_pk_f16_f32 v13, v6, v7
	v_cvt_pk_f16_f32 v12, v4, v5
	global_store_dwordx2 v8, v[12:13], s[54:55] sc1
	s_cbranch_vccnz .LBB0_1641
	v_lshl_add_u64 v[12:13], s[8:9], 0, v[160:161]
	global_load_dwordx4 v[12:15], v[12:13], off
	v_lshl_add_u64 v[16:17], s[12:13], 0, v[160:161]
	global_load_dwordx4 v[16:19], v[16:17], off
	v_mov_b32_e32 v9, v161
	s_waitcnt vmcnt(1)
	v_pk_add_f32 v[14:15], v[14:15], 1.0 op_sel_hi:[1,0]
	v_pk_add_f32 v[12:13], v[12:13], 1.0 op_sel_hi:[1,0]
	s_waitcnt vmcnt(0)
	v_pk_mul_f32 v[14:15], v[18:19], v[14:15]
	v_pk_mul_f32 v[12:13], v[16:17], v[12:13]
	v_pk_mul_f32 v[14:15], v[6:7], v[14:15]
	v_pk_mul_f32 v[12:13], v[4:5], v[12:13]
	s_nop 0
	v_cvt_pk_bf16_f32 v12, v12, v13
	v_cvt_pk_bf16_f32 v13, v14, v15
	v_lshl_add_u64 v[14:15], s[14:15], 0, v[8:9]
	global_store_dwordx2 v[14:15], v[12:13], off sc1
.LBB0_1641:
	v_add_u32_e32 v8, 0x100, v8
	global_load_dwordx2 v[16:17], v8, s[54:55]
	v_add_u32_e32 v160, 0x200, v160
	global_load_dwordx4 v[12:15], v160, s[56:57]
	s_and_b64 vcc, exec, s[40:41]
	s_waitcnt vmcnt(1)
	v_cvt_f32_f16_e32 v18, v16
	v_cvt_f32_f16_e32 v20, v17
	v_cvt_f32_f16_sdwa v21, v17 dst_sel:DWORD dst_unused:UNUSED_PAD src0_sel:WORD_1
	v_cvt_f32_f16_sdwa v19, v16 dst_sel:DWORD dst_unused:UNUSED_PAD src0_sel:WORD_1
	s_waitcnt vmcnt(0)
	v_pk_fma_f32 v[2:3], v[2:3], v[14:15], v[20:21]
	v_pk_fma_f32 v[0:1], v[0:1], v[12:13], v[18:19]
	v_cvt_pk_f16_f32 v13, v2, v3
	v_cvt_pk_f16_f32 v12, v0, v1
	global_store_dwordx2 v8, v[12:13], s[54:55] sc1
	s_cbranch_vccnz .LBB0_1643
	v_lshl_add_u64 v[12:13], s[8:9], 0, v[160:161]
	global_load_dwordx4 v[12:15], v[12:13], off
	v_lshl_add_u64 v[16:17], s[12:13], 0, v[160:161]
	global_load_dwordx4 v[16:19], v[16:17], off
	v_mov_b32_e32 v9, v161
	v_lshl_add_u64 v[8:9], s[14:15], 0, v[8:9]
	s_waitcnt vmcnt(1)
	v_pk_add_f32 v[12:13], v[12:13], 1.0 op_sel_hi:[1,0]
	v_pk_add_f32 v[14:15], v[14:15], 1.0 op_sel_hi:[1,0]
	s_waitcnt vmcnt(0)
	v_pk_mul_f32 v[12:13], v[16:17], v[12:13]
	v_pk_mul_f32 v[14:15], v[18:19], v[14:15]
	v_pk_mul_f32 v[12:13], v[0:1], v[12:13]
	v_pk_mul_f32 v[14:15], v[2:3], v[14:15]
	v_cvt_pk_bf16_f32 v12, v12, v13
	s_nop 0
	v_cvt_pk_bf16_f32 v13, v14, v15
	global_store_dwordx2 v[8:9], v[12:13], off sc1
